# GEMM K-loops: MFMA sections start right after the barrier (s_setprio pairs and the redundant lgkmcnt(0) removed)
# speedup vs baseline: 1.0101x; 1.0035x over previous
; #define PG8_STAGE(bufoff, gbase, voff) do { _Pragma("unroll") for (int _i = 0; _i < 2; ++_i) \
;         __builtin_amdgcn_global_load_lds((const unsigned*)((const char*)(gbase) + (voff)[_i]), (PG8_LAS unsigned*)(lds + (bufoff) + ldsw + _i * 8192), 16, 0, 0); } while (0)
; #define PG8_LDA(dst, b, h) do { _Pragma("unroll") for (int m = 0; m < 4; ++m) _Pragma("unroll") for (int k = 0; k < 2; ++k) dst[m][k] = *(const PG8_LAS bf16x8*)(lds + PG8_SA(b, h) + aoff + m * 2048 + k * 1024); } while (0)
; #define PG8_LDB(dst, b, h) do { _Pragma("unroll") for (int n = 0; n < 2; ++n) _Pragma("unroll") for (int k = 0; k < 2; ++k) dst[n][k] = *(const PG8_LAS bf16x8*)(lds + PG8_SB(b, h) + boff + n * 2048 + k * 1024); } while (0)
; #define PG8_MMA(ai, bj, At, Bt) do { __builtin_amdgcn_s_setprio(1); _Pragma("unroll") for (int m = 0; m < 4; ++m) _Pragma("unroll") for (int n = 0; n < 2; ++n) _Pragma("unroll") for (int k = 0; k < 2; ++k) \
;         acc[ai][bj][m][n] = __builtin_amdgcn_mfma_f32_16x16x32_bf16(Bt[n][k], At[m][k], acc[ai][bj][m][n], 0, 0, 0); __builtin_amdgcn_s_setprio(0); } while (0)
; #define PG8_WAIT_V(n) asm volatile("s_waitcnt vmcnt(" #n ")" ::: "memory")
; #define PG8_WAIT_L(n) asm volatile("s_waitcnt lgkmcnt(" #n ")" ::: "memory")
; #define PG8_BAR __builtin_amdgcn_s_barrier()
; #define PG8_SCHED __builtin_amdgcn_sched_barrier(0)
; template <class Epi, class Sched, bool ALIGN_EPI = false, bool SP2 = false>
; __device__ __forceinline__ void gemm_phase(PG8_LAS unsigned char* lds, const Gemm g, const Sched& S, const Epi& E) {
;     ...
;             PG8_LDB(B0, 0, 0); PG8_LDB(B1, 0, 1); PG8_SCHED; PG8_LDA(At, 0, 0); PG8_STAGE(PG8_SA(1, 1), a1 + hstepA, voffA);
;             PG8_WAIT_V(8); PG8_WAIT_L(0); PG8_BAR; PG8_MMA(0, 0, At, B0); PG8_MMA(0, 1, At, B1); PG8_BAR; PG8_SCHED;
;             PG8_LDA(At, 0, 1); PG8_STAGE(PG8_SB(0, 0), b2, voffB); PG8_STAGE(PG8_SB(0, 1), b2 + hstep, voffB); PG8_STAGE(PG8_SA(0, 0), a2, voffA);
;             PG8_WAIT_V(8); PG8_WAIT_L(0); PG8_BAR; PG8_MMA(1, 0, At, B0); PG8_MMA(1, 1, At, B1); PG8_BAR; PG8_SCHED;
.LBB0_115:
	ds_read_b128 v[150:153], v158
	ds_read_b128 v[162:165], v158 offset:1024
	ds_read_b128 v[166:169], v158 offset:2048
	ds_read_b128 v[170:173], v158 offset:3072
	ds_read_b128 v[174:177], v159
	ds_read_b128 v[178:181], v159 offset:1024
	ds_read_b128 v[182:185], v159 offset:2048
	ds_read_b128 v[186:189], v159 offset:3072
	s_add_u32 s68, s34, 0xfff00080
	s_addc_u32 s69, s35, -1
	s_cmp_eq_u32 s67, 60
	s_cselect_b32 s87, s21, s69
	s_cselect_b32 s86, s27, s68
	s_cselect_b32 s85, s19, s66
	s_cselect_b32 s84, s31, s65
	s_add_i32 m0, s53, 0xc000
	ds_read_b128 v[190:193], v160
	ds_read_b128 v[194:197], v160 offset:1024
	ds_read_b128 v[198:201], v160 offset:2048
	ds_read_b128 v[202:205], v160 offset:3072
	ds_read_b128 v[206:209], v160 offset:4096
	ds_read_b128 v[210:213], v160 offset:5120
	ds_read_b128 v[214:217], v160 offset:6144
	ds_read_b128 v[218:221], v160 offset:7168
	global_load_lds_dwordx4 v140, s[34:35]
	s_add_i32 m0, s53, 0xe000
	s_nop 0
	global_load_lds_dwordx4 v142, s[34:35]
	s_waitcnt vmcnt(8)
	s_waitcnt lgkmcnt(0)
	s_barrier
	v_mfma_f32_16x16x32_bf16 v[124:127], v[150:153], v[190:193], v[124:127]
	v_mfma_f32_16x16x32_bf16 v[120:123], v[166:169], v[190:193], v[120:123]
	v_mfma_f32_16x16x32_bf16 v[108:111], v[150:153], v[198:201], v[108:111]
	v_mfma_f32_16x16x32_bf16 v[104:107], v[166:169], v[198:201], v[104:107]
	v_mfma_f32_16x16x32_bf16 v[92:95], v[150:153], v[206:209], v[92:95]
	v_mfma_f32_16x16x32_bf16 v[88:91], v[166:169], v[206:209], v[88:91]
	v_mfma_f32_16x16x32_bf16 v[76:79], v[150:153], v[214:217], v[76:79]
	v_mfma_f32_16x16x32_bf16 v[72:75], v[166:169], v[214:217], v[72:75]
	v_mfma_f32_16x16x32_bf16 v[124:127], v[162:165], v[194:197], v[124:127]
	v_mfma_f32_16x16x32_bf16 v[120:123], v[170:173], v[194:197], v[120:123]
	v_mfma_f32_16x16x32_bf16 v[108:111], v[162:165], v[202:205], v[108:111]
	v_mfma_f32_16x16x32_bf16 v[104:107], v[170:173], v[202:205], v[104:107]
	v_mfma_f32_16x16x32_bf16 v[92:95], v[162:165], v[210:213], v[92:95]
	v_mfma_f32_16x16x32_bf16 v[88:91], v[170:173], v[210:213], v[88:91]
	v_mfma_f32_16x16x32_bf16 v[76:79], v[162:165], v[218:221], v[76:79]
	v_mfma_f32_16x16x32_bf16 v[72:75], v[170:173], v[218:221], v[72:75]
	v_mfma_f32_16x16x32_bf16 v[116:119], v[174:177], v[190:193], v[116:119]
	v_mfma_f32_16x16x32_bf16 v[112:115], v[182:185], v[190:193], v[112:115]
	v_mfma_f32_16x16x32_bf16 v[100:103], v[174:177], v[198:201], v[100:103]
	v_mfma_f32_16x16x32_bf16 v[96:99], v[182:185], v[198:201], v[96:99]
	v_mfma_f32_16x16x32_bf16 v[84:87], v[174:177], v[206:209], v[84:87]
	v_mfma_f32_16x16x32_bf16 v[80:83], v[182:185], v[206:209], v[80:83]
	v_mfma_f32_16x16x32_bf16 v[68:71], v[174:177], v[214:217], v[68:71]
	v_mfma_f32_16x16x32_bf16 v[64:67], v[182:185], v[214:217], v[64:67]
	v_mfma_f32_16x16x32_bf16 v[116:119], v[178:181], v[194:197], v[116:119]
	v_mfma_f32_16x16x32_bf16 v[112:115], v[186:189], v[194:197], v[112:115]
	v_mfma_f32_16x16x32_bf16 v[100:103], v[178:181], v[202:205], v[100:103]
	v_mfma_f32_16x16x32_bf16 v[96:99], v[186:189], v[202:205], v[96:99]
	v_mfma_f32_16x16x32_bf16 v[84:87], v[178:181], v[210:213], v[84:87]
	v_mfma_f32_16x16x32_bf16 v[80:83], v[186:189], v[210:213], v[80:83]
	v_mfma_f32_16x16x32_bf16 v[68:71], v[178:181], v[218:221], v[68:71]
	v_mfma_f32_16x16x32_bf16 v[64:67], v[186:189], v[218:221], v[64:67]
	s_barrier
	s_add_u32 s98, s84, s12
	s_addc_u32 s99, s85, s13
	s_add_u32 s100, s86, s12
	s_addc_u32 s101, s87, s13
	s_add_i32 s68, s62, s33
	s_mov_b32 m0, s68
	ds_read_b128 v[190:193], v160 offset:16384
	ds_read_b128 v[194:197], v160 offset:17408
	ds_read_b128 v[198:201], v160 offset:18432
	ds_read_b128 v[202:205], v160 offset:19456
	ds_read_b128 v[206:209], v160 offset:20480
	ds_read_b128 v[210:213], v160 offset:21504
	ds_read_b128 v[214:217], v160 offset:22528
	ds_read_b128 v[218:221], v160 offset:23552
	global_load_lds_dwordx4 v132, s[84:85]
	s_add_i32 m0, s68, 0x2000
	s_add_u32 s68, s84, 0x100000
	s_addc_u32 s69, s85, 0
	s_add_i32 s70, s63, s33
	global_load_lds_dwordx4 v128, s[84:85]
	s_mov_b32 m0, s70
	s_nop 0
	global_load_lds_dwordx4 v132, s[68:69]
	s_add_i32 m0, s70, 0x2000
	s_nop 0
	global_load_lds_dwordx4 v128, s[68:69]
	s_mov_b32 m0, s53
	s_nop 0
	global_load_lds_dwordx4 v134, s[86:87]
	s_mov_b32 m0, s54
	s_nop 0
	global_load_lds_dwordx4 v130, s[86:87]
	s_waitcnt vmcnt(8)
	s_waitcnt lgkmcnt(0)
	s_barrier
	v_mfma_f32_16x16x32_bf16 v[60:63], v[150:153], v[190:193], v[60:63]
	v_mfma_f32_16x16x32_bf16 v[56:59], v[166:169], v[190:193], v[56:59]
	v_mfma_f32_16x16x32_bf16 v[44:47], v[150:153], v[198:201], v[44:47]
	v_mfma_f32_16x16x32_bf16 v[40:43], v[166:169], v[198:201], v[40:43]
	v_mfma_f32_16x16x32_bf16 v[28:31], v[150:153], v[206:209], v[28:31]
	v_mfma_f32_16x16x32_bf16 v[24:27], v[166:169], v[206:209], v[24:27]
	v_mfma_f32_16x16x32_bf16 v[12:15], v[150:153], v[214:217], v[12:15]
	v_mfma_f32_16x16x32_bf16 v[8:11], v[166:169], v[214:217], v[8:11]
	v_mfma_f32_16x16x32_bf16 v[60:63], v[162:165], v[194:197], v[60:63]
	v_mfma_f32_16x16x32_bf16 v[56:59], v[170:173], v[194:197], v[56:59]
	v_mfma_f32_16x16x32_bf16 v[44:47], v[162:165], v[202:205], v[44:47]
	v_mfma_f32_16x16x32_bf16 v[40:43], v[170:173], v[202:205], v[40:43]
	v_mfma_f32_16x16x32_bf16 v[28:31], v[162:165], v[210:213], v[28:31]
	v_mfma_f32_16x16x32_bf16 v[24:27], v[170:173], v[210:213], v[24:27]
	v_mfma_f32_16x16x32_bf16 v[12:15], v[162:165], v[218:221], v[12:15]
	v_mfma_f32_16x16x32_bf16 v[8:11], v[170:173], v[218:221], v[8:11]
	v_mfma_f32_16x16x32_bf16 v[52:55], v[174:177], v[190:193], v[52:55]
	v_mfma_f32_16x16x32_bf16 v[48:51], v[182:185], v[190:193], v[48:51]
	v_mfma_f32_16x16x32_bf16 v[36:39], v[174:177], v[198:201], v[36:39]
	v_mfma_f32_16x16x32_bf16 v[32:35], v[182:185], v[198:201], v[32:35]
	v_mfma_f32_16x16x32_bf16 v[20:23], v[174:177], v[206:209], v[20:23]
	v_mfma_f32_16x16x32_bf16 v[16:19], v[182:185], v[206:209], v[16:19]
	v_mfma_f32_16x16x32_bf16 v[4:7], v[174:177], v[214:217], v[4:7]
	v_mfma_f32_16x16x32_bf16 v[0:3], v[182:185], v[214:217], v[0:3]
	v_mfma_f32_16x16x32_bf16 v[52:55], v[178:181], v[194:197], v[52:55]
	v_mfma_f32_16x16x32_bf16 v[48:51], v[186:189], v[194:197], v[48:51]
	v_mfma_f32_16x16x32_bf16 v[36:39], v[178:181], v[202:205], v[36:39]
	v_mfma_f32_16x16x32_bf16 v[32:35], v[186:189], v[202:205], v[32:35]
	v_mfma_f32_16x16x32_bf16 v[20:23], v[178:181], v[210:213], v[20:23]
	v_mfma_f32_16x16x32_bf16 v[16:19], v[186:189], v[210:213], v[16:19]
	v_mfma_f32_16x16x32_bf16 v[4:7], v[178:181], v[218:221], v[4:7]
	v_mfma_f32_16x16x32_bf16 v[0:3], v[186:189], v[218:221], v[0:3]
	s_barrier
; #define PG8_STAGE(bufoff, gbase, voff) do { _Pragma("unroll") for (int _i = 0; _i < 2; ++_i) \
;         __builtin_amdgcn_global_load_lds((const unsigned*)((const char*)(gbase) + (voff)[_i]), (PG8_LAS unsigned*)(lds + (bufoff) + ldsw + _i * 8192), 16, 0, 0); } while (0)
; #define PG8_LDA(dst, b, h) do { _Pragma("unroll") for (int m = 0; m < 4; ++m) _Pragma("unroll") for (int k = 0; k < 2; ++k) dst[m][k] = *(const PG8_LAS bf16x8*)(lds + PG8_SA(b, h) + aoff + m * 2048 + k * 1024); } while (0)
; #define PG8_LDB(dst, b, h) do { _Pragma("unroll") for (int n = 0; n < 2; ++n) _Pragma("unroll") for (int k = 0; k < 2; ++k) dst[n][k] = *(const PG8_LAS bf16x8*)(lds + PG8_SB(b, h) + boff + n * 2048 + k * 1024); } while (0)
; #define PG8_MMA(ai, bj, At, Bt) do { __builtin_amdgcn_s_setprio(1); _Pragma("unroll") for (int m = 0; m < 4; ++m) _Pragma("unroll") for (int n = 0; n < 2; ++n) _Pragma("unroll") for (int k = 0; k < 2; ++k) \
;         acc[ai][bj][m][n] = __builtin_amdgcn_mfma_f32_16x16x32_bf16(Bt[n][k], At[m][k], acc[ai][bj][m][n], 0, 0, 0); __builtin_amdgcn_s_setprio(0); } while (0)
; #define PG8_WAIT_V(n) asm volatile("s_waitcnt vmcnt(" #n ")" ::: "memory")
; #define PG8_WAIT_L(n) asm volatile("s_waitcnt lgkmcnt(" #n ")" ::: "memory")
; #define PG8_BAR __builtin_amdgcn_s_barrier()
; #define PG8_SCHED __builtin_amdgcn_sched_barrier(0)
; template <class Epi, class Sched, bool ALIGN_EPI = false, bool SP2 = false>
; __device__ __forceinline__ void gemm_phase(PG8_LAS unsigned char* lds, const Gemm g, const Sched& S, const Epi& E) {
;     ...
;         for (int t = 0; t < nt; t += 2) {
;     ...
;             PG8_LDB(B0, 1, 0); PG8_LDB(B1, 1, 1); PG8_SCHED; PG8_LDA(At, 1, 0); PG8_STAGE(PG8_SA(0, 1), a2 + hstepA, voffA);
;             PG8_WAIT_V(8); PG8_WAIT_L(0); PG8_BAR; PG8_MMA(0, 0, At, B0); PG8_MMA(0, 1, At, B1); PG8_BAR; PG8_SCHED;
;             PG8_LDA(At, 1, 1); PG8_STAGE(PG8_SB(1, 0), b3, voffB); PG8_STAGE(PG8_SB(1, 1), b3 + hstep, voffB); PG8_STAGE(PG8_SA(1, 0), a3, voffA);
;             PG8_WAIT_V(8); PG8_WAIT_L(0); PG8_BAR; PG8_MMA(1, 0, At, B0); PG8_MMA(1, 1, At, B1); PG8_BAR; PG8_SCHED;
	s_add_i32 s70, 0, 0x18000
	v_add_u32_e32 v136, s70, v157
	s_add_i32 s71, 0, 0x1c000
	ds_read_b128 v[150:153], v136
	ds_read_b128 v[162:165], v136 offset:1024
	ds_read_b128 v[166:169], v136 offset:2048
	ds_read_b128 v[170:173], v136 offset:3072
	v_add_u32_e32 v136, s71, v157
	ds_read_b128 v[174:177], v136
	ds_read_b128 v[178:181], v136 offset:1024
	ds_read_b128 v[182:185], v136 offset:2048
	ds_read_b128 v[186:189], v136 offset:3072
	s_add_u32 s68, s86, 0x100000
	s_addc_u32 s69, s87, 0
	s_mov_b32 m0, s55
	ds_read_b128 v[190:193], v160 offset:32768
	ds_read_b128 v[194:197], v160 offset:33792
	ds_read_b128 v[198:201], v160 offset:34816
	ds_read_b128 v[202:205], v160 offset:35840
	ds_read_b128 v[206:209], v160 offset:36864
	ds_read_b128 v[210:213], v160 offset:37888
	ds_read_b128 v[214:217], v160 offset:38912
	ds_read_b128 v[218:221], v160 offset:39936
	global_load_lds_dwordx4 v134, s[68:69]
	s_mov_b32 m0, s56
	s_nop 0
	global_load_lds_dwordx4 v130, s[68:69]
	s_waitcnt vmcnt(8)
	s_waitcnt lgkmcnt(0)
	s_barrier
	v_mfma_f32_16x16x32_bf16 v[124:127], v[150:153], v[190:193], v[124:127]
	v_mfma_f32_16x16x32_bf16 v[120:123], v[166:169], v[190:193], v[120:123]
	v_mfma_f32_16x16x32_bf16 v[108:111], v[150:153], v[198:201], v[108:111]
	v_mfma_f32_16x16x32_bf16 v[104:107], v[166:169], v[198:201], v[104:107]
	v_mfma_f32_16x16x32_bf16 v[92:95], v[150:153], v[206:209], v[92:95]
	v_mfma_f32_16x16x32_bf16 v[88:91], v[166:169], v[206:209], v[88:91]
	v_mfma_f32_16x16x32_bf16 v[76:79], v[150:153], v[214:217], v[76:79]
	v_mfma_f32_16x16x32_bf16 v[72:75], v[166:169], v[214:217], v[72:75]
	v_mfma_f32_16x16x32_bf16 v[124:127], v[162:165], v[194:197], v[124:127]
	v_mfma_f32_16x16x32_bf16 v[120:123], v[170:173], v[194:197], v[120:123]
	v_mfma_f32_16x16x32_bf16 v[108:111], v[162:165], v[202:205], v[108:111]
	v_mfma_f32_16x16x32_bf16 v[104:107], v[170:173], v[202:205], v[104:107]
	v_mfma_f32_16x16x32_bf16 v[92:95], v[162:165], v[210:213], v[92:95]
	v_mfma_f32_16x16x32_bf16 v[88:91], v[170:173], v[210:213], v[88:91]
	v_mfma_f32_16x16x32_bf16 v[76:79], v[162:165], v[218:221], v[76:79]
	v_mfma_f32_16x16x32_bf16 v[72:75], v[170:173], v[218:221], v[72:75]
	v_mfma_f32_16x16x32_bf16 v[116:119], v[174:177], v[190:193], v[116:119]
	v_mfma_f32_16x16x32_bf16 v[112:115], v[182:185], v[190:193], v[112:115]
	v_mfma_f32_16x16x32_bf16 v[100:103], v[174:177], v[198:201], v[100:103]
	v_mfma_f32_16x16x32_bf16 v[96:99], v[182:185], v[198:201], v[96:99]
	v_mfma_f32_16x16x32_bf16 v[84:87], v[174:177], v[206:209], v[84:87]
	v_mfma_f32_16x16x32_bf16 v[80:83], v[182:185], v[206:209], v[80:83]
	v_mfma_f32_16x16x32_bf16 v[68:71], v[174:177], v[214:217], v[68:71]
	v_mfma_f32_16x16x32_bf16 v[64:67], v[182:185], v[214:217], v[64:67]
	v_mfma_f32_16x16x32_bf16 v[116:119], v[178:181], v[194:197], v[116:119]
	v_mfma_f32_16x16x32_bf16 v[112:115], v[186:189], v[194:197], v[112:115]
	v_mfma_f32_16x16x32_bf16 v[100:103], v[178:181], v[202:205], v[100:103]
	v_mfma_f32_16x16x32_bf16 v[96:99], v[186:189], v[202:205], v[96:99]
	v_mfma_f32_16x16x32_bf16 v[84:87], v[178:181], v[210:213], v[84:87]
	v_mfma_f32_16x16x32_bf16 v[80:83], v[186:189], v[210:213], v[80:83]
	v_mfma_f32_16x16x32_bf16 v[68:71], v[178:181], v[218:221], v[68:71]
	v_mfma_f32_16x16x32_bf16 v[64:67], v[186:189], v[218:221], v[64:67]
	s_barrier
	s_add_i32 s68, s70, s33
	s_mov_b32 m0, s68
	ds_read_b128 v[190:193], v160 offset:49152
	ds_read_b128 v[194:197], v160 offset:50176
	ds_read_b128 v[198:201], v160 offset:51200
	ds_read_b128 v[202:205], v160 offset:52224
	ds_read_b128 v[206:209], v160 offset:53248
	ds_read_b128 v[210:213], v160 offset:54272
	ds_read_b128 v[214:217], v160 offset:55296
	ds_read_b128 v[218:221], v160 offset:56320
	global_load_lds_dwordx4 v132, s[98:99]
	s_add_i32 m0, s68, 0x2000
	s_add_u32 s68, s84, 0x100080
	s_addc_u32 s69, s85, 0
	s_add_i32 s70, s71, s33
	global_load_lds_dwordx4 v128, s[98:99]
	s_mov_b32 m0, s70
	s_nop 0
	global_load_lds_dwordx4 v132, s[68:69]
	s_add_i32 m0, s70, 0x2000
	s_nop 0
	global_load_lds_dwordx4 v128, s[68:69]
	s_mov_b32 m0, s60
	s_nop 0
	global_load_lds_dwordx4 v134, s[100:101]
	s_mov_b32 m0, s61
	s_nop 0
	global_load_lds_dwordx4 v130, s[100:101]
	s_waitcnt vmcnt(8)
	s_waitcnt lgkmcnt(0)
	s_barrier
	v_mfma_f32_16x16x32_bf16 v[60:63], v[150:153], v[190:193], v[60:63]
	v_mfma_f32_16x16x32_bf16 v[56:59], v[166:169], v[190:193], v[56:59]
	v_mfma_f32_16x16x32_bf16 v[44:47], v[150:153], v[198:201], v[44:47]
	v_mfma_f32_16x16x32_bf16 v[40:43], v[166:169], v[198:201], v[40:43]
	v_mfma_f32_16x16x32_bf16 v[28:31], v[150:153], v[206:209], v[28:31]
	v_mfma_f32_16x16x32_bf16 v[24:27], v[166:169], v[206:209], v[24:27]
	v_mfma_f32_16x16x32_bf16 v[12:15], v[150:153], v[214:217], v[12:15]
	v_mfma_f32_16x16x32_bf16 v[8:11], v[166:169], v[214:217], v[8:11]
	v_mfma_f32_16x16x32_bf16 v[60:63], v[162:165], v[194:197], v[60:63]
	v_mfma_f32_16x16x32_bf16 v[56:59], v[170:173], v[194:197], v[56:59]
	v_mfma_f32_16x16x32_bf16 v[44:47], v[162:165], v[202:205], v[44:47]
	v_mfma_f32_16x16x32_bf16 v[40:43], v[170:173], v[202:205], v[40:43]
	v_mfma_f32_16x16x32_bf16 v[28:31], v[162:165], v[210:213], v[28:31]
	v_mfma_f32_16x16x32_bf16 v[24:27], v[170:173], v[210:213], v[24:27]
	v_mfma_f32_16x16x32_bf16 v[12:15], v[162:165], v[218:221], v[12:15]
	v_mfma_f32_16x16x32_bf16 v[8:11], v[170:173], v[218:221], v[8:11]
	v_mfma_f32_16x16x32_bf16 v[52:55], v[174:177], v[190:193], v[52:55]
	v_mfma_f32_16x16x32_bf16 v[48:51], v[182:185], v[190:193], v[48:51]
	v_mfma_f32_16x16x32_bf16 v[36:39], v[174:177], v[198:201], v[36:39]
	v_mfma_f32_16x16x32_bf16 v[32:35], v[182:185], v[198:201], v[32:35]
	v_mfma_f32_16x16x32_bf16 v[20:23], v[174:177], v[206:209], v[20:23]
	v_mfma_f32_16x16x32_bf16 v[16:19], v[182:185], v[206:209], v[16:19]
	v_mfma_f32_16x16x32_bf16 v[4:7], v[174:177], v[214:217], v[4:7]
	v_mfma_f32_16x16x32_bf16 v[0:3], v[182:185], v[214:217], v[0:3]
	v_mfma_f32_16x16x32_bf16 v[52:55], v[178:181], v[194:197], v[52:55]
	v_mfma_f32_16x16x32_bf16 v[48:51], v[186:189], v[194:197], v[48:51]
	v_mfma_f32_16x16x32_bf16 v[36:39], v[178:181], v[202:205], v[36:39]
	v_mfma_f32_16x16x32_bf16 v[32:35], v[186:189], v[202:205], v[32:35]
	v_mfma_f32_16x16x32_bf16 v[20:23], v[178:181], v[210:213], v[20:23]
	v_mfma_f32_16x16x32_bf16 v[16:19], v[186:189], v[210:213], v[16:19]
	v_mfma_f32_16x16x32_bf16 v[4:7], v[178:181], v[218:221], v[4:7]
	v_mfma_f32_16x16x32_bf16 v[0:3], v[186:189], v[218:221], v[0:3]
	s_barrier
	s_add_i32 s67, s67, 2
	s_add_u32 s34, s34, 0x100
	s_addc_u32 s35, s35, 0
	s_add_u32 s65, s65, 0x100
	s_addc_u32 s66, s66, 0
	s_cmp_gt_u32 s67, 61
	s_cbranch_scc0 .LBB0_115
	s_and_b64 vcc, exec, s[14:15]
	s_cbranch_vccz .LBB0_118
	s_barrier

; #define PG8_STAGE(bufoff, gbase, voff) do { _Pragma("unroll") for (int _i = 0; _i < 2; ++_i) \
;         __builtin_amdgcn_global_load_lds((const unsigned*)((const char*)(gbase) + (voff)[_i]), (PG8_LAS unsigned*)(lds + (bufoff) + ldsw + _i * 8192), 16, 0, 0); } while (0)
; #define PG8_LDA(dst, b, h) do { _Pragma("unroll") for (int m = 0; m < 4; ++m) _Pragma("unroll") for (int k = 0; k < 2; ++k) dst[m][k] = *(const PG8_LAS bf16x8*)(lds + PG8_SA(b, h) + aoff + m * 2048 + k * 1024); } while (0)
; #define PG8_LDB(dst, b, h) do { _Pragma("unroll") for (int n = 0; n < 2; ++n) _Pragma("unroll") for (int k = 0; k < 2; ++k) dst[n][k] = *(const PG8_LAS bf16x8*)(lds + PG8_SB(b, h) + boff + n * 2048 + k * 1024); } while (0)
; #define PG8_MMA(ai, bj, At, Bt) do { __builtin_amdgcn_s_setprio(1); _Pragma("unroll") for (int m = 0; m < 4; ++m) _Pragma("unroll") for (int n = 0; n < 2; ++n) _Pragma("unroll") for (int k = 0; k < 2; ++k) \
;         acc[ai][bj][m][n] = __builtin_amdgcn_mfma_f32_16x16x32_bf16(Bt[n][k], At[m][k], acc[ai][bj][m][n], 0, 0, 0); __builtin_amdgcn_s_setprio(0); } while (0)
; #define PG8_WAIT_V(n) asm volatile("s_waitcnt vmcnt(" #n ")" ::: "memory")
; #define PG8_WAIT_L(n) asm volatile("s_waitcnt lgkmcnt(" #n ")" ::: "memory")
; #define PG8_BAR __builtin_amdgcn_s_barrier()
; #define PG8_SCHED __builtin_amdgcn_sched_barrier(0)
; template <class Epi, class Sched, bool ALIGN_EPI = false, bool SP2 = false>
; __device__ __forceinline__ void gemm_phase(PG8_LAS unsigned char* lds, const Gemm g, const Sched& S, const Epi& E) {
;     ...
;             PG8_LDB(B0, 0, 0); PG8_LDB(B1, 0, 1); PG8_SCHED; PG8_LDA(At, 0, 0); PG8_STAGE(PG8_SA(1, 1), a1 + hstepA, voffA);
;             PG8_WAIT_V(8); PG8_WAIT_L(0); PG8_BAR; PG8_MMA(0, 0, At, B0); PG8_MMA(0, 1, At, B1); PG8_BAR; PG8_SCHED;
;             PG8_LDA(At, 0, 1); PG8_STAGE(PG8_SB(0, 0), b2, voffB); PG8_STAGE(PG8_SB(0, 1), b2 + hstep, voffB); PG8_STAGE(PG8_SA(0, 0), a2, voffA);
;             PG8_WAIT_V(8); PG8_WAIT_L(0); PG8_BAR; PG8_MMA(1, 0, At, B0); PG8_MMA(1, 1, At, B1); PG8_BAR; PG8_SCHED;
.LBB0_1198:
	ds_read_b128 v[144:147], v153
	ds_read_b128 v[158:161], v153 offset:1024
	ds_read_b128 v[162:165], v153 offset:2048
	ds_read_b128 v[166:169], v153 offset:3072
	ds_read_b128 v[170:173], v154
	ds_read_b128 v[174:177], v154 offset:1024
	ds_read_b128 v[178:181], v154 offset:2048
	ds_read_b128 v[182:185], v154 offset:3072
	s_add_u32 s38, s34, 0xfff00080
	s_addc_u32 s39, s35, -1
	s_cmp_eq_u32 s65, 60
	s_cselect_b32 s41, s21, s39
	s_cselect_b32 s40, s27, s38
	s_cselect_b32 s39, s19, s64
	s_cselect_b32 s38, s62, s63
	s_add_i32 m0, s31, 0xc000
	ds_read_b128 v[186:189], v155
	ds_read_b128 v[190:193], v155 offset:1024
	ds_read_b128 v[194:197], v155 offset:2048
	ds_read_b128 v[198:201], v155 offset:3072
	ds_read_b128 v[202:205], v155 offset:4096
	ds_read_b128 v[206:209], v155 offset:5120
	ds_read_b128 v[210:213], v155 offset:6144
	ds_read_b128 v[214:217], v155 offset:7168
	global_load_lds_dwordx4 v136, s[34:35]
	s_add_i32 m0, s31, 0xe000
	s_nop 0
	global_load_lds_dwordx4 v138, s[34:35]
	s_waitcnt vmcnt(8)
	s_waitcnt lgkmcnt(0)
	s_barrier
	v_mfma_f32_16x16x32_bf16 v[124:127], v[144:147], v[186:189], v[124:127]
	v_mfma_f32_16x16x32_bf16 v[120:123], v[162:165], v[186:189], v[120:123]
	v_mfma_f32_16x16x32_bf16 v[108:111], v[144:147], v[194:197], v[108:111]
	v_mfma_f32_16x16x32_bf16 v[48:51], v[162:165], v[194:197], v[48:51]
	v_mfma_f32_16x16x32_bf16 v[100:103], v[144:147], v[202:205], v[100:103]
	v_mfma_f32_16x16x32_bf16 v[64:67], v[162:165], v[202:205], v[64:67]
	v_mfma_f32_16x16x32_bf16 v[92:95], v[144:147], v[210:213], v[92:95]
	v_mfma_f32_16x16x32_bf16 v[80:83], v[162:165], v[210:213], v[80:83]
	v_mfma_f32_16x16x32_bf16 v[124:127], v[158:161], v[190:193], v[124:127]
	v_mfma_f32_16x16x32_bf16 v[120:123], v[166:169], v[190:193], v[120:123]
	v_mfma_f32_16x16x32_bf16 v[108:111], v[158:161], v[198:201], v[108:111]
	v_mfma_f32_16x16x32_bf16 v[48:51], v[166:169], v[198:201], v[48:51]
	v_mfma_f32_16x16x32_bf16 v[100:103], v[158:161], v[206:209], v[100:103]
	v_mfma_f32_16x16x32_bf16 v[64:67], v[166:169], v[206:209], v[64:67]
	v_mfma_f32_16x16x32_bf16 v[92:95], v[158:161], v[214:217], v[92:95]
	v_mfma_f32_16x16x32_bf16 v[80:83], v[166:169], v[214:217], v[80:83]
	v_mfma_f32_16x16x32_bf16 v[116:119], v[170:173], v[186:189], v[116:119]
	v_mfma_f32_16x16x32_bf16 v[112:115], v[178:181], v[186:189], v[112:115]
	v_mfma_f32_16x16x32_bf16 v[104:107], v[170:173], v[194:197], v[104:107]
	v_mfma_f32_16x16x32_bf16 v[52:55], v[178:181], v[194:197], v[52:55]
	v_mfma_f32_16x16x32_bf16 v[96:99], v[170:173], v[202:205], v[96:99]
	v_mfma_f32_16x16x32_bf16 v[76:79], v[178:181], v[202:205], v[76:79]
	v_mfma_f32_16x16x32_bf16 v[88:91], v[170:173], v[210:213], v[88:91]
	v_mfma_f32_16x16x32_bf16 v[84:87], v[178:181], v[210:213], v[84:87]
	v_mfma_f32_16x16x32_bf16 v[116:119], v[174:177], v[190:193], v[116:119]
	v_mfma_f32_16x16x32_bf16 v[112:115], v[182:185], v[190:193], v[112:115]
	v_mfma_f32_16x16x32_bf16 v[104:107], v[174:177], v[198:201], v[104:107]
	v_mfma_f32_16x16x32_bf16 v[52:55], v[182:185], v[198:201], v[52:55]
	v_mfma_f32_16x16x32_bf16 v[96:99], v[174:177], v[206:209], v[96:99]
	v_mfma_f32_16x16x32_bf16 v[76:79], v[182:185], v[206:209], v[76:79]
	v_mfma_f32_16x16x32_bf16 v[88:91], v[174:177], v[214:217], v[88:91]
	v_mfma_f32_16x16x32_bf16 v[84:87], v[182:185], v[214:217], v[84:87]
	s_barrier
	s_add_u32 s98, s38, s14
	s_addc_u32 s99, s39, s15
	s_add_u32 s100, s40, s14
	s_addc_u32 s101, s41, s15
	s_add_i32 s66, s60, s33
	s_mov_b32 m0, s66
	ds_read_b128 v[186:189], v155 offset:16384
	ds_read_b128 v[190:193], v155 offset:17408
	ds_read_b128 v[194:197], v155 offset:18432
	ds_read_b128 v[198:201], v155 offset:19456
	ds_read_b128 v[202:205], v155 offset:20480
	ds_read_b128 v[206:209], v155 offset:21504
	ds_read_b128 v[210:213], v155 offset:22528
	ds_read_b128 v[214:217], v155 offset:23552
	global_load_lds_dwordx4 v130, s[38:39]
	s_add_i32 m0, s66, 0x2000
	s_add_u32 s66, s38, 0x100000
	s_addc_u32 s67, s39, 0
	s_add_i32 s68, s61, s33
	global_load_lds_dwordx4 v134, s[38:39]
	s_mov_b32 m0, s68
	s_nop 0
	global_load_lds_dwordx4 v130, s[66:67]
	s_add_i32 m0, s68, 0x2000
	s_nop 0
	global_load_lds_dwordx4 v134, s[66:67]
	s_mov_b32 m0, s31
	s_nop 0
	global_load_lds_dwordx4 v128, s[40:41]
	s_mov_b32 m0, s52
	s_nop 0
	global_load_lds_dwordx4 v132, s[40:41]
	s_waitcnt vmcnt(8)
	s_waitcnt lgkmcnt(0)
	s_barrier
	v_mfma_f32_16x16x32_bf16 v[72:75], v[144:147], v[186:189], v[72:75]
	v_mfma_f32_16x16x32_bf16 v[68:71], v[162:165], v[186:189], v[68:71]
	v_mfma_f32_16x16x32_bf16 v[44:47], v[144:147], v[194:197], v[44:47]
	v_mfma_f32_16x16x32_bf16 v[40:43], v[162:165], v[194:197], v[40:43]
	v_mfma_f32_16x16x32_bf16 v[28:31], v[144:147], v[202:205], v[28:31]
	v_mfma_f32_16x16x32_bf16 v[24:27], v[162:165], v[202:205], v[24:27]
	v_mfma_f32_16x16x32_bf16 v[12:15], v[144:147], v[210:213], v[12:15]
	v_mfma_f32_16x16x32_bf16 v[8:11], v[162:165], v[210:213], v[8:11]
	v_mfma_f32_16x16x32_bf16 v[72:75], v[158:161], v[190:193], v[72:75]
	v_mfma_f32_16x16x32_bf16 v[68:71], v[166:169], v[190:193], v[68:71]
	v_mfma_f32_16x16x32_bf16 v[44:47], v[158:161], v[198:201], v[44:47]
	v_mfma_f32_16x16x32_bf16 v[40:43], v[166:169], v[198:201], v[40:43]
	v_mfma_f32_16x16x32_bf16 v[28:31], v[158:161], v[206:209], v[28:31]
	v_mfma_f32_16x16x32_bf16 v[24:27], v[166:169], v[206:209], v[24:27]
	v_mfma_f32_16x16x32_bf16 v[12:15], v[158:161], v[214:217], v[12:15]
	v_mfma_f32_16x16x32_bf16 v[8:11], v[166:169], v[214:217], v[8:11]
	v_mfma_f32_16x16x32_bf16 v[60:63], v[170:173], v[186:189], v[60:63]
	v_mfma_f32_16x16x32_bf16 v[56:59], v[178:181], v[186:189], v[56:59]
	v_mfma_f32_16x16x32_bf16 v[36:39], v[170:173], v[194:197], v[36:39]
	v_mfma_f32_16x16x32_bf16 v[32:35], v[178:181], v[194:197], v[32:35]
	v_mfma_f32_16x16x32_bf16 v[20:23], v[170:173], v[202:205], v[20:23]
	v_mfma_f32_16x16x32_bf16 v[16:19], v[178:181], v[202:205], v[16:19]
	v_mfma_f32_16x16x32_bf16 v[4:7], v[170:173], v[210:213], v[4:7]
	v_mfma_f32_16x16x32_bf16 v[0:3], v[178:181], v[210:213], v[0:3]
	v_mfma_f32_16x16x32_bf16 v[60:63], v[174:177], v[190:193], v[60:63]
	v_mfma_f32_16x16x32_bf16 v[56:59], v[182:185], v[190:193], v[56:59]
	v_mfma_f32_16x16x32_bf16 v[36:39], v[174:177], v[198:201], v[36:39]
	v_mfma_f32_16x16x32_bf16 v[32:35], v[182:185], v[198:201], v[32:35]
	v_mfma_f32_16x16x32_bf16 v[20:23], v[174:177], v[206:209], v[20:23]
	v_mfma_f32_16x16x32_bf16 v[16:19], v[182:185], v[206:209], v[16:19]
	v_mfma_f32_16x16x32_bf16 v[4:7], v[174:177], v[214:217], v[4:7]
	v_mfma_f32_16x16x32_bf16 v[0:3], v[182:185], v[214:217], v[0:3]
	s_barrier
; #define PG8_STAGE(bufoff, gbase, voff) do { _Pragma("unroll") for (int _i = 0; _i < 2; ++_i) \
;         __builtin_amdgcn_global_load_lds((const unsigned*)((const char*)(gbase) + (voff)[_i]), (PG8_LAS unsigned*)(lds + (bufoff) + ldsw + _i * 8192), 16, 0, 0); } while (0)
; #define PG8_LDA(dst, b, h) do { _Pragma("unroll") for (int m = 0; m < 4; ++m) _Pragma("unroll") for (int k = 0; k < 2; ++k) dst[m][k] = *(const PG8_LAS bf16x8*)(lds + PG8_SA(b, h) + aoff + m * 2048 + k * 1024); } while (0)
; #define PG8_LDB(dst, b, h) do { _Pragma("unroll") for (int n = 0; n < 2; ++n) _Pragma("unroll") for (int k = 0; k < 2; ++k) dst[n][k] = *(const PG8_LAS bf16x8*)(lds + PG8_SB(b, h) + boff + n * 2048 + k * 1024); } while (0)
; #define PG8_MMA(ai, bj, At, Bt) do { __builtin_amdgcn_s_setprio(1); _Pragma("unroll") for (int m = 0; m < 4; ++m) _Pragma("unroll") for (int n = 0; n < 2; ++n) _Pragma("unroll") for (int k = 0; k < 2; ++k) \
;         acc[ai][bj][m][n] = __builtin_amdgcn_mfma_f32_16x16x32_bf16(Bt[n][k], At[m][k], acc[ai][bj][m][n], 0, 0, 0); __builtin_amdgcn_s_setprio(0); } while (0)
; #define PG8_WAIT_V(n) asm volatile("s_waitcnt vmcnt(" #n ")" ::: "memory")
; #define PG8_WAIT_L(n) asm volatile("s_waitcnt lgkmcnt(" #n ")" ::: "memory")
; #define PG8_BAR __builtin_amdgcn_s_barrier()
; #define PG8_SCHED __builtin_amdgcn_sched_barrier(0)
; template <class Epi, class Sched, bool ALIGN_EPI = false, bool SP2 = false>
; __device__ __forceinline__ void gemm_phase(PG8_LAS unsigned char* lds, const Gemm g, const Sched& S, const Epi& E) {
;     ...
;         for (int t = 0; t < nt; t += 2) {
;     ...
;             PG8_LDB(B0, 1, 0); PG8_LDB(B1, 1, 1); PG8_SCHED; PG8_LDA(At, 1, 0); PG8_STAGE(PG8_SA(0, 1), a2 + hstepA, voffA);
;             PG8_WAIT_V(8); PG8_WAIT_L(0); PG8_BAR; PG8_MMA(0, 0, At, B0); PG8_MMA(0, 1, At, B1); PG8_BAR; PG8_SCHED;
;             PG8_LDA(At, 1, 1); PG8_STAGE(PG8_SB(1, 0), b3, voffB); PG8_STAGE(PG8_SB(1, 1), b3 + hstep, voffB); PG8_STAGE(PG8_SA(1, 0), a3, voffA);
;             PG8_WAIT_V(8); PG8_WAIT_L(0); PG8_BAR; PG8_MMA(1, 0, At, B0); PG8_MMA(1, 1, At, B1); PG8_BAR; PG8_SCHED;
	s_add_i32 s66, 0, 0x18000
	v_add_u32_e32 v157, s66, v151
	s_add_i32 s67, 0, 0x1c000
	ds_read_b128 v[144:147], v157
	ds_read_b128 v[158:161], v157 offset:1024
	ds_read_b128 v[162:165], v157 offset:2048
	ds_read_b128 v[166:169], v157 offset:3072
	v_add_u32_e32 v157, s67, v151
	ds_read_b128 v[170:173], v157
	ds_read_b128 v[174:177], v157 offset:1024
	ds_read_b128 v[178:181], v157 offset:2048
	ds_read_b128 v[182:185], v157 offset:3072
	s_add_u32 s40, s40, 0x100000
	s_addc_u32 s41, s41, 0
	s_mov_b32 m0, s53
	ds_read_b128 v[186:189], v155 offset:32768
	ds_read_b128 v[190:193], v155 offset:33792
	ds_read_b128 v[194:197], v155 offset:34816
	ds_read_b128 v[198:201], v155 offset:35840
	ds_read_b128 v[202:205], v155 offset:36864
	ds_read_b128 v[206:209], v155 offset:37888
	ds_read_b128 v[210:213], v155 offset:38912
	ds_read_b128 v[214:217], v155 offset:39936
	global_load_lds_dwordx4 v128, s[40:41]
	s_mov_b32 m0, s54
	s_nop 0
	global_load_lds_dwordx4 v132, s[40:41]
	s_waitcnt vmcnt(8)
	s_waitcnt lgkmcnt(0)
	s_barrier
	v_mfma_f32_16x16x32_bf16 v[124:127], v[144:147], v[186:189], v[124:127]
	v_mfma_f32_16x16x32_bf16 v[120:123], v[162:165], v[186:189], v[120:123]
	v_mfma_f32_16x16x32_bf16 v[108:111], v[144:147], v[194:197], v[108:111]
	v_mfma_f32_16x16x32_bf16 v[48:51], v[162:165], v[194:197], v[48:51]
	v_mfma_f32_16x16x32_bf16 v[100:103], v[144:147], v[202:205], v[100:103]
	v_mfma_f32_16x16x32_bf16 v[64:67], v[162:165], v[202:205], v[64:67]
	v_mfma_f32_16x16x32_bf16 v[92:95], v[144:147], v[210:213], v[92:95]
	v_mfma_f32_16x16x32_bf16 v[80:83], v[162:165], v[210:213], v[80:83]
	v_mfma_f32_16x16x32_bf16 v[124:127], v[158:161], v[190:193], v[124:127]
	v_mfma_f32_16x16x32_bf16 v[120:123], v[166:169], v[190:193], v[120:123]
	v_mfma_f32_16x16x32_bf16 v[108:111], v[158:161], v[198:201], v[108:111]
	v_mfma_f32_16x16x32_bf16 v[48:51], v[166:169], v[198:201], v[48:51]
	v_mfma_f32_16x16x32_bf16 v[100:103], v[158:161], v[206:209], v[100:103]
	v_mfma_f32_16x16x32_bf16 v[64:67], v[166:169], v[206:209], v[64:67]
	v_mfma_f32_16x16x32_bf16 v[92:95], v[158:161], v[214:217], v[92:95]
	v_mfma_f32_16x16x32_bf16 v[80:83], v[166:169], v[214:217], v[80:83]
	v_mfma_f32_16x16x32_bf16 v[116:119], v[170:173], v[186:189], v[116:119]
	v_mfma_f32_16x16x32_bf16 v[112:115], v[178:181], v[186:189], v[112:115]
	v_mfma_f32_16x16x32_bf16 v[104:107], v[170:173], v[194:197], v[104:107]
	v_mfma_f32_16x16x32_bf16 v[52:55], v[178:181], v[194:197], v[52:55]
	v_mfma_f32_16x16x32_bf16 v[96:99], v[170:173], v[202:205], v[96:99]
	v_mfma_f32_16x16x32_bf16 v[76:79], v[178:181], v[202:205], v[76:79]
	v_mfma_f32_16x16x32_bf16 v[88:91], v[170:173], v[210:213], v[88:91]
	v_mfma_f32_16x16x32_bf16 v[84:87], v[178:181], v[210:213], v[84:87]
	v_mfma_f32_16x16x32_bf16 v[116:119], v[174:177], v[190:193], v[116:119]
	v_mfma_f32_16x16x32_bf16 v[112:115], v[182:185], v[190:193], v[112:115]
	v_mfma_f32_16x16x32_bf16 v[104:107], v[174:177], v[198:201], v[104:107]
	v_mfma_f32_16x16x32_bf16 v[52:55], v[182:185], v[198:201], v[52:55]
	v_mfma_f32_16x16x32_bf16 v[96:99], v[174:177], v[206:209], v[96:99]
	v_mfma_f32_16x16x32_bf16 v[76:79], v[182:185], v[206:209], v[76:79]
	v_mfma_f32_16x16x32_bf16 v[88:91], v[174:177], v[214:217], v[88:91]
	v_mfma_f32_16x16x32_bf16 v[84:87], v[182:185], v[214:217], v[84:87]
	s_barrier
	s_add_i32 s40, s66, s33
	s_mov_b32 m0, s40
	ds_read_b128 v[186:189], v155 offset:49152
	ds_read_b128 v[190:193], v155 offset:50176
	ds_read_b128 v[194:197], v155 offset:51200
	ds_read_b128 v[198:201], v155 offset:52224
	ds_read_b128 v[202:205], v155 offset:53248
	ds_read_b128 v[206:209], v155 offset:54272
	ds_read_b128 v[210:213], v155 offset:55296
	ds_read_b128 v[214:217], v155 offset:56320
	global_load_lds_dwordx4 v130, s[98:99]
	s_add_i32 m0, s40, 0x2000
	s_add_u32 s38, s38, 0x100080
	s_addc_u32 s39, s39, 0
	s_add_i32 s40, s67, s33
	global_load_lds_dwordx4 v134, s[98:99]
	s_mov_b32 m0, s40
	s_nop 0
	global_load_lds_dwordx4 v130, s[38:39]
	s_add_i32 m0, s40, 0x2000
	s_nop 0
	global_load_lds_dwordx4 v134, s[38:39]
	s_mov_b32 m0, s56
	s_nop 0
	global_load_lds_dwordx4 v128, s[100:101]
	s_mov_b32 m0, s57
	s_nop 0
	global_load_lds_dwordx4 v132, s[100:101]
	s_waitcnt vmcnt(8)
	s_waitcnt lgkmcnt(0)
	s_barrier
	v_mfma_f32_16x16x32_bf16 v[72:75], v[144:147], v[186:189], v[72:75]
	v_mfma_f32_16x16x32_bf16 v[68:71], v[162:165], v[186:189], v[68:71]
	v_mfma_f32_16x16x32_bf16 v[44:47], v[144:147], v[194:197], v[44:47]
	v_mfma_f32_16x16x32_bf16 v[40:43], v[162:165], v[194:197], v[40:43]
	v_mfma_f32_16x16x32_bf16 v[28:31], v[144:147], v[202:205], v[28:31]
	v_mfma_f32_16x16x32_bf16 v[24:27], v[162:165], v[202:205], v[24:27]
	v_mfma_f32_16x16x32_bf16 v[12:15], v[144:147], v[210:213], v[12:15]
	v_mfma_f32_16x16x32_bf16 v[8:11], v[162:165], v[210:213], v[8:11]
	v_mfma_f32_16x16x32_bf16 v[72:75], v[158:161], v[190:193], v[72:75]
	v_mfma_f32_16x16x32_bf16 v[68:71], v[166:169], v[190:193], v[68:71]
	v_mfma_f32_16x16x32_bf16 v[44:47], v[158:161], v[198:201], v[44:47]
	v_mfma_f32_16x16x32_bf16 v[40:43], v[166:169], v[198:201], v[40:43]
	v_mfma_f32_16x16x32_bf16 v[28:31], v[158:161], v[206:209], v[28:31]
	v_mfma_f32_16x16x32_bf16 v[24:27], v[166:169], v[206:209], v[24:27]
	v_mfma_f32_16x16x32_bf16 v[12:15], v[158:161], v[214:217], v[12:15]
	v_mfma_f32_16x16x32_bf16 v[8:11], v[166:169], v[214:217], v[8:11]
	v_mfma_f32_16x16x32_bf16 v[60:63], v[170:173], v[186:189], v[60:63]
	v_mfma_f32_16x16x32_bf16 v[56:59], v[178:181], v[186:189], v[56:59]
	v_mfma_f32_16x16x32_bf16 v[36:39], v[170:173], v[194:197], v[36:39]
	v_mfma_f32_16x16x32_bf16 v[32:35], v[178:181], v[194:197], v[32:35]
	v_mfma_f32_16x16x32_bf16 v[20:23], v[170:173], v[202:205], v[20:23]
	v_mfma_f32_16x16x32_bf16 v[16:19], v[178:181], v[202:205], v[16:19]
	v_mfma_f32_16x16x32_bf16 v[4:7], v[170:173], v[210:213], v[4:7]
	v_mfma_f32_16x16x32_bf16 v[0:3], v[178:181], v[210:213], v[0:3]
	v_mfma_f32_16x16x32_bf16 v[60:63], v[174:177], v[190:193], v[60:63]
	v_mfma_f32_16x16x32_bf16 v[56:59], v[182:185], v[190:193], v[56:59]
	v_mfma_f32_16x16x32_bf16 v[36:39], v[174:177], v[198:201], v[36:39]
	v_mfma_f32_16x16x32_bf16 v[32:35], v[182:185], v[198:201], v[32:35]
	v_mfma_f32_16x16x32_bf16 v[20:23], v[174:177], v[206:209], v[20:23]
	v_mfma_f32_16x16x32_bf16 v[16:19], v[182:185], v[206:209], v[16:19]
	v_mfma_f32_16x16x32_bf16 v[4:7], v[174:177], v[214:217], v[4:7]
	v_mfma_f32_16x16x32_bf16 v[0:3], v[182:185], v[214:217], v[0:3]
	s_barrier
	s_add_i32 s65, s65, 2
	s_add_u32 s34, s34, 0x100
	s_addc_u32 s35, s35, 0
	s_add_u32 s63, s63, 0x100
	s_addc_u32 s64, s64, 0
	s_cmp_gt_u32 s65, 61
	s_cbranch_scc0 .LBB0_1198
	s_and_b64 vcc, exec, s[16:17]
	s_cbranch_vccz .LBB0_1201
	s_barrier

; #define PG8_STAGE(bufoff, gbase, voff) do { _Pragma("unroll") for (int _i = 0; _i < 2; ++_i) \
;         __builtin_amdgcn_global_load_lds((const unsigned*)((const char*)(gbase) + (voff)[_i]), (PG8_LAS unsigned*)(lds + (bufoff) + ldsw + _i * 8192), 16, 0, 0); } while (0)
; #define PG8_LDA(dst, b, h) do { _Pragma("unroll") for (int m = 0; m < 4; ++m) _Pragma("unroll") for (int k = 0; k < 2; ++k) dst[m][k] = *(const PG8_LAS bf16x8*)(lds + PG8_SA(b, h) + aoff + m * 2048 + k * 1024); } while (0)
; #define PG8_LDB(dst, b, h) do { _Pragma("unroll") for (int n = 0; n < 2; ++n) _Pragma("unroll") for (int k = 0; k < 2; ++k) dst[n][k] = *(const PG8_LAS bf16x8*)(lds + PG8_SB(b, h) + boff + n * 2048 + k * 1024); } while (0)
; #define PG8_MMA(ai, bj, At, Bt) do { __builtin_amdgcn_s_setprio(1); _Pragma("unroll") for (int m = 0; m < 4; ++m) _Pragma("unroll") for (int n = 0; n < 2; ++n) _Pragma("unroll") for (int k = 0; k < 2; ++k) \
;         acc[ai][bj][m][n] = __builtin_amdgcn_mfma_f32_16x16x32_bf16(Bt[n][k], At[m][k], acc[ai][bj][m][n], 0, 0, 0); __builtin_amdgcn_s_setprio(0); } while (0)
; #define PG8_WAIT_V(n) asm volatile("s_waitcnt vmcnt(" #n ")" ::: "memory")
; #define PG8_WAIT_L(n) asm volatile("s_waitcnt lgkmcnt(" #n ")" ::: "memory")
; #define PG8_BAR __builtin_amdgcn_s_barrier()
; #define PG8_SCHED __builtin_amdgcn_sched_barrier(0)
; template <class Epi, class Sched, bool ALIGN_EPI = false, bool SP2 = false>
; __device__ __forceinline__ void gemm_phase(PG8_LAS unsigned char* lds, const Gemm g, const Sched& S, const Epi& E) {
;     ...
;             PG8_LDB(B0, 0, 0); PG8_LDB(B1, 0, 1); PG8_SCHED; PG8_LDA(At, 0, 0); PG8_STAGE(PG8_SA(1, 1), a1 + hstepA, voffA);
;             PG8_WAIT_V(8); PG8_WAIT_L(0); PG8_BAR; PG8_MMA(0, 0, At, B0); PG8_MMA(0, 1, At, B1); PG8_BAR; PG8_SCHED;
;             PG8_LDA(At, 0, 1); PG8_STAGE(PG8_SB(0, 0), b2, voffB); PG8_STAGE(PG8_SB(0, 1), b2 + hstep, voffB); PG8_STAGE(PG8_SA(0, 0), a2, voffA);
;             PG8_WAIT_V(8); PG8_WAIT_L(0); PG8_BAR; PG8_MMA(1, 0, At, B0); PG8_MMA(1, 1, At, B1); PG8_BAR; PG8_SCHED;
.LBB0_1310:
	ds_read_b128 v[128:131], v236
	ds_read_b128 v[132:135], v236 offset:1024
	ds_read_b128 v[136:139], v236 offset:2048
	ds_read_b128 v[140:143], v236 offset:3072
	ds_read_b128 v[144:147], v237
	ds_read_b128 v[148:151], v237 offset:1024
	ds_read_b128 v[152:155], v237 offset:2048
	ds_read_b128 v[156:159], v237 offset:3072
	s_add_u32 s96, s94, 0x100
	s_addc_u32 s97, s95, 0
	s_cmp_eq_u32 s71, 60
	s_cselect_b32 s7, s41, s97
	s_cselect_b32 s6, s52, s96
	s_cselect_b32 vcc_hi, s39, s70
	s_cselect_b32 vcc_lo, s53, s69
	v_lshl_add_u64 v[164:165], s[94:95], 0, v[178:179]
	s_add_i32 m0, s56, 0xc000
	ds_read_b128 v[160:163], v238
	ds_read_b128 v[186:189], v238 offset:1024
	ds_read_b128 v[190:193], v238 offset:2048
	ds_read_b128 v[194:197], v238 offset:3072
	ds_read_b128 v[198:201], v238 offset:4096
	ds_read_b128 v[202:205], v238 offset:5120
	ds_read_b128 v[206:209], v238 offset:6144
	ds_read_b128 v[210:213], v238 offset:7168
	global_load_lds_dwordx4 v[164:165], off
	v_lshl_add_u64 v[164:165], s[94:95], 0, v[180:181]
	s_add_i32 m0, s56, 0xe000
	s_nop 0
	global_load_lds_dwordx4 v[164:165], off
	s_waitcnt vmcnt(8)
	s_waitcnt lgkmcnt(0)
	s_barrier
	v_mfma_f32_16x16x32_bf16 v[124:127], v[128:131], v[160:163], v[124:127]
	v_mfma_f32_16x16x32_bf16 v[120:123], v[136:139], v[160:163], v[120:123]
	v_mfma_f32_16x16x32_bf16 v[108:111], v[128:131], v[190:193], v[108:111]
	v_mfma_f32_16x16x32_bf16 v[104:107], v[136:139], v[190:193], v[104:107]
	v_mfma_f32_16x16x32_bf16 v[92:95], v[128:131], v[198:201], v[92:95]
	v_mfma_f32_16x16x32_bf16 v[88:91], v[136:139], v[198:201], v[88:91]
	v_mfma_f32_16x16x32_bf16 v[76:79], v[128:131], v[206:209], v[76:79]
	v_mfma_f32_16x16x32_bf16 v[72:75], v[136:139], v[206:209], v[72:75]
	v_mfma_f32_16x16x32_bf16 v[124:127], v[132:135], v[186:189], v[124:127]
	v_mfma_f32_16x16x32_bf16 v[120:123], v[140:143], v[186:189], v[120:123]
	v_mfma_f32_16x16x32_bf16 v[108:111], v[132:135], v[194:197], v[108:111]
	v_mfma_f32_16x16x32_bf16 v[104:107], v[140:143], v[194:197], v[104:107]
	v_mfma_f32_16x16x32_bf16 v[92:95], v[132:135], v[202:205], v[92:95]
	v_mfma_f32_16x16x32_bf16 v[88:91], v[140:143], v[202:205], v[88:91]
	v_mfma_f32_16x16x32_bf16 v[76:79], v[132:135], v[210:213], v[76:79]
	v_mfma_f32_16x16x32_bf16 v[72:75], v[140:143], v[210:213], v[72:75]
	v_mfma_f32_16x16x32_bf16 v[116:119], v[144:147], v[160:163], v[116:119]
	v_mfma_f32_16x16x32_bf16 v[112:115], v[152:155], v[160:163], v[112:115]
	v_mfma_f32_16x16x32_bf16 v[100:103], v[144:147], v[190:193], v[100:103]
	v_mfma_f32_16x16x32_bf16 v[96:99], v[152:155], v[190:193], v[96:99]
	v_mfma_f32_16x16x32_bf16 v[84:87], v[144:147], v[198:201], v[84:87]
	v_mfma_f32_16x16x32_bf16 v[80:83], v[152:155], v[198:201], v[80:83]
	v_mfma_f32_16x16x32_bf16 v[68:71], v[144:147], v[206:209], v[68:71]
	v_mfma_f32_16x16x32_bf16 v[64:67], v[152:155], v[206:209], v[64:67]
	v_mfma_f32_16x16x32_bf16 v[116:119], v[148:151], v[186:189], v[116:119]
	v_mfma_f32_16x16x32_bf16 v[112:115], v[156:159], v[186:189], v[112:115]
	v_mfma_f32_16x16x32_bf16 v[100:103], v[148:151], v[194:197], v[100:103]
	v_mfma_f32_16x16x32_bf16 v[96:99], v[156:159], v[194:197], v[96:99]
	v_mfma_f32_16x16x32_bf16 v[84:87], v[148:151], v[202:205], v[84:87]
	v_mfma_f32_16x16x32_bf16 v[80:83], v[156:159], v[202:205], v[80:83]
	v_mfma_f32_16x16x32_bf16 v[68:71], v[148:151], v[210:213], v[68:71]
	v_mfma_f32_16x16x32_bf16 v[64:67], v[156:159], v[210:213], v[64:67]
	s_barrier
	s_add_u32 s98, vcc_lo, s10
	s_addc_u32 s99, vcc_hi, s11
	s_add_u32 s100, s6, s10
	s_addc_u32 s101, s7, s11
	s_add_i32 s72, s65, s55
	s_mov_b32 m0, s72
	ds_read_b128 v[160:163], v238 offset:16384
	ds_read_b128 v[186:189], v238 offset:17408
	ds_read_b128 v[190:193], v238 offset:18432
	ds_read_b128 v[194:197], v238 offset:19456
	ds_read_b128 v[198:201], v238 offset:20480
	ds_read_b128 v[202:205], v238 offset:21504
	ds_read_b128 v[206:209], v238 offset:22528
	ds_read_b128 v[210:213], v238 offset:23552
	global_load_lds_dwordx4 v168, vcc
	s_add_i32 m0, s72, 0x2000
	s_add_u32 s72, vcc_lo, 0x100000
	s_addc_u32 s73, vcc_hi, 0
	s_add_i32 s74, s66, s55
	global_load_lds_dwordx4 v172, vcc
	s_mov_b32 m0, s74
	s_nop 0
	global_load_lds_dwordx4 v168, s[72:73]
	s_add_i32 m0, s74, 0x2000
	s_nop 0
	global_load_lds_dwordx4 v172, s[72:73]
	s_mov_b32 m0, s56
	s_nop 0
	global_load_lds_dwordx4 v166, s[6:7]
	s_mov_b32 m0, s57
	s_nop 0
	global_load_lds_dwordx4 v170, s[6:7]
	s_waitcnt vmcnt(8)
	s_waitcnt lgkmcnt(0)
	s_barrier
	v_mfma_f32_16x16x32_bf16 v[60:63], v[128:131], v[160:163], v[60:63]
	v_mfma_f32_16x16x32_bf16 v[56:59], v[136:139], v[160:163], v[56:59]
	v_mfma_f32_16x16x32_bf16 v[44:47], v[128:131], v[190:193], v[44:47]
	v_mfma_f32_16x16x32_bf16 v[40:43], v[136:139], v[190:193], v[40:43]
	v_mfma_f32_16x16x32_bf16 v[28:31], v[128:131], v[198:201], v[28:31]
	v_mfma_f32_16x16x32_bf16 v[24:27], v[136:139], v[198:201], v[24:27]
	v_mfma_f32_16x16x32_bf16 v[12:15], v[128:131], v[206:209], v[12:15]
	v_mfma_f32_16x16x32_bf16 v[8:11], v[136:139], v[206:209], v[8:11]
	v_mfma_f32_16x16x32_bf16 v[60:63], v[132:135], v[186:189], v[60:63]
	v_mfma_f32_16x16x32_bf16 v[56:59], v[140:143], v[186:189], v[56:59]
	v_mfma_f32_16x16x32_bf16 v[44:47], v[132:135], v[194:197], v[44:47]
	v_mfma_f32_16x16x32_bf16 v[40:43], v[140:143], v[194:197], v[40:43]
	v_mfma_f32_16x16x32_bf16 v[28:31], v[132:135], v[202:205], v[28:31]
	v_mfma_f32_16x16x32_bf16 v[24:27], v[140:143], v[202:205], v[24:27]
	v_mfma_f32_16x16x32_bf16 v[12:15], v[132:135], v[210:213], v[12:15]
	v_mfma_f32_16x16x32_bf16 v[8:11], v[140:143], v[210:213], v[8:11]
	v_mfma_f32_16x16x32_bf16 v[52:55], v[144:147], v[160:163], v[52:55]
	v_mfma_f32_16x16x32_bf16 v[48:51], v[152:155], v[160:163], v[48:51]
	v_mfma_f32_16x16x32_bf16 v[36:39], v[144:147], v[190:193], v[36:39]
	v_mfma_f32_16x16x32_bf16 v[32:35], v[152:155], v[190:193], v[32:35]
	v_mfma_f32_16x16x32_bf16 v[20:23], v[144:147], v[198:201], v[20:23]
	v_mfma_f32_16x16x32_bf16 v[16:19], v[152:155], v[198:201], v[16:19]
	v_mfma_f32_16x16x32_bf16 v[4:7], v[144:147], v[206:209], v[4:7]
	v_mfma_f32_16x16x32_bf16 v[0:3], v[152:155], v[206:209], v[0:3]
	v_mfma_f32_16x16x32_bf16 v[52:55], v[148:151], v[186:189], v[52:55]
	v_mfma_f32_16x16x32_bf16 v[48:51], v[156:159], v[186:189], v[48:51]
	v_mfma_f32_16x16x32_bf16 v[36:39], v[148:151], v[194:197], v[36:39]
	v_mfma_f32_16x16x32_bf16 v[32:35], v[156:159], v[194:197], v[32:35]
	v_mfma_f32_16x16x32_bf16 v[20:23], v[148:151], v[202:205], v[20:23]
	v_mfma_f32_16x16x32_bf16 v[16:19], v[156:159], v[202:205], v[16:19]
	v_mfma_f32_16x16x32_bf16 v[4:7], v[148:151], v[210:213], v[4:7]
	v_mfma_f32_16x16x32_bf16 v[0:3], v[156:159], v[210:213], v[0:3]
	s_barrier
; #define PG8_STAGE(bufoff, gbase, voff) do { _Pragma("unroll") for (int _i = 0; _i < 2; ++_i) \
;         __builtin_amdgcn_global_load_lds((const unsigned*)((const char*)(gbase) + (voff)[_i]), (PG8_LAS unsigned*)(lds + (bufoff) + ldsw + _i * 8192), 16, 0, 0); } while (0)
; #define PG8_LDA(dst, b, h) do { _Pragma("unroll") for (int m = 0; m < 4; ++m) _Pragma("unroll") for (int k = 0; k < 2; ++k) dst[m][k] = *(const PG8_LAS bf16x8*)(lds + PG8_SA(b, h) + aoff + m * 2048 + k * 1024); } while (0)
; #define PG8_LDB(dst, b, h) do { _Pragma("unroll") for (int n = 0; n < 2; ++n) _Pragma("unroll") for (int k = 0; k < 2; ++k) dst[n][k] = *(const PG8_LAS bf16x8*)(lds + PG8_SB(b, h) + boff + n * 2048 + k * 1024); } while (0)
; #define PG8_MMA(ai, bj, At, Bt) do { __builtin_amdgcn_s_setprio(1); _Pragma("unroll") for (int m = 0; m < 4; ++m) _Pragma("unroll") for (int n = 0; n < 2; ++n) _Pragma("unroll") for (int k = 0; k < 2; ++k) \
;         acc[ai][bj][m][n] = __builtin_amdgcn_mfma_f32_16x16x32_bf16(Bt[n][k], At[m][k], acc[ai][bj][m][n], 0, 0, 0); __builtin_amdgcn_s_setprio(0); } while (0)
; #define PG8_WAIT_V(n) asm volatile("s_waitcnt vmcnt(" #n ")" ::: "memory")
; #define PG8_WAIT_L(n) asm volatile("s_waitcnt lgkmcnt(" #n ")" ::: "memory")
; #define PG8_BAR __builtin_amdgcn_s_barrier()
; #define PG8_SCHED __builtin_amdgcn_sched_barrier(0)
; template <class Epi, class Sched, bool ALIGN_EPI = false, bool SP2 = false>
; __device__ __forceinline__ void gemm_phase(PG8_LAS unsigned char* lds, const Gemm g, const Sched& S, const Epi& E) {
;     ...
;         for (int t = 0; t < nt; t += 2) {
;     ...
;             PG8_LDB(B0, 1, 0); PG8_LDB(B1, 1, 1); PG8_SCHED; PG8_LDA(At, 1, 0); PG8_STAGE(PG8_SA(0, 1), a2 + hstepA, voffA);
;             PG8_WAIT_V(8); PG8_WAIT_L(0); PG8_BAR; PG8_MMA(0, 0, At, B0); PG8_MMA(0, 1, At, B1); PG8_BAR; PG8_SCHED;
;             PG8_LDA(At, 1, 1); PG8_STAGE(PG8_SB(1, 0), b3, voffB); PG8_STAGE(PG8_SB(1, 1), b3 + hstep, voffB); PG8_STAGE(PG8_SA(1, 0), a3, voffA);
;             PG8_WAIT_V(8); PG8_WAIT_L(0); PG8_BAR; PG8_MMA(1, 0, At, B0); PG8_MMA(1, 1, At, B1); PG8_BAR; PG8_SCHED;
	s_add_i32 s72, 0, 0x18000
	s_add_i32 s73, 0, 0x1c000
	v_add_u32_e32 v140, s72, v234
	v_add_u32_e32 v156, s73, v234
	ds_read_b128 v[128:131], v140
	ds_read_b128 v[132:135], v140 offset:1024
	ds_read_b128 v[136:139], v140 offset:2048
	ds_read_b128 v[140:143], v140 offset:3072
	ds_read_b128 v[144:147], v156
	ds_read_b128 v[148:151], v156 offset:1024
	ds_read_b128 v[152:155], v156 offset:2048
	ds_read_b128 v[156:159], v156 offset:3072
	s_add_u32 s6, s6, 0x100000
	s_addc_u32 s7, s7, 0
	s_mov_b32 m0, s58
	ds_read_b128 v[160:163], v238 offset:32768
	ds_read_b128 v[186:189], v238 offset:33792
	ds_read_b128 v[190:193], v238 offset:34816
	ds_read_b128 v[194:197], v238 offset:35840
	ds_read_b128 v[198:201], v238 offset:36864
	ds_read_b128 v[202:205], v238 offset:37888
	ds_read_b128 v[206:209], v238 offset:38912
	ds_read_b128 v[210:213], v238 offset:39936
	global_load_lds_dwordx4 v166, s[6:7]
	s_mov_b32 m0, s59
	s_nop 0
	global_load_lds_dwordx4 v170, s[6:7]
	s_waitcnt vmcnt(8)
	s_waitcnt lgkmcnt(0)
	s_barrier
	v_mfma_f32_16x16x32_bf16 v[124:127], v[128:131], v[160:163], v[124:127]
	v_mfma_f32_16x16x32_bf16 v[120:123], v[136:139], v[160:163], v[120:123]
	v_mfma_f32_16x16x32_bf16 v[108:111], v[128:131], v[190:193], v[108:111]
	v_mfma_f32_16x16x32_bf16 v[104:107], v[136:139], v[190:193], v[104:107]
	v_mfma_f32_16x16x32_bf16 v[92:95], v[128:131], v[198:201], v[92:95]
	v_mfma_f32_16x16x32_bf16 v[88:91], v[136:139], v[198:201], v[88:91]
	v_mfma_f32_16x16x32_bf16 v[76:79], v[128:131], v[206:209], v[76:79]
	v_mfma_f32_16x16x32_bf16 v[72:75], v[136:139], v[206:209], v[72:75]
	v_mfma_f32_16x16x32_bf16 v[124:127], v[132:135], v[186:189], v[124:127]
	v_mfma_f32_16x16x32_bf16 v[120:123], v[140:143], v[186:189], v[120:123]
	v_mfma_f32_16x16x32_bf16 v[108:111], v[132:135], v[194:197], v[108:111]
	v_mfma_f32_16x16x32_bf16 v[104:107], v[140:143], v[194:197], v[104:107]
	v_mfma_f32_16x16x32_bf16 v[92:95], v[132:135], v[202:205], v[92:95]
	v_mfma_f32_16x16x32_bf16 v[88:91], v[140:143], v[202:205], v[88:91]
	v_mfma_f32_16x16x32_bf16 v[76:79], v[132:135], v[210:213], v[76:79]
	v_mfma_f32_16x16x32_bf16 v[72:75], v[140:143], v[210:213], v[72:75]
	v_mfma_f32_16x16x32_bf16 v[116:119], v[144:147], v[160:163], v[116:119]
	v_mfma_f32_16x16x32_bf16 v[112:115], v[152:155], v[160:163], v[112:115]
	v_mfma_f32_16x16x32_bf16 v[100:103], v[144:147], v[190:193], v[100:103]
	v_mfma_f32_16x16x32_bf16 v[96:99], v[152:155], v[190:193], v[96:99]
	v_mfma_f32_16x16x32_bf16 v[84:87], v[144:147], v[198:201], v[84:87]
	v_mfma_f32_16x16x32_bf16 v[80:83], v[152:155], v[198:201], v[80:83]
	v_mfma_f32_16x16x32_bf16 v[68:71], v[144:147], v[206:209], v[68:71]
	v_mfma_f32_16x16x32_bf16 v[64:67], v[152:155], v[206:209], v[64:67]
	v_mfma_f32_16x16x32_bf16 v[116:119], v[148:151], v[186:189], v[116:119]
	v_mfma_f32_16x16x32_bf16 v[112:115], v[156:159], v[186:189], v[112:115]
	v_mfma_f32_16x16x32_bf16 v[100:103], v[148:151], v[194:197], v[100:103]
	v_mfma_f32_16x16x32_bf16 v[96:99], v[156:159], v[194:197], v[96:99]
	v_mfma_f32_16x16x32_bf16 v[84:87], v[148:151], v[202:205], v[84:87]
	v_mfma_f32_16x16x32_bf16 v[80:83], v[156:159], v[202:205], v[80:83]
	v_mfma_f32_16x16x32_bf16 v[68:71], v[148:151], v[210:213], v[68:71]
	v_mfma_f32_16x16x32_bf16 v[64:67], v[156:159], v[210:213], v[64:67]
	s_barrier
	s_add_i32 s6, s72, s55
	s_mov_b32 m0, s6
	ds_read_b128 v[160:163], v238 offset:49152
	ds_read_b128 v[186:189], v238 offset:50176
	ds_read_b128 v[190:193], v238 offset:51200
	ds_read_b128 v[194:197], v238 offset:52224
	ds_read_b128 v[198:201], v238 offset:53248
	ds_read_b128 v[202:205], v238 offset:54272
	ds_read_b128 v[206:209], v238 offset:55296
	ds_read_b128 v[210:213], v238 offset:56320
	global_load_lds_dwordx4 v168, s[98:99]
	s_add_i32 m0, s6, 0x2000
	s_add_u32 s6, vcc_lo, 0x100080
	s_addc_u32 s7, vcc_hi, 0
	s_add_i32 s72, s73, s55
	global_load_lds_dwordx4 v172, s[98:99]
	s_mov_b32 m0, s72
	s_nop 0
	global_load_lds_dwordx4 v168, s[6:7]
	s_add_i32 m0, s72, 0x2000
	s_nop 0
	global_load_lds_dwordx4 v172, s[6:7]
	s_mov_b32 m0, s63
	s_nop 0
	global_load_lds_dwordx4 v166, s[100:101]
	s_mov_b32 m0, s64
	s_nop 0
	global_load_lds_dwordx4 v170, s[100:101]
	s_waitcnt vmcnt(8)
	s_waitcnt lgkmcnt(0)
	s_barrier
	v_mfma_f32_16x16x32_bf16 v[60:63], v[128:131], v[160:163], v[60:63]
	v_mfma_f32_16x16x32_bf16 v[56:59], v[136:139], v[160:163], v[56:59]
	v_mfma_f32_16x16x32_bf16 v[44:47], v[128:131], v[190:193], v[44:47]
	v_mfma_f32_16x16x32_bf16 v[40:43], v[136:139], v[190:193], v[40:43]
	v_mfma_f32_16x16x32_bf16 v[28:31], v[128:131], v[198:201], v[28:31]
	v_mfma_f32_16x16x32_bf16 v[24:27], v[136:139], v[198:201], v[24:27]
	v_mfma_f32_16x16x32_bf16 v[12:15], v[128:131], v[206:209], v[12:15]
	v_mfma_f32_16x16x32_bf16 v[8:11], v[136:139], v[206:209], v[8:11]
	v_mfma_f32_16x16x32_bf16 v[60:63], v[132:135], v[186:189], v[60:63]
	v_mfma_f32_16x16x32_bf16 v[56:59], v[140:143], v[186:189], v[56:59]
	v_mfma_f32_16x16x32_bf16 v[44:47], v[132:135], v[194:197], v[44:47]
	v_mfma_f32_16x16x32_bf16 v[40:43], v[140:143], v[194:197], v[40:43]
	v_mfma_f32_16x16x32_bf16 v[28:31], v[132:135], v[202:205], v[28:31]
	v_mfma_f32_16x16x32_bf16 v[24:27], v[140:143], v[202:205], v[24:27]
	v_mfma_f32_16x16x32_bf16 v[12:15], v[132:135], v[210:213], v[12:15]
	v_mfma_f32_16x16x32_bf16 v[8:11], v[140:143], v[210:213], v[8:11]
	v_mfma_f32_16x16x32_bf16 v[52:55], v[144:147], v[160:163], v[52:55]
	v_mfma_f32_16x16x32_bf16 v[48:51], v[152:155], v[160:163], v[48:51]
	v_mfma_f32_16x16x32_bf16 v[36:39], v[144:147], v[190:193], v[36:39]
	v_mfma_f32_16x16x32_bf16 v[32:35], v[152:155], v[190:193], v[32:35]
	v_mfma_f32_16x16x32_bf16 v[20:23], v[144:147], v[198:201], v[20:23]
	v_mfma_f32_16x16x32_bf16 v[16:19], v[152:155], v[198:201], v[16:19]
	v_mfma_f32_16x16x32_bf16 v[4:7], v[144:147], v[206:209], v[4:7]
	v_mfma_f32_16x16x32_bf16 v[0:3], v[152:155], v[206:209], v[0:3]
	v_mfma_f32_16x16x32_bf16 v[52:55], v[148:151], v[186:189], v[52:55]
	v_mfma_f32_16x16x32_bf16 v[48:51], v[156:159], v[186:189], v[48:51]
	v_mfma_f32_16x16x32_bf16 v[36:39], v[148:151], v[194:197], v[36:39]
	v_mfma_f32_16x16x32_bf16 v[32:35], v[156:159], v[194:197], v[32:35]
	v_mfma_f32_16x16x32_bf16 v[20:23], v[148:151], v[202:205], v[20:23]
	v_mfma_f32_16x16x32_bf16 v[16:19], v[156:159], v[202:205], v[16:19]
	v_mfma_f32_16x16x32_bf16 v[4:7], v[148:151], v[210:213], v[4:7]
	v_mfma_f32_16x16x32_bf16 v[0:3], v[156:159], v[210:213], v[0:3]
	s_barrier
	s_add_i32 s71, s71, 2
	s_add_u32 s69, s69, 0x100
	s_addc_u32 s70, s70, 0
	s_cmp_gt_u32 s71, 61
	s_mov_b64 s[94:95], s[96:97]
	s_cbranch_scc0 .LBB0_1310
	s_and_b64 vcc, exec, s[12:13]
	s_cbranch_vccz .LBB0_1313
	s_barrier

; #define PG8_STAGE(bufoff, gbase, voff) do { _Pragma("unroll") for (int _i = 0; _i < 2; ++_i) \
;         __builtin_amdgcn_global_load_lds((const unsigned*)((const char*)(gbase) + (voff)[_i]), (PG8_LAS unsigned*)(lds + (bufoff) + ldsw + _i * 8192), 16, 0, 0); } while (0)
; #define PG8_LDA(dst, b, h) do { _Pragma("unroll") for (int m = 0; m < 4; ++m) _Pragma("unroll") for (int k = 0; k < 2; ++k) dst[m][k] = *(const PG8_LAS bf16x8*)(lds + PG8_SA(b, h) + aoff + m * 2048 + k * 1024); } while (0)
; #define PG8_LDB(dst, b, h) do { _Pragma("unroll") for (int n = 0; n < 2; ++n) _Pragma("unroll") for (int k = 0; k < 2; ++k) dst[n][k] = *(const PG8_LAS bf16x8*)(lds + PG8_SB(b, h) + boff + n * 2048 + k * 1024); } while (0)
; #define PG8_MMA(ai, bj, At, Bt) do { __builtin_amdgcn_s_setprio(1); _Pragma("unroll") for (int m = 0; m < 4; ++m) _Pragma("unroll") for (int n = 0; n < 2; ++n) _Pragma("unroll") for (int k = 0; k < 2; ++k) \
;         acc[ai][bj][m][n] = __builtin_amdgcn_mfma_f32_16x16x32_bf16(Bt[n][k], At[m][k], acc[ai][bj][m][n], 0, 0, 0); __builtin_amdgcn_s_setprio(0); } while (0)
; #define PG8_WAIT_V(n) asm volatile("s_waitcnt vmcnt(" #n ")" ::: "memory")
; #define PG8_WAIT_L(n) asm volatile("s_waitcnt lgkmcnt(" #n ")" ::: "memory")
; #define PG8_BAR __builtin_amdgcn_s_barrier()
; #define PG8_SCHED __builtin_amdgcn_sched_barrier(0)
; template <class Epi, class Sched, bool ALIGN_EPI = false, bool SP2 = false>
; __device__ __forceinline__ void gemm_phase(PG8_LAS unsigned char* lds, const Gemm g, const Sched& S, const Epi& E) {
;     ...
;             PG8_LDB(B0, 0, 0); PG8_LDB(B1, 0, 1); PG8_SCHED; PG8_LDA(At, 0, 0); PG8_STAGE(PG8_SA(1, 1), a1 + hstepA, voffA);
;             PG8_WAIT_V(8); PG8_WAIT_L(0); PG8_BAR; PG8_MMA(0, 0, At, B0); PG8_MMA(0, 1, At, B1); PG8_BAR; PG8_SCHED;
;             PG8_LDA(At, 0, 1); PG8_STAGE(PG8_SB(0, 0), b2, voffB); PG8_STAGE(PG8_SB(0, 1), b2 + hstep, voffB); PG8_STAGE(PG8_SA(0, 0), a2, voffA);
;             PG8_WAIT_V(8); PG8_WAIT_L(0); PG8_BAR; PG8_MMA(1, 0, At, B0); PG8_MMA(1, 1, At, B1); PG8_BAR; PG8_SCHED;
.LBB0_1515:
	ds_read_b128 v[144:147], v153
	ds_read_b128 v[158:161], v153 offset:1024
	ds_read_b128 v[162:165], v153 offset:2048
	ds_read_b128 v[166:169], v153 offset:3072
	ds_read_b128 v[170:173], v154
	ds_read_b128 v[174:177], v154 offset:1024
	ds_read_b128 v[178:181], v154 offset:2048
	ds_read_b128 v[182:185], v154 offset:3072
	s_add_u32 s24, s22, 0x4000
	s_addc_u32 s25, s23, 0
	s_cmpk_eq_i32 s63, 0xa8
	s_cselect_b32 s30, s6, s24
	s_cselect_b32 s31, s7, s25
	s_cselect_b32 s26, s20, s61
	s_cselect_b32 s27, s21, s62
	s_add_u32 s24, s30, 0x8000
	s_addc_u32 s25, s31, 0
	s_add_i32 m0, s34, 0xc000
	ds_read_b128 v[186:189], v155
	ds_read_b128 v[190:193], v155 offset:1024
	ds_read_b128 v[194:197], v155 offset:2048
	ds_read_b128 v[198:201], v155 offset:3072
	ds_read_b128 v[202:205], v155 offset:4096
	ds_read_b128 v[206:209], v155 offset:5120
	ds_read_b128 v[210:213], v155 offset:6144
	ds_read_b128 v[214:217], v155 offset:7168
	global_load_lds_dwordx4 v136, s[22:23]
	s_add_i32 m0, s34, 0xe000
	s_nop 0
	global_load_lds_dwordx4 v138, s[22:23]
	s_waitcnt vmcnt(8)
	s_waitcnt lgkmcnt(0)
	s_barrier
	v_mfma_f32_16x16x32_bf16 v[124:127], v[144:147], v[186:189], v[124:127]
	v_mfma_f32_16x16x32_bf16 v[120:123], v[162:165], v[186:189], v[120:123]
	v_mfma_f32_16x16x32_bf16 v[108:111], v[144:147], v[194:197], v[108:111]
	v_mfma_f32_16x16x32_bf16 v[48:51], v[162:165], v[194:197], v[48:51]
	v_mfma_f32_16x16x32_bf16 v[100:103], v[144:147], v[202:205], v[100:103]
	v_mfma_f32_16x16x32_bf16 v[64:67], v[162:165], v[202:205], v[64:67]
	v_mfma_f32_16x16x32_bf16 v[92:95], v[144:147], v[210:213], v[92:95]
	v_mfma_f32_16x16x32_bf16 v[80:83], v[162:165], v[210:213], v[80:83]
	v_mfma_f32_16x16x32_bf16 v[124:127], v[158:161], v[190:193], v[124:127]
	v_mfma_f32_16x16x32_bf16 v[120:123], v[166:169], v[190:193], v[120:123]
	v_mfma_f32_16x16x32_bf16 v[108:111], v[158:161], v[198:201], v[108:111]
	v_mfma_f32_16x16x32_bf16 v[48:51], v[166:169], v[198:201], v[48:51]
	v_mfma_f32_16x16x32_bf16 v[100:103], v[158:161], v[206:209], v[100:103]
	v_mfma_f32_16x16x32_bf16 v[64:67], v[166:169], v[206:209], v[64:67]
	v_mfma_f32_16x16x32_bf16 v[92:95], v[158:161], v[214:217], v[92:95]
	v_mfma_f32_16x16x32_bf16 v[80:83], v[166:169], v[214:217], v[80:83]
	v_mfma_f32_16x16x32_bf16 v[116:119], v[170:173], v[186:189], v[116:119]
	v_mfma_f32_16x16x32_bf16 v[112:115], v[178:181], v[186:189], v[112:115]
	v_mfma_f32_16x16x32_bf16 v[104:107], v[170:173], v[194:197], v[104:107]
	v_mfma_f32_16x16x32_bf16 v[52:55], v[178:181], v[194:197], v[52:55]
	v_mfma_f32_16x16x32_bf16 v[96:99], v[170:173], v[202:205], v[96:99]
	v_mfma_f32_16x16x32_bf16 v[76:79], v[178:181], v[202:205], v[76:79]
	v_mfma_f32_16x16x32_bf16 v[88:91], v[170:173], v[210:213], v[88:91]
	v_mfma_f32_16x16x32_bf16 v[84:87], v[178:181], v[210:213], v[84:87]
	v_mfma_f32_16x16x32_bf16 v[116:119], v[174:177], v[190:193], v[116:119]
	v_mfma_f32_16x16x32_bf16 v[112:115], v[182:185], v[190:193], v[112:115]
	v_mfma_f32_16x16x32_bf16 v[104:107], v[174:177], v[198:201], v[104:107]
	v_mfma_f32_16x16x32_bf16 v[52:55], v[182:185], v[198:201], v[52:55]
	v_mfma_f32_16x16x32_bf16 v[96:99], v[174:177], v[206:209], v[96:99]
	v_mfma_f32_16x16x32_bf16 v[76:79], v[182:185], v[206:209], v[76:79]
	v_mfma_f32_16x16x32_bf16 v[88:91], v[174:177], v[214:217], v[88:91]
	v_mfma_f32_16x16x32_bf16 v[84:87], v[182:185], v[214:217], v[84:87]
	s_barrier
	s_add_u32 s98, s26, s16
	s_addc_u32 s99, s27, s17
	s_add_i32 s64, s55, s33
	s_mov_b32 m0, s64
	ds_read_b128 v[186:189], v155 offset:16384
	ds_read_b128 v[190:193], v155 offset:17408
	ds_read_b128 v[194:197], v155 offset:18432
	ds_read_b128 v[198:201], v155 offset:19456
	ds_read_b128 v[202:205], v155 offset:20480
	ds_read_b128 v[206:209], v155 offset:21504
	ds_read_b128 v[210:213], v155 offset:22528
	ds_read_b128 v[214:217], v155 offset:23552
	global_load_lds_dwordx4 v130, s[26:27]
	s_add_i32 m0, s64, 0x2000
	s_add_u32 s64, s26, 0x2b0000
	s_addc_u32 s65, s27, 0
	s_add_i32 s66, s56, s33
	global_load_lds_dwordx4 v134, s[26:27]
	s_mov_b32 m0, s66
	s_nop 0
	global_load_lds_dwordx4 v130, s[64:65]
	s_add_i32 m0, s66, 0x2000
	s_nop 0
	global_load_lds_dwordx4 v134, s[64:65]
	s_mov_b32 m0, s34
	s_nop 0
	global_load_lds_dwordx4 v128, s[30:31]
	s_mov_b32 m0, s35
	s_nop 0
	global_load_lds_dwordx4 v132, s[30:31]
	s_waitcnt vmcnt(8)
	s_waitcnt lgkmcnt(0)
	s_barrier
	v_mfma_f32_16x16x32_bf16 v[72:75], v[144:147], v[186:189], v[72:75]
	v_mfma_f32_16x16x32_bf16 v[68:71], v[162:165], v[186:189], v[68:71]
	v_mfma_f32_16x16x32_bf16 v[44:47], v[144:147], v[194:197], v[44:47]
	v_mfma_f32_16x16x32_bf16 v[40:43], v[162:165], v[194:197], v[40:43]
	v_mfma_f32_16x16x32_bf16 v[28:31], v[144:147], v[202:205], v[28:31]
	v_mfma_f32_16x16x32_bf16 v[24:27], v[162:165], v[202:205], v[24:27]
	v_mfma_f32_16x16x32_bf16 v[12:15], v[144:147], v[210:213], v[12:15]
	v_mfma_f32_16x16x32_bf16 v[8:11], v[162:165], v[210:213], v[8:11]
	v_mfma_f32_16x16x32_bf16 v[72:75], v[158:161], v[190:193], v[72:75]
	v_mfma_f32_16x16x32_bf16 v[68:71], v[166:169], v[190:193], v[68:71]
	v_mfma_f32_16x16x32_bf16 v[44:47], v[158:161], v[198:201], v[44:47]
	v_mfma_f32_16x16x32_bf16 v[40:43], v[166:169], v[198:201], v[40:43]
	v_mfma_f32_16x16x32_bf16 v[28:31], v[158:161], v[206:209], v[28:31]
	v_mfma_f32_16x16x32_bf16 v[24:27], v[166:169], v[206:209], v[24:27]
	v_mfma_f32_16x16x32_bf16 v[12:15], v[158:161], v[214:217], v[12:15]
	v_mfma_f32_16x16x32_bf16 v[8:11], v[166:169], v[214:217], v[8:11]
	v_mfma_f32_16x16x32_bf16 v[60:63], v[170:173], v[186:189], v[60:63]
	v_mfma_f32_16x16x32_bf16 v[56:59], v[178:181], v[186:189], v[56:59]
	v_mfma_f32_16x16x32_bf16 v[36:39], v[170:173], v[194:197], v[36:39]
	v_mfma_f32_16x16x32_bf16 v[32:35], v[178:181], v[194:197], v[32:35]
	v_mfma_f32_16x16x32_bf16 v[20:23], v[170:173], v[202:205], v[20:23]
	v_mfma_f32_16x16x32_bf16 v[16:19], v[178:181], v[202:205], v[16:19]
	v_mfma_f32_16x16x32_bf16 v[4:7], v[170:173], v[210:213], v[4:7]
	v_mfma_f32_16x16x32_bf16 v[0:3], v[178:181], v[210:213], v[0:3]
	v_mfma_f32_16x16x32_bf16 v[60:63], v[174:177], v[190:193], v[60:63]
	v_mfma_f32_16x16x32_bf16 v[56:59], v[182:185], v[190:193], v[56:59]
	v_mfma_f32_16x16x32_bf16 v[36:39], v[174:177], v[198:201], v[36:39]
	v_mfma_f32_16x16x32_bf16 v[32:35], v[182:185], v[198:201], v[32:35]
	v_mfma_f32_16x16x32_bf16 v[20:23], v[174:177], v[206:209], v[20:23]
	v_mfma_f32_16x16x32_bf16 v[16:19], v[182:185], v[206:209], v[16:19]
	v_mfma_f32_16x16x32_bf16 v[4:7], v[174:177], v[214:217], v[4:7]
	v_mfma_f32_16x16x32_bf16 v[0:3], v[182:185], v[214:217], v[0:3]
	s_barrier
; #define PG8_STAGE(bufoff, gbase, voff) do { _Pragma("unroll") for (int _i = 0; _i < 2; ++_i) \
;         __builtin_amdgcn_global_load_lds((const unsigned*)((const char*)(gbase) + (voff)[_i]), (PG8_LAS unsigned*)(lds + (bufoff) + ldsw + _i * 8192), 16, 0, 0); } while (0)
; #define PG8_LDA(dst, b, h) do { _Pragma("unroll") for (int m = 0; m < 4; ++m) _Pragma("unroll") for (int k = 0; k < 2; ++k) dst[m][k] = *(const PG8_LAS bf16x8*)(lds + PG8_SA(b, h) + aoff + m * 2048 + k * 1024); } while (0)
; #define PG8_LDB(dst, b, h) do { _Pragma("unroll") for (int n = 0; n < 2; ++n) _Pragma("unroll") for (int k = 0; k < 2; ++k) dst[n][k] = *(const PG8_LAS bf16x8*)(lds + PG8_SB(b, h) + boff + n * 2048 + k * 1024); } while (0)
; #define PG8_MMA(ai, bj, At, Bt) do { __builtin_amdgcn_s_setprio(1); _Pragma("unroll") for (int m = 0; m < 4; ++m) _Pragma("unroll") for (int n = 0; n < 2; ++n) _Pragma("unroll") for (int k = 0; k < 2; ++k) \
;         acc[ai][bj][m][n] = __builtin_amdgcn_mfma_f32_16x16x32_bf16(Bt[n][k], At[m][k], acc[ai][bj][m][n], 0, 0, 0); __builtin_amdgcn_s_setprio(0); } while (0)
; #define PG8_WAIT_V(n) asm volatile("s_waitcnt vmcnt(" #n ")" ::: "memory")
; #define PG8_WAIT_L(n) asm volatile("s_waitcnt lgkmcnt(" #n ")" ::: "memory")
; #define PG8_BAR __builtin_amdgcn_s_barrier()
; #define PG8_SCHED __builtin_amdgcn_sched_barrier(0)
; template <class Epi, class Sched, bool ALIGN_EPI = false, bool SP2 = false>
; __device__ __forceinline__ void gemm_phase(PG8_LAS unsigned char* lds, const Gemm g, const Sched& S, const Epi& E) {
;     ...
;         for (int t = 0; t < nt; t += 2) {
;     ...
;             PG8_LDB(B0, 1, 0); PG8_LDB(B1, 1, 1); PG8_SCHED; PG8_LDA(At, 1, 0); PG8_STAGE(PG8_SA(0, 1), a2 + hstepA, voffA);
;             PG8_WAIT_V(8); PG8_WAIT_L(0); PG8_BAR; PG8_MMA(0, 0, At, B0); PG8_MMA(0, 1, At, B1); PG8_BAR; PG8_SCHED;
;             PG8_LDA(At, 1, 1); PG8_STAGE(PG8_SB(1, 0), b3, voffB); PG8_STAGE(PG8_SB(1, 1), b3 + hstep, voffB); PG8_STAGE(PG8_SA(1, 0), a3, voffA);
;             PG8_WAIT_V(8); PG8_WAIT_L(0); PG8_BAR; PG8_MMA(1, 0, At, B0); PG8_MMA(1, 1, At, B1); PG8_BAR; PG8_SCHED;
	s_add_i32 s64, 0, 0x18000
	v_add_u32_e32 v157, s64, v151
	s_add_i32 s65, 0, 0x1c000
	ds_read_b128 v[144:147], v157
	ds_read_b128 v[158:161], v157 offset:1024
	ds_read_b128 v[162:165], v157 offset:2048
	ds_read_b128 v[166:169], v157 offset:3072
	v_add_u32_e32 v157, s65, v151
	ds_read_b128 v[170:173], v157
	ds_read_b128 v[174:177], v157 offset:1024
	ds_read_b128 v[178:181], v157 offset:2048
	ds_read_b128 v[182:185], v157 offset:3072
	s_add_u32 s30, s30, 0x4000
	s_addc_u32 s31, s31, 0
	s_mov_b32 m0, s38
	ds_read_b128 v[186:189], v155 offset:32768
	ds_read_b128 v[190:193], v155 offset:33792
	ds_read_b128 v[194:197], v155 offset:34816
	ds_read_b128 v[198:201], v155 offset:35840
	ds_read_b128 v[202:205], v155 offset:36864
	ds_read_b128 v[206:209], v155 offset:37888
	ds_read_b128 v[210:213], v155 offset:38912
	ds_read_b128 v[214:217], v155 offset:39936
	global_load_lds_dwordx4 v128, s[30:31]
	s_mov_b32 m0, s39
	s_nop 0
	global_load_lds_dwordx4 v132, s[30:31]
	s_waitcnt vmcnt(8)
	s_waitcnt lgkmcnt(0)
	s_barrier
	v_mfma_f32_16x16x32_bf16 v[124:127], v[144:147], v[186:189], v[124:127]
	v_mfma_f32_16x16x32_bf16 v[120:123], v[162:165], v[186:189], v[120:123]
	v_mfma_f32_16x16x32_bf16 v[108:111], v[144:147], v[194:197], v[108:111]
	v_mfma_f32_16x16x32_bf16 v[48:51], v[162:165], v[194:197], v[48:51]
	v_mfma_f32_16x16x32_bf16 v[100:103], v[144:147], v[202:205], v[100:103]
	v_mfma_f32_16x16x32_bf16 v[64:67], v[162:165], v[202:205], v[64:67]
	v_mfma_f32_16x16x32_bf16 v[92:95], v[144:147], v[210:213], v[92:95]
	v_mfma_f32_16x16x32_bf16 v[80:83], v[162:165], v[210:213], v[80:83]
	v_mfma_f32_16x16x32_bf16 v[124:127], v[158:161], v[190:193], v[124:127]
	v_mfma_f32_16x16x32_bf16 v[120:123], v[166:169], v[190:193], v[120:123]
	v_mfma_f32_16x16x32_bf16 v[108:111], v[158:161], v[198:201], v[108:111]
	v_mfma_f32_16x16x32_bf16 v[48:51], v[166:169], v[198:201], v[48:51]
	v_mfma_f32_16x16x32_bf16 v[100:103], v[158:161], v[206:209], v[100:103]
	v_mfma_f32_16x16x32_bf16 v[64:67], v[166:169], v[206:209], v[64:67]
	v_mfma_f32_16x16x32_bf16 v[92:95], v[158:161], v[214:217], v[92:95]
	v_mfma_f32_16x16x32_bf16 v[80:83], v[166:169], v[214:217], v[80:83]
	v_mfma_f32_16x16x32_bf16 v[116:119], v[170:173], v[186:189], v[116:119]
	v_mfma_f32_16x16x32_bf16 v[112:115], v[178:181], v[186:189], v[112:115]
	v_mfma_f32_16x16x32_bf16 v[104:107], v[170:173], v[194:197], v[104:107]
	v_mfma_f32_16x16x32_bf16 v[52:55], v[178:181], v[194:197], v[52:55]
	v_mfma_f32_16x16x32_bf16 v[96:99], v[170:173], v[202:205], v[96:99]
	v_mfma_f32_16x16x32_bf16 v[76:79], v[178:181], v[202:205], v[76:79]
	v_mfma_f32_16x16x32_bf16 v[88:91], v[170:173], v[210:213], v[88:91]
	v_mfma_f32_16x16x32_bf16 v[84:87], v[178:181], v[210:213], v[84:87]
	v_mfma_f32_16x16x32_bf16 v[116:119], v[174:177], v[190:193], v[116:119]
	v_mfma_f32_16x16x32_bf16 v[112:115], v[182:185], v[190:193], v[112:115]
	v_mfma_f32_16x16x32_bf16 v[104:107], v[174:177], v[198:201], v[104:107]
	v_mfma_f32_16x16x32_bf16 v[52:55], v[182:185], v[198:201], v[52:55]
	v_mfma_f32_16x16x32_bf16 v[96:99], v[174:177], v[206:209], v[96:99]
	v_mfma_f32_16x16x32_bf16 v[76:79], v[182:185], v[206:209], v[76:79]
	v_mfma_f32_16x16x32_bf16 v[88:91], v[174:177], v[214:217], v[88:91]
	v_mfma_f32_16x16x32_bf16 v[84:87], v[182:185], v[214:217], v[84:87]
	s_barrier
	s_add_i32 s30, s64, s33
	s_mov_b32 m0, s30
	ds_read_b128 v[186:189], v155 offset:49152
	ds_read_b128 v[190:193], v155 offset:50176
	ds_read_b128 v[194:197], v155 offset:51200
	ds_read_b128 v[198:201], v155 offset:52224
	ds_read_b128 v[202:205], v155 offset:53248
	ds_read_b128 v[206:209], v155 offset:54272
	ds_read_b128 v[210:213], v155 offset:55296
	ds_read_b128 v[214:217], v155 offset:56320
	global_load_lds_dwordx4 v130, s[98:99]
	s_add_i32 m0, s30, 0x2000
	s_add_u32 s26, s26, 0x2b0080
	s_addc_u32 s27, s27, 0
	s_add_i32 s30, s65, s33
	global_load_lds_dwordx4 v134, s[98:99]
	s_mov_b32 m0, s30
	s_nop 0
	global_load_lds_dwordx4 v130, s[26:27]
	s_add_i32 m0, s30, 0x2000
	s_nop 0
	global_load_lds_dwordx4 v134, s[26:27]
	s_mov_b32 m0, s41
	s_nop 0
	global_load_lds_dwordx4 v128, s[24:25]
	s_mov_b32 m0, s52
	s_nop 0
	global_load_lds_dwordx4 v132, s[24:25]
	s_waitcnt vmcnt(8)
	s_waitcnt lgkmcnt(0)
	s_barrier
	v_mfma_f32_16x16x32_bf16 v[72:75], v[144:147], v[186:189], v[72:75]
	v_mfma_f32_16x16x32_bf16 v[68:71], v[162:165], v[186:189], v[68:71]
	v_mfma_f32_16x16x32_bf16 v[44:47], v[144:147], v[194:197], v[44:47]
	v_mfma_f32_16x16x32_bf16 v[40:43], v[162:165], v[194:197], v[40:43]
	v_mfma_f32_16x16x32_bf16 v[28:31], v[144:147], v[202:205], v[28:31]
	v_mfma_f32_16x16x32_bf16 v[24:27], v[162:165], v[202:205], v[24:27]
	v_mfma_f32_16x16x32_bf16 v[12:15], v[144:147], v[210:213], v[12:15]
	v_mfma_f32_16x16x32_bf16 v[8:11], v[162:165], v[210:213], v[8:11]
	v_mfma_f32_16x16x32_bf16 v[72:75], v[158:161], v[190:193], v[72:75]
	v_mfma_f32_16x16x32_bf16 v[68:71], v[166:169], v[190:193], v[68:71]
	v_mfma_f32_16x16x32_bf16 v[44:47], v[158:161], v[198:201], v[44:47]
	v_mfma_f32_16x16x32_bf16 v[40:43], v[166:169], v[198:201], v[40:43]
	v_mfma_f32_16x16x32_bf16 v[28:31], v[158:161], v[206:209], v[28:31]
	v_mfma_f32_16x16x32_bf16 v[24:27], v[166:169], v[206:209], v[24:27]
	v_mfma_f32_16x16x32_bf16 v[12:15], v[158:161], v[214:217], v[12:15]
	v_mfma_f32_16x16x32_bf16 v[8:11], v[166:169], v[214:217], v[8:11]
	v_mfma_f32_16x16x32_bf16 v[60:63], v[170:173], v[186:189], v[60:63]
	v_mfma_f32_16x16x32_bf16 v[56:59], v[178:181], v[186:189], v[56:59]
	v_mfma_f32_16x16x32_bf16 v[36:39], v[170:173], v[194:197], v[36:39]
	v_mfma_f32_16x16x32_bf16 v[32:35], v[178:181], v[194:197], v[32:35]
	v_mfma_f32_16x16x32_bf16 v[20:23], v[170:173], v[202:205], v[20:23]
	v_mfma_f32_16x16x32_bf16 v[16:19], v[178:181], v[202:205], v[16:19]
	v_mfma_f32_16x16x32_bf16 v[4:7], v[170:173], v[210:213], v[4:7]
	v_mfma_f32_16x16x32_bf16 v[0:3], v[178:181], v[210:213], v[0:3]
	v_mfma_f32_16x16x32_bf16 v[60:63], v[174:177], v[190:193], v[60:63]
	v_mfma_f32_16x16x32_bf16 v[56:59], v[182:185], v[190:193], v[56:59]
	v_mfma_f32_16x16x32_bf16 v[36:39], v[174:177], v[198:201], v[36:39]
	v_mfma_f32_16x16x32_bf16 v[32:35], v[182:185], v[198:201], v[32:35]
	v_mfma_f32_16x16x32_bf16 v[20:23], v[174:177], v[206:209], v[20:23]
	v_mfma_f32_16x16x32_bf16 v[16:19], v[182:185], v[206:209], v[16:19]
	v_mfma_f32_16x16x32_bf16 v[4:7], v[174:177], v[214:217], v[4:7]
	v_mfma_f32_16x16x32_bf16 v[0:3], v[182:185], v[214:217], v[0:3]
	s_barrier
	s_add_i32 s63, s63, 2
	s_add_u32 s61, s61, 0x100
	s_addc_u32 s62, s62, 0
	s_add_u32 s22, s22, 0x10000
	s_addc_u32 s23, s23, 0
	s_cmpk_gt_u32 s63, 0xa9
	s_cbranch_scc0 .LBB0_1515
	s_and_b64 vcc, exec, s[18:19]
	s_cbranch_vccz .LBB0_1518
	s_barrier

; #define PG8_STAGE(bufoff, gbase, voff) do { _Pragma("unroll") for (int _i = 0; _i < 2; ++_i) \
;         __builtin_amdgcn_global_load_lds((const unsigned*)((const char*)(gbase) + (voff)[_i]), (PG8_LAS unsigned*)(lds + (bufoff) + ldsw + _i * 8192), 16, 0, 0); } while (0)
; #define PG8_LDA(dst, b, h) do { _Pragma("unroll") for (int m = 0; m < 4; ++m) _Pragma("unroll") for (int k = 0; k < 2; ++k) dst[m][k] = *(const PG8_LAS bf16x8*)(lds + PG8_SA(b, h) + aoff + m * 2048 + k * 1024); } while (0)
; #define PG8_LDB(dst, b, h) do { _Pragma("unroll") for (int n = 0; n < 2; ++n) _Pragma("unroll") for (int k = 0; k < 2; ++k) dst[n][k] = *(const PG8_LAS bf16x8*)(lds + PG8_SB(b, h) + boff + n * 2048 + k * 1024); } while (0)
; #define PG8_MMA(ai, bj, At, Bt) do { __builtin_amdgcn_s_setprio(1); _Pragma("unroll") for (int m = 0; m < 4; ++m) _Pragma("unroll") for (int n = 0; n < 2; ++n) _Pragma("unroll") for (int k = 0; k < 2; ++k) \
;         acc[ai][bj][m][n] = __builtin_amdgcn_mfma_f32_16x16x32_bf16(Bt[n][k], At[m][k], acc[ai][bj][m][n], 0, 0, 0); __builtin_amdgcn_s_setprio(0); } while (0)
; #define PG8_WAIT_V(n) asm volatile("s_waitcnt vmcnt(" #n ")" ::: "memory")
; #define PG8_WAIT_L(n) asm volatile("s_waitcnt lgkmcnt(" #n ")" ::: "memory")
; #define PG8_BAR __builtin_amdgcn_s_barrier()
; #define PG8_SCHED __builtin_amdgcn_sched_barrier(0)
; template <class Epi, class Sched, bool ALIGN_EPI = false, bool SP2 = false>
; __device__ __forceinline__ void gemm_phase(PG8_LAS unsigned char* lds, const Gemm g, const Sched& S, const Epi& E) {
;     ...
;             PG8_LDB(B0, 0, 0); PG8_LDB(B1, 0, 1); PG8_SCHED; PG8_LDA(At, 0, 0); PG8_STAGE(PG8_SA(1, 1), a1 + hstepA, voffA);
;             PG8_WAIT_V(8); PG8_WAIT_L(0); PG8_BAR; PG8_MMA(0, 0, At, B0); PG8_MMA(0, 1, At, B1); PG8_BAR; PG8_SCHED;
;             PG8_LDA(At, 0, 1); PG8_STAGE(PG8_SB(0, 0), b2, voffB); PG8_STAGE(PG8_SB(0, 1), b2 + hstep, voffB); PG8_STAGE(PG8_SA(0, 0), a2, voffA);
;             PG8_WAIT_V(8); PG8_WAIT_L(0); PG8_BAR; PG8_MMA(1, 0, At, B0); PG8_MMA(1, 1, At, B1); PG8_BAR; PG8_SCHED;
.LBB0_1631:
	ds_read_b128 v[144:147], v155
	ds_read_b128 v[148:151], v155 offset:1024
	ds_read_b128 v[160:163], v155 offset:2048
	ds_read_b128 v[164:167], v155 offset:3072
	ds_read_b128 v[168:171], v156
	ds_read_b128 v[172:175], v156 offset:1024
	ds_read_b128 v[176:179], v156 offset:2048
	ds_read_b128 v[180:183], v156 offset:3072
	s_add_u32 s65, s84, 0xfff00080
	s_addc_u32 s66, s85, -1
	s_cmp_eq_u32 s64, 60
	s_cselect_b32 s89, s25, s66
	s_cselect_b32 s88, s35, s65
	s_cselect_b32 s87, s23, s63
	s_cselect_b32 s86, s61, s62
	s_add_i32 m0, s29, 0xc000
	ds_read_b128 v[184:187], v157
	ds_read_b128 v[188:191], v157 offset:1024
	ds_read_b128 v[192:195], v157 offset:2048
	ds_read_b128 v[196:199], v157 offset:3072
	ds_read_b128 v[200:203], v157 offset:4096
	ds_read_b128 v[204:207], v157 offset:5120
	ds_read_b128 v[208:211], v157 offset:6144
	ds_read_b128 v[212:215], v157 offset:7168
	global_load_lds_dwordx4 v136, s[84:85]
	s_add_i32 m0, s29, 0xe000
	s_nop 0
	global_load_lds_dwordx4 v138, s[84:85]
	s_waitcnt vmcnt(8)
	s_waitcnt lgkmcnt(0)
	s_barrier
	v_mfma_f32_16x16x32_bf16 v[124:127], v[144:147], v[184:187], v[124:127]
	v_mfma_f32_16x16x32_bf16 v[120:123], v[160:163], v[184:187], v[120:123]
	v_mfma_f32_16x16x32_bf16 v[108:111], v[144:147], v[192:195], v[108:111]
	v_mfma_f32_16x16x32_bf16 v[32:35], v[160:163], v[192:195], v[32:35]
	v_mfma_f32_16x16x32_bf16 v[100:103], v[144:147], v[200:203], v[100:103]
	v_mfma_f32_16x16x32_bf16 v[52:55], v[160:163], v[200:203], v[52:55]
	v_mfma_f32_16x16x32_bf16 v[92:95], v[144:147], v[208:211], v[92:95]
	v_mfma_f32_16x16x32_bf16 v[72:75], v[160:163], v[208:211], v[72:75]
	v_mfma_f32_16x16x32_bf16 v[124:127], v[148:151], v[188:191], v[124:127]
	v_mfma_f32_16x16x32_bf16 v[120:123], v[164:167], v[188:191], v[120:123]
	v_mfma_f32_16x16x32_bf16 v[108:111], v[148:151], v[196:199], v[108:111]
	v_mfma_f32_16x16x32_bf16 v[32:35], v[164:167], v[196:199], v[32:35]
	v_mfma_f32_16x16x32_bf16 v[100:103], v[148:151], v[204:207], v[100:103]
	v_mfma_f32_16x16x32_bf16 v[52:55], v[164:167], v[204:207], v[52:55]
	v_mfma_f32_16x16x32_bf16 v[92:95], v[148:151], v[212:215], v[92:95]
	v_mfma_f32_16x16x32_bf16 v[72:75], v[164:167], v[212:215], v[72:75]
	v_mfma_f32_16x16x32_bf16 v[116:119], v[168:171], v[184:187], v[116:119]
	v_mfma_f32_16x16x32_bf16 v[112:115], v[176:179], v[184:187], v[112:115]
	v_mfma_f32_16x16x32_bf16 v[104:107], v[168:171], v[192:195], v[104:107]
	v_mfma_f32_16x16x32_bf16 v[44:47], v[176:179], v[192:195], v[44:47]
	v_mfma_f32_16x16x32_bf16 v[96:99], v[168:171], v[200:203], v[96:99]
	v_mfma_f32_16x16x32_bf16 v[68:71], v[176:179], v[200:203], v[68:71]
	v_mfma_f32_16x16x32_bf16 v[88:91], v[168:171], v[208:211], v[88:91]
	v_mfma_f32_16x16x32_bf16 v[84:87], v[176:179], v[208:211], v[84:87]
	v_mfma_f32_16x16x32_bf16 v[116:119], v[172:175], v[188:191], v[116:119]
	v_mfma_f32_16x16x32_bf16 v[112:115], v[180:183], v[188:191], v[112:115]
	v_mfma_f32_16x16x32_bf16 v[104:107], v[172:175], v[196:199], v[104:107]
	v_mfma_f32_16x16x32_bf16 v[44:47], v[180:183], v[196:199], v[44:47]
	v_mfma_f32_16x16x32_bf16 v[96:99], v[172:175], v[204:207], v[96:99]
	v_mfma_f32_16x16x32_bf16 v[68:71], v[180:183], v[204:207], v[68:71]
	v_mfma_f32_16x16x32_bf16 v[88:91], v[172:175], v[212:215], v[88:91]
	v_mfma_f32_16x16x32_bf16 v[84:87], v[180:183], v[212:215], v[84:87]
	s_barrier
	s_add_u32 s98, s86, s18
	s_addc_u32 s99, s87, s19
	s_add_u32 s100, s88, s18
	s_addc_u32 s101, s89, s19
	s_add_i32 s65, s58, s3
	s_mov_b32 m0, s65
	ds_read_b128 v[184:187], v157 offset:16384
	ds_read_b128 v[188:191], v157 offset:17408
	ds_read_b128 v[192:195], v157 offset:18432
	ds_read_b128 v[196:199], v157 offset:19456
	ds_read_b128 v[200:203], v157 offset:20480
	ds_read_b128 v[204:207], v157 offset:21504
	ds_read_b128 v[208:211], v157 offset:22528
	ds_read_b128 v[212:215], v157 offset:23552
	global_load_lds_dwordx4 v130, s[86:87]
	s_add_i32 m0, s65, 0x2000
	s_add_u32 s66, s86, 0x100000
	s_addc_u32 s67, s87, 0
	s_add_i32 s65, s59, s3
	global_load_lds_dwordx4 v134, s[86:87]
	s_mov_b32 m0, s65
	s_nop 0
	global_load_lds_dwordx4 v130, s[66:67]
	s_add_i32 m0, s65, 0x2000
	s_nop 0
	global_load_lds_dwordx4 v134, s[66:67]
	s_mov_b32 m0, s29
	s_nop 0
	global_load_lds_dwordx4 v128, s[88:89]
	s_mov_b32 m0, s33
	s_nop 0
	global_load_lds_dwordx4 v132, s[88:89]
	s_waitcnt vmcnt(8)
	s_waitcnt lgkmcnt(0)
	s_barrier
	v_mfma_f32_16x16x32_bf16 v[80:83], v[144:147], v[184:187], v[80:83]
	v_mfma_f32_16x16x32_bf16 v[76:79], v[160:163], v[184:187], v[76:79]
	v_mfma_f32_16x16x32_bf16 v[56:59], v[144:147], v[192:195], v[56:59]
	v_mfma_f32_16x16x32_bf16 v[48:51], v[160:163], v[192:195], v[48:51]
	v_mfma_f32_16x16x32_bf16 v[28:31], v[144:147], v[200:203], v[28:31]
	v_mfma_f32_16x16x32_bf16 v[24:27], v[160:163], v[200:203], v[24:27]
	v_mfma_f32_16x16x32_bf16 v[12:15], v[144:147], v[208:211], v[12:15]
	v_mfma_f32_16x16x32_bf16 v[8:11], v[160:163], v[208:211], v[8:11]
	v_mfma_f32_16x16x32_bf16 v[80:83], v[148:151], v[188:191], v[80:83]
	v_mfma_f32_16x16x32_bf16 v[76:79], v[164:167], v[188:191], v[76:79]
	v_mfma_f32_16x16x32_bf16 v[56:59], v[148:151], v[196:199], v[56:59]
	v_mfma_f32_16x16x32_bf16 v[48:51], v[164:167], v[196:199], v[48:51]
	v_mfma_f32_16x16x32_bf16 v[28:31], v[148:151], v[204:207], v[28:31]
	v_mfma_f32_16x16x32_bf16 v[24:27], v[164:167], v[204:207], v[24:27]
	v_mfma_f32_16x16x32_bf16 v[12:15], v[148:151], v[212:215], v[12:15]
	v_mfma_f32_16x16x32_bf16 v[8:11], v[164:167], v[212:215], v[8:11]
	v_mfma_f32_16x16x32_bf16 v[64:67], v[168:171], v[184:187], v[64:67]
	v_mfma_f32_16x16x32_bf16 v[60:63], v[176:179], v[184:187], v[60:63]
	v_mfma_f32_16x16x32_bf16 v[40:43], v[168:171], v[192:195], v[40:43]
	v_mfma_f32_16x16x32_bf16 v[36:39], v[176:179], v[192:195], v[36:39]
	v_mfma_f32_16x16x32_bf16 v[20:23], v[168:171], v[200:203], v[20:23]
	v_mfma_f32_16x16x32_bf16 v[16:19], v[176:179], v[200:203], v[16:19]
	v_mfma_f32_16x16x32_bf16 v[4:7], v[168:171], v[208:211], v[4:7]
	v_mfma_f32_16x16x32_bf16 v[0:3], v[176:179], v[208:211], v[0:3]
	v_mfma_f32_16x16x32_bf16 v[64:67], v[172:175], v[188:191], v[64:67]
	v_mfma_f32_16x16x32_bf16 v[60:63], v[180:183], v[188:191], v[60:63]
	v_mfma_f32_16x16x32_bf16 v[40:43], v[172:175], v[196:199], v[40:43]
	v_mfma_f32_16x16x32_bf16 v[36:39], v[180:183], v[196:199], v[36:39]
	v_mfma_f32_16x16x32_bf16 v[20:23], v[172:175], v[204:207], v[20:23]
	v_mfma_f32_16x16x32_bf16 v[16:19], v[180:183], v[204:207], v[16:19]
	v_mfma_f32_16x16x32_bf16 v[4:7], v[172:175], v[212:215], v[4:7]
	v_mfma_f32_16x16x32_bf16 v[0:3], v[180:183], v[212:215], v[0:3]
	s_barrier
; #define PG8_STAGE(bufoff, gbase, voff) do { _Pragma("unroll") for (int _i = 0; _i < 2; ++_i) \
;         __builtin_amdgcn_global_load_lds((const unsigned*)((const char*)(gbase) + (voff)[_i]), (PG8_LAS unsigned*)(lds + (bufoff) + ldsw + _i * 8192), 16, 0, 0); } while (0)
; #define PG8_LDA(dst, b, h) do { _Pragma("unroll") for (int m = 0; m < 4; ++m) _Pragma("unroll") for (int k = 0; k < 2; ++k) dst[m][k] = *(const PG8_LAS bf16x8*)(lds + PG8_SA(b, h) + aoff + m * 2048 + k * 1024); } while (0)
; #define PG8_LDB(dst, b, h) do { _Pragma("unroll") for (int n = 0; n < 2; ++n) _Pragma("unroll") for (int k = 0; k < 2; ++k) dst[n][k] = *(const PG8_LAS bf16x8*)(lds + PG8_SB(b, h) + boff + n * 2048 + k * 1024); } while (0)
; #define PG8_MMA(ai, bj, At, Bt) do { __builtin_amdgcn_s_setprio(1); _Pragma("unroll") for (int m = 0; m < 4; ++m) _Pragma("unroll") for (int n = 0; n < 2; ++n) _Pragma("unroll") for (int k = 0; k < 2; ++k) \
;         acc[ai][bj][m][n] = __builtin_amdgcn_mfma_f32_16x16x32_bf16(Bt[n][k], At[m][k], acc[ai][bj][m][n], 0, 0, 0); __builtin_amdgcn_s_setprio(0); } while (0)
; #define PG8_WAIT_V(n) asm volatile("s_waitcnt vmcnt(" #n ")" ::: "memory")
; #define PG8_WAIT_L(n) asm volatile("s_waitcnt lgkmcnt(" #n ")" ::: "memory")
; #define PG8_BAR __builtin_amdgcn_s_barrier()
; #define PG8_SCHED __builtin_amdgcn_sched_barrier(0)
; template <class Epi, class Sched, bool ALIGN_EPI = false, bool SP2 = false>
; __device__ __forceinline__ void gemm_phase(PG8_LAS unsigned char* lds, const Gemm g, const Sched& S, const Epi& E) {
;     ...
;             PG8_LDB(B0, 1, 0); PG8_LDB(B1, 1, 1); PG8_SCHED; PG8_LDA(At, 1, 0); PG8_STAGE(PG8_SA(0, 1), a2 + hstepA, voffA);
;             PG8_WAIT_V(8); PG8_WAIT_L(0); PG8_BAR; PG8_MMA(0, 0, At, B0); PG8_MMA(0, 1, At, B1); PG8_BAR; PG8_SCHED;
;             PG8_LDA(At, 1, 1); PG8_STAGE(PG8_SB(1, 0), b3, voffB); PG8_STAGE(PG8_SB(1, 1), b3 + hstep, voffB); PG8_STAGE(PG8_SA(1, 0), a3, voffA);
;             PG8_WAIT_V(8); PG8_WAIT_L(0); PG8_BAR; PG8_MMA(1, 0, At, B0); PG8_MMA(1, 1, At, B1); PG8_BAR; PG8_SCHED;
	s_add_i32 s65, 0, 0x18000
	s_add_i32 s68, 0, 0x1c000
	v_add_u32_e32 v164, s65, v153
	v_add_u32_e32 v180, s68, v153
	ds_read_b128 v[144:147], v164
	ds_read_b128 v[148:151], v164 offset:1024
	ds_read_b128 v[160:163], v164 offset:2048
	ds_read_b128 v[164:167], v164 offset:3072
	ds_read_b128 v[168:171], v180
	ds_read_b128 v[172:175], v180 offset:1024
	ds_read_b128 v[176:179], v180 offset:2048
	ds_read_b128 v[180:183], v180 offset:3072
	s_add_u32 s66, s88, 0x100000
	s_addc_u32 s67, s89, 0
	s_mov_b32 m0, s41
	ds_read_b128 v[184:187], v157 offset:32768
	ds_read_b128 v[188:191], v157 offset:33792
	ds_read_b128 v[192:195], v157 offset:34816
	ds_read_b128 v[196:199], v157 offset:35840
	ds_read_b128 v[200:203], v157 offset:36864
	ds_read_b128 v[204:207], v157 offset:37888
	ds_read_b128 v[208:211], v157 offset:38912
	ds_read_b128 v[212:215], v157 offset:39936
	global_load_lds_dwordx4 v128, s[66:67]
	s_mov_b32 m0, s52
	s_nop 0
	global_load_lds_dwordx4 v132, s[66:67]
	s_waitcnt vmcnt(8)
	s_waitcnt lgkmcnt(0)
	s_barrier
	v_mfma_f32_16x16x32_bf16 v[124:127], v[144:147], v[184:187], v[124:127]
	v_mfma_f32_16x16x32_bf16 v[120:123], v[160:163], v[184:187], v[120:123]
	v_mfma_f32_16x16x32_bf16 v[108:111], v[144:147], v[192:195], v[108:111]
	v_mfma_f32_16x16x32_bf16 v[32:35], v[160:163], v[192:195], v[32:35]
	v_mfma_f32_16x16x32_bf16 v[100:103], v[144:147], v[200:203], v[100:103]
	v_mfma_f32_16x16x32_bf16 v[52:55], v[160:163], v[200:203], v[52:55]
	v_mfma_f32_16x16x32_bf16 v[92:95], v[144:147], v[208:211], v[92:95]
	v_mfma_f32_16x16x32_bf16 v[72:75], v[160:163], v[208:211], v[72:75]
	v_mfma_f32_16x16x32_bf16 v[124:127], v[148:151], v[188:191], v[124:127]
	v_mfma_f32_16x16x32_bf16 v[120:123], v[164:167], v[188:191], v[120:123]
	v_mfma_f32_16x16x32_bf16 v[108:111], v[148:151], v[196:199], v[108:111]
	v_mfma_f32_16x16x32_bf16 v[32:35], v[164:167], v[196:199], v[32:35]
	v_mfma_f32_16x16x32_bf16 v[100:103], v[148:151], v[204:207], v[100:103]
	v_mfma_f32_16x16x32_bf16 v[52:55], v[164:167], v[204:207], v[52:55]
	v_mfma_f32_16x16x32_bf16 v[92:95], v[148:151], v[212:215], v[92:95]
	v_mfma_f32_16x16x32_bf16 v[72:75], v[164:167], v[212:215], v[72:75]
	v_mfma_f32_16x16x32_bf16 v[116:119], v[168:171], v[184:187], v[116:119]
	v_mfma_f32_16x16x32_bf16 v[112:115], v[176:179], v[184:187], v[112:115]
	v_mfma_f32_16x16x32_bf16 v[104:107], v[168:171], v[192:195], v[104:107]
	v_mfma_f32_16x16x32_bf16 v[44:47], v[176:179], v[192:195], v[44:47]
	v_mfma_f32_16x16x32_bf16 v[96:99], v[168:171], v[200:203], v[96:99]
	v_mfma_f32_16x16x32_bf16 v[68:71], v[176:179], v[200:203], v[68:71]
	v_mfma_f32_16x16x32_bf16 v[88:91], v[168:171], v[208:211], v[88:91]
	v_mfma_f32_16x16x32_bf16 v[84:87], v[176:179], v[208:211], v[84:87]
	v_mfma_f32_16x16x32_bf16 v[116:119], v[172:175], v[188:191], v[116:119]
	v_mfma_f32_16x16x32_bf16 v[112:115], v[180:183], v[188:191], v[112:115]
	v_mfma_f32_16x16x32_bf16 v[104:107], v[172:175], v[196:199], v[104:107]
	v_mfma_f32_16x16x32_bf16 v[44:47], v[180:183], v[196:199], v[44:47]
	v_mfma_f32_16x16x32_bf16 v[96:99], v[172:175], v[204:207], v[96:99]
	v_mfma_f32_16x16x32_bf16 v[68:71], v[180:183], v[204:207], v[68:71]
	v_mfma_f32_16x16x32_bf16 v[88:91], v[172:175], v[212:215], v[88:91]
	v_mfma_f32_16x16x32_bf16 v[84:87], v[180:183], v[212:215], v[84:87]
	s_barrier
	s_add_i32 s65, s65, s3
	s_mov_b32 m0, s65
	ds_read_b128 v[184:187], v157 offset:49152
	ds_read_b128 v[188:191], v157 offset:50176
	ds_read_b128 v[192:195], v157 offset:51200
	ds_read_b128 v[196:199], v157 offset:52224
	ds_read_b128 v[200:203], v157 offset:53248
	ds_read_b128 v[204:207], v157 offset:54272
	ds_read_b128 v[208:211], v157 offset:55296
	ds_read_b128 v[212:215], v157 offset:56320
	global_load_lds_dwordx4 v130, s[98:99]
	s_add_i32 m0, s65, 0x2000
	s_add_u32 s66, s86, 0x100080
	s_addc_u32 s67, s87, 0
	s_add_i32 s65, s68, s3
	global_load_lds_dwordx4 v134, s[98:99]
	s_mov_b32 m0, s65
	s_nop 0
	global_load_lds_dwordx4 v130, s[66:67]
	s_add_i32 m0, s65, 0x2000
	s_nop 0
	global_load_lds_dwordx4 v134, s[66:67]
	s_mov_b32 m0, s54
	s_nop 0
	global_load_lds_dwordx4 v128, s[100:101]
	s_mov_b32 m0, s55
	s_nop 0
	global_load_lds_dwordx4 v132, s[100:101]
	s_waitcnt vmcnt(8)
	s_waitcnt lgkmcnt(0)
	s_barrier
	v_mfma_f32_16x16x32_bf16 v[80:83], v[144:147], v[184:187], v[80:83]
	v_mfma_f32_16x16x32_bf16 v[76:79], v[160:163], v[184:187], v[76:79]
	v_mfma_f32_16x16x32_bf16 v[56:59], v[144:147], v[192:195], v[56:59]
	v_mfma_f32_16x16x32_bf16 v[48:51], v[160:163], v[192:195], v[48:51]
	v_mfma_f32_16x16x32_bf16 v[28:31], v[144:147], v[200:203], v[28:31]
	v_mfma_f32_16x16x32_bf16 v[24:27], v[160:163], v[200:203], v[24:27]
	v_mfma_f32_16x16x32_bf16 v[12:15], v[144:147], v[208:211], v[12:15]
	v_mfma_f32_16x16x32_bf16 v[8:11], v[160:163], v[208:211], v[8:11]
	v_mfma_f32_16x16x32_bf16 v[80:83], v[148:151], v[188:191], v[80:83]
	v_mfma_f32_16x16x32_bf16 v[76:79], v[164:167], v[188:191], v[76:79]
	v_mfma_f32_16x16x32_bf16 v[56:59], v[148:151], v[196:199], v[56:59]
	v_mfma_f32_16x16x32_bf16 v[48:51], v[164:167], v[196:199], v[48:51]
	v_mfma_f32_16x16x32_bf16 v[28:31], v[148:151], v[204:207], v[28:31]
	v_mfma_f32_16x16x32_bf16 v[24:27], v[164:167], v[204:207], v[24:27]
	v_mfma_f32_16x16x32_bf16 v[12:15], v[148:151], v[212:215], v[12:15]
	v_mfma_f32_16x16x32_bf16 v[8:11], v[164:167], v[212:215], v[8:11]
	v_mfma_f32_16x16x32_bf16 v[64:67], v[168:171], v[184:187], v[64:67]
	v_mfma_f32_16x16x32_bf16 v[60:63], v[176:179], v[184:187], v[60:63]
	v_mfma_f32_16x16x32_bf16 v[40:43], v[168:171], v[192:195], v[40:43]
	v_mfma_f32_16x16x32_bf16 v[36:39], v[176:179], v[192:195], v[36:39]
	v_mfma_f32_16x16x32_bf16 v[20:23], v[168:171], v[200:203], v[20:23]
	v_mfma_f32_16x16x32_bf16 v[16:19], v[176:179], v[200:203], v[16:19]
	v_mfma_f32_16x16x32_bf16 v[4:7], v[168:171], v[208:211], v[4:7]
	v_mfma_f32_16x16x32_bf16 v[0:3], v[176:179], v[208:211], v[0:3]
	v_mfma_f32_16x16x32_bf16 v[64:67], v[172:175], v[188:191], v[64:67]
	v_mfma_f32_16x16x32_bf16 v[60:63], v[180:183], v[188:191], v[60:63]
	v_mfma_f32_16x16x32_bf16 v[40:43], v[172:175], v[196:199], v[40:43]
	v_mfma_f32_16x16x32_bf16 v[36:39], v[180:183], v[196:199], v[36:39]
	v_mfma_f32_16x16x32_bf16 v[20:23], v[172:175], v[204:207], v[20:23]
	v_mfma_f32_16x16x32_bf16 v[16:19], v[180:183], v[204:207], v[16:19]
	v_mfma_f32_16x16x32_bf16 v[4:7], v[172:175], v[212:215], v[4:7]
	v_mfma_f32_16x16x32_bf16 v[0:3], v[180:183], v[212:215], v[0:3]
	s_barrier
	s_add_i32 s64, s64, 2
	s_add_u32 s84, s84, 0x100
	s_addc_u32 s85, s85, 0
	s_add_u32 s62, s62, 0x100
	s_addc_u32 s63, s63, 0
	s_cmp_gt_u32 s64, 61
	s_cbranch_scc0 .LBB0_1631
	s_and_b64 vcc, exec, s[20:21]
	s_cbranch_vccz .LBB0_1634
	s_barrier

; #define PG8_STAGE(bufoff, gbase, voff) do { _Pragma("unroll") for (int _i = 0; _i < 2; ++_i) \
;         __builtin_amdgcn_global_load_lds((const unsigned*)((const char*)(gbase) + (voff)[_i]), (PG8_LAS unsigned*)(lds + (bufoff) + ldsw + _i * 8192), 16, 0, 0); } while (0)
; #define PG8_LDA(dst, b, h) do { _Pragma("unroll") for (int m = 0; m < 4; ++m) _Pragma("unroll") for (int k = 0; k < 2; ++k) dst[m][k] = *(const PG8_LAS bf16x8*)(lds + PG8_SA(b, h) + aoff + m * 2048 + k * 1024); } while (0)
; #define PG8_LDB(dst, b, h) do { _Pragma("unroll") for (int n = 0; n < 2; ++n) _Pragma("unroll") for (int k = 0; k < 2; ++k) dst[n][k] = *(const PG8_LAS bf16x8*)(lds + PG8_SB(b, h) + boff + n * 2048 + k * 1024); } while (0)
; #define PG8_MMA(ai, bj, At, Bt) do { __builtin_amdgcn_s_setprio(1); _Pragma("unroll") for (int m = 0; m < 4; ++m) _Pragma("unroll") for (int n = 0; n < 2; ++n) _Pragma("unroll") for (int k = 0; k < 2; ++k) \
;         acc[ai][bj][m][n] = __builtin_amdgcn_mfma_f32_16x16x32_bf16(Bt[n][k], At[m][k], acc[ai][bj][m][n], 0, 0, 0); __builtin_amdgcn_s_setprio(0); } while (0)
; #define PG8_WAIT_V(n) asm volatile("s_waitcnt vmcnt(" #n ")" ::: "memory")
; #define PG8_WAIT_L(n) asm volatile("s_waitcnt lgkmcnt(" #n ")" ::: "memory")
; #define PG8_BAR __builtin_amdgcn_s_barrier()
; #define PG8_SCHED __builtin_amdgcn_sched_barrier(0)
; template <class Epi, class Sched, bool ALIGN_EPI = false, bool SP2 = false>
; __device__ __forceinline__ void gemm_phase(PG8_LAS unsigned char* lds, const Gemm g, const Sched& S, const Epi& E) {
;     ...
;             PG8_LDB(B0, 0, 0); PG8_LDB(B1, 0, 1); PG8_SCHED; PG8_LDA(At, 0, 0); PG8_STAGE(PG8_SA(1, 1), a1 + hstepA, voffA);
;             PG8_WAIT_V(8); PG8_WAIT_L(0); PG8_BAR; PG8_MMA(0, 0, At, B0); PG8_MMA(0, 1, At, B1); PG8_BAR; PG8_SCHED;
;             PG8_LDA(At, 0, 1); PG8_STAGE(PG8_SB(0, 0), b2, voffB); PG8_STAGE(PG8_SB(0, 1), b2 + hstep, voffB); PG8_STAGE(PG8_SA(0, 0), a2, voffA);
;             PG8_WAIT_V(8); PG8_WAIT_L(0); PG8_BAR; PG8_MMA(1, 0, At, B0); PG8_MMA(1, 1, At, B1); PG8_BAR; PG8_SCHED;
.LBB0_1741:
	ds_read_b128 v[150:153], v158
	ds_read_b128 v[162:165], v158 offset:1024
	ds_read_b128 v[166:169], v158 offset:2048
	ds_read_b128 v[170:173], v158 offset:3072
	ds_read_b128 v[174:177], v159
	ds_read_b128 v[178:181], v159 offset:1024
	ds_read_b128 v[182:185], v159 offset:2048
	ds_read_b128 v[186:189], v159 offset:3072
	s_add_u32 s40, s34, 0xfff00080
	s_addc_u32 s41, s35, -1
	s_cmp_eq_u32 s67, 60
	s_cselect_b32 s85, s21, s41
	s_cselect_b32 s84, s27, s40
	s_cselect_b32 s41, s19, s66
	s_cselect_b32 s40, s31, s65
	s_add_i32 m0, s53, 0xc000
	ds_read_b128 v[190:193], v160
	ds_read_b128 v[194:197], v160 offset:1024
	ds_read_b128 v[198:201], v160 offset:2048
	ds_read_b128 v[202:205], v160 offset:3072
	ds_read_b128 v[206:209], v160 offset:4096
	ds_read_b128 v[210:213], v160 offset:5120
	ds_read_b128 v[214:217], v160 offset:6144
	ds_read_b128 v[218:221], v160 offset:7168
	global_load_lds_dwordx4 v140, s[34:35]
	s_add_i32 m0, s53, 0xe000
	s_nop 0
	global_load_lds_dwordx4 v142, s[34:35]
	s_waitcnt vmcnt(8)
	s_waitcnt lgkmcnt(0)
	s_barrier
	v_mfma_f32_16x16x32_bf16 v[124:127], v[150:153], v[190:193], v[124:127]
	v_mfma_f32_16x16x32_bf16 v[120:123], v[166:169], v[190:193], v[120:123]
	v_mfma_f32_16x16x32_bf16 v[108:111], v[150:153], v[198:201], v[108:111]
	v_mfma_f32_16x16x32_bf16 v[104:107], v[166:169], v[198:201], v[104:107]
	v_mfma_f32_16x16x32_bf16 v[92:95], v[150:153], v[206:209], v[92:95]
	v_mfma_f32_16x16x32_bf16 v[88:91], v[166:169], v[206:209], v[88:91]
	v_mfma_f32_16x16x32_bf16 v[76:79], v[150:153], v[214:217], v[76:79]
	v_mfma_f32_16x16x32_bf16 v[72:75], v[166:169], v[214:217], v[72:75]
	v_mfma_f32_16x16x32_bf16 v[124:127], v[162:165], v[194:197], v[124:127]
	v_mfma_f32_16x16x32_bf16 v[120:123], v[170:173], v[194:197], v[120:123]
	v_mfma_f32_16x16x32_bf16 v[108:111], v[162:165], v[202:205], v[108:111]
	v_mfma_f32_16x16x32_bf16 v[104:107], v[170:173], v[202:205], v[104:107]
	v_mfma_f32_16x16x32_bf16 v[92:95], v[162:165], v[210:213], v[92:95]
	v_mfma_f32_16x16x32_bf16 v[88:91], v[170:173], v[210:213], v[88:91]
	v_mfma_f32_16x16x32_bf16 v[76:79], v[162:165], v[218:221], v[76:79]
	v_mfma_f32_16x16x32_bf16 v[72:75], v[170:173], v[218:221], v[72:75]
	v_mfma_f32_16x16x32_bf16 v[116:119], v[174:177], v[190:193], v[116:119]
	v_mfma_f32_16x16x32_bf16 v[112:115], v[182:185], v[190:193], v[112:115]
	v_mfma_f32_16x16x32_bf16 v[100:103], v[174:177], v[198:201], v[100:103]
	v_mfma_f32_16x16x32_bf16 v[96:99], v[182:185], v[198:201], v[96:99]
	v_mfma_f32_16x16x32_bf16 v[84:87], v[174:177], v[206:209], v[84:87]
	v_mfma_f32_16x16x32_bf16 v[80:83], v[182:185], v[206:209], v[80:83]
	v_mfma_f32_16x16x32_bf16 v[68:71], v[174:177], v[214:217], v[68:71]
	v_mfma_f32_16x16x32_bf16 v[64:67], v[182:185], v[214:217], v[64:67]
	v_mfma_f32_16x16x32_bf16 v[116:119], v[178:181], v[194:197], v[116:119]
	v_mfma_f32_16x16x32_bf16 v[112:115], v[186:189], v[194:197], v[112:115]
	v_mfma_f32_16x16x32_bf16 v[100:103], v[178:181], v[202:205], v[100:103]
	v_mfma_f32_16x16x32_bf16 v[96:99], v[186:189], v[202:205], v[96:99]
	v_mfma_f32_16x16x32_bf16 v[84:87], v[178:181], v[210:213], v[84:87]
	v_mfma_f32_16x16x32_bf16 v[80:83], v[186:189], v[210:213], v[80:83]
	v_mfma_f32_16x16x32_bf16 v[68:71], v[178:181], v[218:221], v[68:71]
	v_mfma_f32_16x16x32_bf16 v[64:67], v[186:189], v[218:221], v[64:67]
	s_barrier
	s_add_u32 s98, s40, s12
	s_addc_u32 s99, s41, s13
	s_add_u32 s100, s84, s12
	s_addc_u32 s101, s85, s13
	s_add_i32 s68, s62, s33
	s_mov_b32 m0, s68
	ds_read_b128 v[190:193], v160 offset:16384
	ds_read_b128 v[194:197], v160 offset:17408
	ds_read_b128 v[198:201], v160 offset:18432
	ds_read_b128 v[202:205], v160 offset:19456
	ds_read_b128 v[206:209], v160 offset:20480
	ds_read_b128 v[210:213], v160 offset:21504
	ds_read_b128 v[214:217], v160 offset:22528
	ds_read_b128 v[218:221], v160 offset:23552
	global_load_lds_dwordx4 v132, s[40:41]
	s_add_i32 m0, s68, 0x2000
	s_add_u32 s68, s40, 0x100000
	s_addc_u32 s69, s41, 0
	s_add_i32 s70, s63, s33
	global_load_lds_dwordx4 v128, s[40:41]
	s_mov_b32 m0, s70
	s_nop 0
	global_load_lds_dwordx4 v132, s[68:69]
	s_add_i32 m0, s70, 0x2000
	s_nop 0
	global_load_lds_dwordx4 v128, s[68:69]
	s_mov_b32 m0, s53
	s_nop 0
	global_load_lds_dwordx4 v134, s[84:85]
	s_mov_b32 m0, s54
	s_nop 0
	global_load_lds_dwordx4 v130, s[84:85]
	s_waitcnt vmcnt(8)
	s_waitcnt lgkmcnt(0)
	s_barrier
	v_mfma_f32_16x16x32_bf16 v[60:63], v[150:153], v[190:193], v[60:63]
	v_mfma_f32_16x16x32_bf16 v[56:59], v[166:169], v[190:193], v[56:59]
	v_mfma_f32_16x16x32_bf16 v[44:47], v[150:153], v[198:201], v[44:47]
	v_mfma_f32_16x16x32_bf16 v[40:43], v[166:169], v[198:201], v[40:43]
	v_mfma_f32_16x16x32_bf16 v[28:31], v[150:153], v[206:209], v[28:31]
	v_mfma_f32_16x16x32_bf16 v[24:27], v[166:169], v[206:209], v[24:27]
	v_mfma_f32_16x16x32_bf16 v[12:15], v[150:153], v[214:217], v[12:15]
	v_mfma_f32_16x16x32_bf16 v[8:11], v[166:169], v[214:217], v[8:11]
	v_mfma_f32_16x16x32_bf16 v[60:63], v[162:165], v[194:197], v[60:63]
	v_mfma_f32_16x16x32_bf16 v[56:59], v[170:173], v[194:197], v[56:59]
	v_mfma_f32_16x16x32_bf16 v[44:47], v[162:165], v[202:205], v[44:47]
	v_mfma_f32_16x16x32_bf16 v[40:43], v[170:173], v[202:205], v[40:43]
	v_mfma_f32_16x16x32_bf16 v[28:31], v[162:165], v[210:213], v[28:31]
	v_mfma_f32_16x16x32_bf16 v[24:27], v[170:173], v[210:213], v[24:27]
	v_mfma_f32_16x16x32_bf16 v[12:15], v[162:165], v[218:221], v[12:15]
	v_mfma_f32_16x16x32_bf16 v[8:11], v[170:173], v[218:221], v[8:11]
	v_mfma_f32_16x16x32_bf16 v[52:55], v[174:177], v[190:193], v[52:55]
	v_mfma_f32_16x16x32_bf16 v[48:51], v[182:185], v[190:193], v[48:51]
	v_mfma_f32_16x16x32_bf16 v[36:39], v[174:177], v[198:201], v[36:39]
	v_mfma_f32_16x16x32_bf16 v[32:35], v[182:185], v[198:201], v[32:35]
	v_mfma_f32_16x16x32_bf16 v[20:23], v[174:177], v[206:209], v[20:23]
	v_mfma_f32_16x16x32_bf16 v[16:19], v[182:185], v[206:209], v[16:19]
	v_mfma_f32_16x16x32_bf16 v[4:7], v[174:177], v[214:217], v[4:7]
	v_mfma_f32_16x16x32_bf16 v[0:3], v[182:185], v[214:217], v[0:3]
	v_mfma_f32_16x16x32_bf16 v[52:55], v[178:181], v[194:197], v[52:55]
	v_mfma_f32_16x16x32_bf16 v[48:51], v[186:189], v[194:197], v[48:51]
	v_mfma_f32_16x16x32_bf16 v[36:39], v[178:181], v[202:205], v[36:39]
	v_mfma_f32_16x16x32_bf16 v[32:35], v[186:189], v[202:205], v[32:35]
	v_mfma_f32_16x16x32_bf16 v[20:23], v[178:181], v[210:213], v[20:23]
	v_mfma_f32_16x16x32_bf16 v[16:19], v[186:189], v[210:213], v[16:19]
	v_mfma_f32_16x16x32_bf16 v[4:7], v[178:181], v[218:221], v[4:7]
	v_mfma_f32_16x16x32_bf16 v[0:3], v[186:189], v[218:221], v[0:3]
	s_barrier
; #define PG8_STAGE(bufoff, gbase, voff) do { _Pragma("unroll") for (int _i = 0; _i < 2; ++_i) \
;         __builtin_amdgcn_global_load_lds((const unsigned*)((const char*)(gbase) + (voff)[_i]), (PG8_LAS unsigned*)(lds + (bufoff) + ldsw + _i * 8192), 16, 0, 0); } while (0)
; #define PG8_LDA(dst, b, h) do { _Pragma("unroll") for (int m = 0; m < 4; ++m) _Pragma("unroll") for (int k = 0; k < 2; ++k) dst[m][k] = *(const PG8_LAS bf16x8*)(lds + PG8_SA(b, h) + aoff + m * 2048 + k * 1024); } while (0)
; #define PG8_LDB(dst, b, h) do { _Pragma("unroll") for (int n = 0; n < 2; ++n) _Pragma("unroll") for (int k = 0; k < 2; ++k) dst[n][k] = *(const PG8_LAS bf16x8*)(lds + PG8_SB(b, h) + boff + n * 2048 + k * 1024); } while (0)
; #define PG8_MMA(ai, bj, At, Bt) do { __builtin_amdgcn_s_setprio(1); _Pragma("unroll") for (int m = 0; m < 4; ++m) _Pragma("unroll") for (int n = 0; n < 2; ++n) _Pragma("unroll") for (int k = 0; k < 2; ++k) \
;         acc[ai][bj][m][n] = __builtin_amdgcn_mfma_f32_16x16x32_bf16(Bt[n][k], At[m][k], acc[ai][bj][m][n], 0, 0, 0); __builtin_amdgcn_s_setprio(0); } while (0)
; #define PG8_WAIT_V(n) asm volatile("s_waitcnt vmcnt(" #n ")" ::: "memory")
; #define PG8_WAIT_L(n) asm volatile("s_waitcnt lgkmcnt(" #n ")" ::: "memory")
; #define PG8_BAR __builtin_amdgcn_s_barrier()
; #define PG8_SCHED __builtin_amdgcn_sched_barrier(0)
; template <class Epi, class Sched, bool ALIGN_EPI = false, bool SP2 = false>
; __device__ __forceinline__ void gemm_phase(PG8_LAS unsigned char* lds, const Gemm g, const Sched& S, const Epi& E) {
;     ...
;             PG8_LDB(B0, 1, 0); PG8_LDB(B1, 1, 1); PG8_SCHED; PG8_LDA(At, 1, 0); PG8_STAGE(PG8_SA(0, 1), a2 + hstepA, voffA);
;             PG8_WAIT_V(8); PG8_WAIT_L(0); PG8_BAR; PG8_MMA(0, 0, At, B0); PG8_MMA(0, 1, At, B1); PG8_BAR; PG8_SCHED;
;             PG8_LDA(At, 1, 1); PG8_STAGE(PG8_SB(1, 0), b3, voffB); PG8_STAGE(PG8_SB(1, 1), b3 + hstep, voffB); PG8_STAGE(PG8_SA(1, 0), a3, voffA);
;             PG8_WAIT_V(8); PG8_WAIT_L(0); PG8_BAR; PG8_MMA(1, 0, At, B0); PG8_MMA(1, 1, At, B1); PG8_BAR; PG8_SCHED;
	s_add_i32 s70, 0, 0x18000
	v_add_u32_e32 v136, s70, v157
	s_add_i32 s71, 0, 0x1c000
	ds_read_b128 v[150:153], v136
	ds_read_b128 v[162:165], v136 offset:1024
	ds_read_b128 v[166:169], v136 offset:2048
	ds_read_b128 v[170:173], v136 offset:3072
	v_add_u32_e32 v136, s71, v157
	ds_read_b128 v[174:177], v136
	ds_read_b128 v[178:181], v136 offset:1024
	ds_read_b128 v[182:185], v136 offset:2048
	ds_read_b128 v[186:189], v136 offset:3072
	s_add_u32 s68, s84, 0x100000
	s_addc_u32 s69, s85, 0
	s_mov_b32 m0, s55
	ds_read_b128 v[190:193], v160 offset:32768
	ds_read_b128 v[194:197], v160 offset:33792
	ds_read_b128 v[198:201], v160 offset:34816
	ds_read_b128 v[202:205], v160 offset:35840
	ds_read_b128 v[206:209], v160 offset:36864
	ds_read_b128 v[210:213], v160 offset:37888
	ds_read_b128 v[214:217], v160 offset:38912
	ds_read_b128 v[218:221], v160 offset:39936
	global_load_lds_dwordx4 v134, s[68:69]
	s_mov_b32 m0, s56
	s_nop 0
	global_load_lds_dwordx4 v130, s[68:69]
	s_waitcnt vmcnt(8)
	s_waitcnt lgkmcnt(0)
	s_barrier
	v_mfma_f32_16x16x32_bf16 v[124:127], v[150:153], v[190:193], v[124:127]
	v_mfma_f32_16x16x32_bf16 v[120:123], v[166:169], v[190:193], v[120:123]
	v_mfma_f32_16x16x32_bf16 v[108:111], v[150:153], v[198:201], v[108:111]
	v_mfma_f32_16x16x32_bf16 v[104:107], v[166:169], v[198:201], v[104:107]
	v_mfma_f32_16x16x32_bf16 v[92:95], v[150:153], v[206:209], v[92:95]
	v_mfma_f32_16x16x32_bf16 v[88:91], v[166:169], v[206:209], v[88:91]
	v_mfma_f32_16x16x32_bf16 v[76:79], v[150:153], v[214:217], v[76:79]
	v_mfma_f32_16x16x32_bf16 v[72:75], v[166:169], v[214:217], v[72:75]
	v_mfma_f32_16x16x32_bf16 v[124:127], v[162:165], v[194:197], v[124:127]
	v_mfma_f32_16x16x32_bf16 v[120:123], v[170:173], v[194:197], v[120:123]
	v_mfma_f32_16x16x32_bf16 v[108:111], v[162:165], v[202:205], v[108:111]
	v_mfma_f32_16x16x32_bf16 v[104:107], v[170:173], v[202:205], v[104:107]
	v_mfma_f32_16x16x32_bf16 v[92:95], v[162:165], v[210:213], v[92:95]
	v_mfma_f32_16x16x32_bf16 v[88:91], v[170:173], v[210:213], v[88:91]
	v_mfma_f32_16x16x32_bf16 v[76:79], v[162:165], v[218:221], v[76:79]
	v_mfma_f32_16x16x32_bf16 v[72:75], v[170:173], v[218:221], v[72:75]
	v_mfma_f32_16x16x32_bf16 v[116:119], v[174:177], v[190:193], v[116:119]
	v_mfma_f32_16x16x32_bf16 v[112:115], v[182:185], v[190:193], v[112:115]
	v_mfma_f32_16x16x32_bf16 v[100:103], v[174:177], v[198:201], v[100:103]
	v_mfma_f32_16x16x32_bf16 v[96:99], v[182:185], v[198:201], v[96:99]
	v_mfma_f32_16x16x32_bf16 v[84:87], v[174:177], v[206:209], v[84:87]
	v_mfma_f32_16x16x32_bf16 v[80:83], v[182:185], v[206:209], v[80:83]
	v_mfma_f32_16x16x32_bf16 v[68:71], v[174:177], v[214:217], v[68:71]
	v_mfma_f32_16x16x32_bf16 v[64:67], v[182:185], v[214:217], v[64:67]
	v_mfma_f32_16x16x32_bf16 v[116:119], v[178:181], v[194:197], v[116:119]
	v_mfma_f32_16x16x32_bf16 v[112:115], v[186:189], v[194:197], v[112:115]
	v_mfma_f32_16x16x32_bf16 v[100:103], v[178:181], v[202:205], v[100:103]
	v_mfma_f32_16x16x32_bf16 v[96:99], v[186:189], v[202:205], v[96:99]
	v_mfma_f32_16x16x32_bf16 v[84:87], v[178:181], v[210:213], v[84:87]
	v_mfma_f32_16x16x32_bf16 v[80:83], v[186:189], v[210:213], v[80:83]
	v_mfma_f32_16x16x32_bf16 v[68:71], v[178:181], v[218:221], v[68:71]
	v_mfma_f32_16x16x32_bf16 v[64:67], v[186:189], v[218:221], v[64:67]
	s_barrier
	s_add_i32 s68, s70, s33
	s_mov_b32 m0, s68
	ds_read_b128 v[190:193], v160 offset:49152
	ds_read_b128 v[194:197], v160 offset:50176
	ds_read_b128 v[198:201], v160 offset:51200
	ds_read_b128 v[202:205], v160 offset:52224
	ds_read_b128 v[206:209], v160 offset:53248
	ds_read_b128 v[210:213], v160 offset:54272
	ds_read_b128 v[214:217], v160 offset:55296
	ds_read_b128 v[218:221], v160 offset:56320
	global_load_lds_dwordx4 v132, s[98:99]
	s_add_i32 m0, s68, 0x2000
	s_add_u32 s40, s40, 0x100080
	s_addc_u32 s41, s41, 0
	s_add_i32 s68, s71, s33
	global_load_lds_dwordx4 v128, s[98:99]
	s_mov_b32 m0, s68
	s_nop 0
	global_load_lds_dwordx4 v132, s[40:41]
	s_add_i32 m0, s68, 0x2000
	s_nop 0
	global_load_lds_dwordx4 v128, s[40:41]
	s_mov_b32 m0, s60
	s_nop 0
	global_load_lds_dwordx4 v134, s[100:101]
	s_mov_b32 m0, s61
	s_nop 0
	global_load_lds_dwordx4 v130, s[100:101]
	s_waitcnt vmcnt(8)
	s_waitcnt lgkmcnt(0)
	s_barrier
	v_mfma_f32_16x16x32_bf16 v[60:63], v[150:153], v[190:193], v[60:63]
	v_mfma_f32_16x16x32_bf16 v[56:59], v[166:169], v[190:193], v[56:59]
	v_mfma_f32_16x16x32_bf16 v[44:47], v[150:153], v[198:201], v[44:47]
	v_mfma_f32_16x16x32_bf16 v[40:43], v[166:169], v[198:201], v[40:43]
	v_mfma_f32_16x16x32_bf16 v[28:31], v[150:153], v[206:209], v[28:31]
	v_mfma_f32_16x16x32_bf16 v[24:27], v[166:169], v[206:209], v[24:27]
	v_mfma_f32_16x16x32_bf16 v[12:15], v[150:153], v[214:217], v[12:15]
	v_mfma_f32_16x16x32_bf16 v[8:11], v[166:169], v[214:217], v[8:11]
	v_mfma_f32_16x16x32_bf16 v[60:63], v[162:165], v[194:197], v[60:63]
	v_mfma_f32_16x16x32_bf16 v[56:59], v[170:173], v[194:197], v[56:59]
	v_mfma_f32_16x16x32_bf16 v[44:47], v[162:165], v[202:205], v[44:47]
	v_mfma_f32_16x16x32_bf16 v[40:43], v[170:173], v[202:205], v[40:43]
	v_mfma_f32_16x16x32_bf16 v[28:31], v[162:165], v[210:213], v[28:31]
	v_mfma_f32_16x16x32_bf16 v[24:27], v[170:173], v[210:213], v[24:27]
	v_mfma_f32_16x16x32_bf16 v[12:15], v[162:165], v[218:221], v[12:15]
	v_mfma_f32_16x16x32_bf16 v[8:11], v[170:173], v[218:221], v[8:11]
	v_mfma_f32_16x16x32_bf16 v[52:55], v[174:177], v[190:193], v[52:55]
	v_mfma_f32_16x16x32_bf16 v[48:51], v[182:185], v[190:193], v[48:51]
	v_mfma_f32_16x16x32_bf16 v[36:39], v[174:177], v[198:201], v[36:39]
	v_mfma_f32_16x16x32_bf16 v[32:35], v[182:185], v[198:201], v[32:35]
	v_mfma_f32_16x16x32_bf16 v[20:23], v[174:177], v[206:209], v[20:23]
	v_mfma_f32_16x16x32_bf16 v[16:19], v[182:185], v[206:209], v[16:19]
	v_mfma_f32_16x16x32_bf16 v[4:7], v[174:177], v[214:217], v[4:7]
	v_mfma_f32_16x16x32_bf16 v[0:3], v[182:185], v[214:217], v[0:3]
	v_mfma_f32_16x16x32_bf16 v[52:55], v[178:181], v[194:197], v[52:55]
	v_mfma_f32_16x16x32_bf16 v[48:51], v[186:189], v[194:197], v[48:51]
	v_mfma_f32_16x16x32_bf16 v[36:39], v[178:181], v[202:205], v[36:39]
	v_mfma_f32_16x16x32_bf16 v[32:35], v[186:189], v[202:205], v[32:35]
	v_mfma_f32_16x16x32_bf16 v[20:23], v[178:181], v[210:213], v[20:23]
	v_mfma_f32_16x16x32_bf16 v[16:19], v[186:189], v[210:213], v[16:19]
	v_mfma_f32_16x16x32_bf16 v[4:7], v[178:181], v[218:221], v[4:7]
	v_mfma_f32_16x16x32_bf16 v[0:3], v[186:189], v[218:221], v[0:3]
	s_barrier
	s_add_i32 s67, s67, 2
	s_add_u32 s34, s34, 0x100
	s_addc_u32 s35, s35, 0
	s_add_u32 s65, s65, 0x100
	s_addc_u32 s66, s66, 0
	s_cmp_gt_u32 s67, 61
	s_cbranch_scc0 .LBB0_1741
	s_and_b64 vcc, exec, s[14:15]
	s_cbranch_vccz .LBB0_1744
	s_barrier

; #define PG8_STAGE(bufoff, gbase, voff) do { _Pragma("unroll") for (int _i = 0; _i < 2; ++_i) \
;         __builtin_amdgcn_global_load_lds((const unsigned*)((const char*)(gbase) + (voff)[_i]), (PG8_LAS unsigned*)(lds + (bufoff) + ldsw + _i * 8192), 16, 0, 0); } while (0)
; #define PG8_LDA(dst, b, h) do { _Pragma("unroll") for (int m = 0; m < 4; ++m) _Pragma("unroll") for (int k = 0; k < 2; ++k) dst[m][k] = *(const PG8_LAS bf16x8*)(lds + PG8_SA(b, h) + aoff + m * 2048 + k * 1024); } while (0)
; #define PG8_LDB(dst, b, h) do { _Pragma("unroll") for (int n = 0; n < 2; ++n) _Pragma("unroll") for (int k = 0; k < 2; ++k) dst[n][k] = *(const PG8_LAS bf16x8*)(lds + PG8_SB(b, h) + boff + n * 2048 + k * 1024); } while (0)
; #define PG8_MMA(ai, bj, At, Bt) do { __builtin_amdgcn_s_setprio(1); _Pragma("unroll") for (int m = 0; m < 4; ++m) _Pragma("unroll") for (int n = 0; n < 2; ++n) _Pragma("unroll") for (int k = 0; k < 2; ++k) \
;         acc[ai][bj][m][n] = __builtin_amdgcn_mfma_f32_16x16x32_bf16(Bt[n][k], At[m][k], acc[ai][bj][m][n], 0, 0, 0); __builtin_amdgcn_s_setprio(0); } while (0)
; #define PG8_WAIT_V(n) asm volatile("s_waitcnt vmcnt(" #n ")" ::: "memory")
; #define PG8_WAIT_L(n) asm volatile("s_waitcnt lgkmcnt(" #n ")" ::: "memory")
; #define PG8_BAR __builtin_amdgcn_s_barrier()
; #define PG8_SCHED __builtin_amdgcn_sched_barrier(0)
; template <class Epi, class Sched, bool ALIGN_EPI = false, bool SP2 = false>
; __device__ __forceinline__ void gemm_phase(PG8_LAS unsigned char* lds, const Gemm g, const Sched& S, const Epi& E) {
;     ...
;             PG8_LDB(B0, 0, 0); PG8_LDB(B1, 0, 1); PG8_SCHED; PG8_LDA(At, 0, 0); PG8_STAGE(PG8_SA(1, 1), a1 + hstepA, voffA);
;             PG8_WAIT_V(8); PG8_WAIT_L(0); PG8_BAR; PG8_MMA(0, 0, At, B0); PG8_MMA(0, 1, At, B1); PG8_BAR; PG8_SCHED;
;             PG8_LDA(At, 0, 1); PG8_STAGE(PG8_SB(0, 0), b2, voffB); PG8_STAGE(PG8_SB(0, 1), b2 + hstep, voffB); PG8_STAGE(PG8_SA(0, 0), a2, voffA);
;             PG8_WAIT_V(8); PG8_WAIT_L(0); PG8_BAR; PG8_MMA(1, 0, At, B0); PG8_MMA(1, 1, At, B1); PG8_BAR; PG8_SCHED;
.LBB0_2770:
	ds_read_b128 v[144:147], v153
	ds_read_b128 v[158:161], v153 offset:1024
	ds_read_b128 v[162:165], v153 offset:2048
	ds_read_b128 v[166:169], v153 offset:3072
	ds_read_b128 v[170:173], v154
	ds_read_b128 v[174:177], v154 offset:1024
	ds_read_b128 v[178:181], v154 offset:2048
	ds_read_b128 v[182:185], v154 offset:3072
	s_add_u32 s48, s46, 0xfff00080
	s_addc_u32 s49, s47, -1
	s_cmp_eq_u32 s69, 60
	s_cselect_b32 s51, s31, s49
	s_cselect_b32 s50, s43, s48
	s_cselect_b32 s49, s27, s68
	s_cselect_b32 s48, s66, s67
	s_add_i32 m0, s45, 0xc000
	ds_read_b128 v[186:189], v155
	ds_read_b128 v[190:193], v155 offset:1024
	ds_read_b128 v[194:197], v155 offset:2048
	ds_read_b128 v[198:201], v155 offset:3072
	ds_read_b128 v[202:205], v155 offset:4096
	ds_read_b128 v[206:209], v155 offset:5120
	ds_read_b128 v[210:213], v155 offset:6144
	ds_read_b128 v[214:217], v155 offset:7168
	global_load_lds_dwordx4 v136, s[46:47]
	s_add_i32 m0, s45, 0xe000
	s_nop 0
	global_load_lds_dwordx4 v138, s[46:47]
	s_waitcnt vmcnt(8)
	s_waitcnt lgkmcnt(0)
	s_barrier
	v_mfma_f32_16x16x32_bf16 v[124:127], v[144:147], v[186:189], v[124:127]
	v_mfma_f32_16x16x32_bf16 v[120:123], v[162:165], v[186:189], v[120:123]
	v_mfma_f32_16x16x32_bf16 v[108:111], v[144:147], v[194:197], v[108:111]
	v_mfma_f32_16x16x32_bf16 v[104:107], v[162:165], v[194:197], v[104:107]
	v_mfma_f32_16x16x32_bf16 v[92:95], v[144:147], v[202:205], v[92:95]
	v_mfma_f32_16x16x32_bf16 v[88:91], v[162:165], v[202:205], v[88:91]
	v_mfma_f32_16x16x32_bf16 v[76:79], v[144:147], v[210:213], v[76:79]
	v_mfma_f32_16x16x32_bf16 v[72:75], v[162:165], v[210:213], v[72:75]
	v_mfma_f32_16x16x32_bf16 v[124:127], v[158:161], v[190:193], v[124:127]
	v_mfma_f32_16x16x32_bf16 v[120:123], v[166:169], v[190:193], v[120:123]
	v_mfma_f32_16x16x32_bf16 v[108:111], v[158:161], v[198:201], v[108:111]
	v_mfma_f32_16x16x32_bf16 v[104:107], v[166:169], v[198:201], v[104:107]
	v_mfma_f32_16x16x32_bf16 v[92:95], v[158:161], v[206:209], v[92:95]
	v_mfma_f32_16x16x32_bf16 v[88:91], v[166:169], v[206:209], v[88:91]
	v_mfma_f32_16x16x32_bf16 v[76:79], v[158:161], v[214:217], v[76:79]
	v_mfma_f32_16x16x32_bf16 v[72:75], v[166:169], v[214:217], v[72:75]
	v_mfma_f32_16x16x32_bf16 v[116:119], v[170:173], v[186:189], v[116:119]
	v_mfma_f32_16x16x32_bf16 v[112:115], v[178:181], v[186:189], v[112:115]
	v_mfma_f32_16x16x32_bf16 v[100:103], v[170:173], v[194:197], v[100:103]
	v_mfma_f32_16x16x32_bf16 v[96:99], v[178:181], v[194:197], v[96:99]
	v_mfma_f32_16x16x32_bf16 v[84:87], v[170:173], v[202:205], v[84:87]
	v_mfma_f32_16x16x32_bf16 v[80:83], v[178:181], v[202:205], v[80:83]
	v_mfma_f32_16x16x32_bf16 v[68:71], v[170:173], v[210:213], v[68:71]
	v_mfma_f32_16x16x32_bf16 v[64:67], v[178:181], v[210:213], v[64:67]
	v_mfma_f32_16x16x32_bf16 v[116:119], v[174:177], v[190:193], v[116:119]
	v_mfma_f32_16x16x32_bf16 v[112:115], v[182:185], v[190:193], v[112:115]
	v_mfma_f32_16x16x32_bf16 v[100:103], v[174:177], v[198:201], v[100:103]
	v_mfma_f32_16x16x32_bf16 v[96:99], v[182:185], v[198:201], v[96:99]
	v_mfma_f32_16x16x32_bf16 v[84:87], v[174:177], v[206:209], v[84:87]
	v_mfma_f32_16x16x32_bf16 v[80:83], v[182:185], v[206:209], v[80:83]
	v_mfma_f32_16x16x32_bf16 v[68:71], v[174:177], v[214:217], v[68:71]
	v_mfma_f32_16x16x32_bf16 v[64:67], v[182:185], v[214:217], v[64:67]
	s_barrier
	s_add_u32 s98, s48, s16
	s_addc_u32 s99, s49, s17
	s_add_u32 s100, s50, s16
	s_addc_u32 s101, s51, s17
	s_add_i32 s70, s60, s33
	s_mov_b32 m0, s70
	ds_read_b128 v[186:189], v155 offset:16384
	ds_read_b128 v[190:193], v155 offset:17408
	ds_read_b128 v[194:197], v155 offset:18432
	ds_read_b128 v[198:201], v155 offset:19456
	ds_read_b128 v[202:205], v155 offset:20480
	ds_read_b128 v[206:209], v155 offset:21504
	ds_read_b128 v[210:213], v155 offset:22528
	ds_read_b128 v[214:217], v155 offset:23552
	global_load_lds_dwordx4 v130, s[48:49]
	s_add_i32 m0, s70, 0x2000
	s_add_u32 s70, s48, 0x100000
	s_addc_u32 s71, s49, 0
	s_add_i32 s72, s61, s33
	global_load_lds_dwordx4 v134, s[48:49]
	s_mov_b32 m0, s72
	s_nop 0
	global_load_lds_dwordx4 v130, s[70:71]
	s_add_i32 m0, s72, 0x2000
	s_nop 0
	global_load_lds_dwordx4 v134, s[70:71]
	s_mov_b32 m0, s45
	s_nop 0
	global_load_lds_dwordx4 v128, s[50:51]
	s_mov_b32 m0, s52
	s_nop 0
	global_load_lds_dwordx4 v132, s[50:51]
	s_waitcnt vmcnt(8)
	s_waitcnt lgkmcnt(0)
	s_barrier
	v_mfma_f32_16x16x32_bf16 v[60:63], v[144:147], v[186:189], v[60:63]
	v_mfma_f32_16x16x32_bf16 v[56:59], v[162:165], v[186:189], v[56:59]
	v_mfma_f32_16x16x32_bf16 v[44:47], v[144:147], v[194:197], v[44:47]
	v_mfma_f32_16x16x32_bf16 v[40:43], v[162:165], v[194:197], v[40:43]
	v_mfma_f32_16x16x32_bf16 v[28:31], v[144:147], v[202:205], v[28:31]
	v_mfma_f32_16x16x32_bf16 v[24:27], v[162:165], v[202:205], v[24:27]
	v_mfma_f32_16x16x32_bf16 v[12:15], v[144:147], v[210:213], v[12:15]
	v_mfma_f32_16x16x32_bf16 v[8:11], v[162:165], v[210:213], v[8:11]
	v_mfma_f32_16x16x32_bf16 v[60:63], v[158:161], v[190:193], v[60:63]
	v_mfma_f32_16x16x32_bf16 v[56:59], v[166:169], v[190:193], v[56:59]
	v_mfma_f32_16x16x32_bf16 v[44:47], v[158:161], v[198:201], v[44:47]
	v_mfma_f32_16x16x32_bf16 v[40:43], v[166:169], v[198:201], v[40:43]
	v_mfma_f32_16x16x32_bf16 v[28:31], v[158:161], v[206:209], v[28:31]
	v_mfma_f32_16x16x32_bf16 v[24:27], v[166:169], v[206:209], v[24:27]
	v_mfma_f32_16x16x32_bf16 v[12:15], v[158:161], v[214:217], v[12:15]
	v_mfma_f32_16x16x32_bf16 v[8:11], v[166:169], v[214:217], v[8:11]
	v_mfma_f32_16x16x32_bf16 v[52:55], v[170:173], v[186:189], v[52:55]
	v_mfma_f32_16x16x32_bf16 v[48:51], v[178:181], v[186:189], v[48:51]
	v_mfma_f32_16x16x32_bf16 v[36:39], v[170:173], v[194:197], v[36:39]
	v_mfma_f32_16x16x32_bf16 v[32:35], v[178:181], v[194:197], v[32:35]
	v_mfma_f32_16x16x32_bf16 v[20:23], v[170:173], v[202:205], v[20:23]
	v_mfma_f32_16x16x32_bf16 v[16:19], v[178:181], v[202:205], v[16:19]
	v_mfma_f32_16x16x32_bf16 v[4:7], v[170:173], v[210:213], v[4:7]
	v_mfma_f32_16x16x32_bf16 v[0:3], v[178:181], v[210:213], v[0:3]
	v_mfma_f32_16x16x32_bf16 v[52:55], v[174:177], v[190:193], v[52:55]
	v_mfma_f32_16x16x32_bf16 v[48:51], v[182:185], v[190:193], v[48:51]
	v_mfma_f32_16x16x32_bf16 v[36:39], v[174:177], v[198:201], v[36:39]
	v_mfma_f32_16x16x32_bf16 v[32:35], v[182:185], v[198:201], v[32:35]
	v_mfma_f32_16x16x32_bf16 v[20:23], v[174:177], v[206:209], v[20:23]
	v_mfma_f32_16x16x32_bf16 v[16:19], v[182:185], v[206:209], v[16:19]
	v_mfma_f32_16x16x32_bf16 v[4:7], v[174:177], v[214:217], v[4:7]
	v_mfma_f32_16x16x32_bf16 v[0:3], v[182:185], v[214:217], v[0:3]
	s_barrier
; #define PG8_STAGE(bufoff, gbase, voff) do { _Pragma("unroll") for (int _i = 0; _i < 2; ++_i) \
;         __builtin_amdgcn_global_load_lds((const unsigned*)((const char*)(gbase) + (voff)[_i]), (PG8_LAS unsigned*)(lds + (bufoff) + ldsw + _i * 8192), 16, 0, 0); } while (0)
; #define PG8_LDA(dst, b, h) do { _Pragma("unroll") for (int m = 0; m < 4; ++m) _Pragma("unroll") for (int k = 0; k < 2; ++k) dst[m][k] = *(const PG8_LAS bf16x8*)(lds + PG8_SA(b, h) + aoff + m * 2048 + k * 1024); } while (0)
; #define PG8_LDB(dst, b, h) do { _Pragma("unroll") for (int n = 0; n < 2; ++n) _Pragma("unroll") for (int k = 0; k < 2; ++k) dst[n][k] = *(const PG8_LAS bf16x8*)(lds + PG8_SB(b, h) + boff + n * 2048 + k * 1024); } while (0)
; #define PG8_MMA(ai, bj, At, Bt) do { __builtin_amdgcn_s_setprio(1); _Pragma("unroll") for (int m = 0; m < 4; ++m) _Pragma("unroll") for (int n = 0; n < 2; ++n) _Pragma("unroll") for (int k = 0; k < 2; ++k) \
;         acc[ai][bj][m][n] = __builtin_amdgcn_mfma_f32_16x16x32_bf16(Bt[n][k], At[m][k], acc[ai][bj][m][n], 0, 0, 0); __builtin_amdgcn_s_setprio(0); } while (0)
; #define PG8_WAIT_V(n) asm volatile("s_waitcnt vmcnt(" #n ")" ::: "memory")
; #define PG8_WAIT_L(n) asm volatile("s_waitcnt lgkmcnt(" #n ")" ::: "memory")
; #define PG8_BAR __builtin_amdgcn_s_barrier()
; #define PG8_SCHED __builtin_amdgcn_sched_barrier(0)
; template <class Epi, class Sched, bool ALIGN_EPI = false, bool SP2 = false>
; __device__ __forceinline__ void gemm_phase(PG8_LAS unsigned char* lds, const Gemm g, const Sched& S, const Epi& E) {
;     ...
;             PG8_LDB(B0, 1, 0); PG8_LDB(B1, 1, 1); PG8_SCHED; PG8_LDA(At, 1, 0); PG8_STAGE(PG8_SA(0, 1), a2 + hstepA, voffA);
;             PG8_WAIT_V(8); PG8_WAIT_L(0); PG8_BAR; PG8_MMA(0, 0, At, B0); PG8_MMA(0, 1, At, B1); PG8_BAR; PG8_SCHED;
;             PG8_LDA(At, 1, 1); PG8_STAGE(PG8_SB(1, 0), b3, voffB); PG8_STAGE(PG8_SB(1, 1), b3 + hstep, voffB); PG8_STAGE(PG8_SA(1, 0), a3, voffA);
;             PG8_WAIT_V(8); PG8_WAIT_L(0); PG8_BAR; PG8_MMA(1, 0, At, B0); PG8_MMA(1, 1, At, B1); PG8_BAR; PG8_SCHED;
	s_add_i32 s70, 0, 0x18000
	v_add_u32_e32 v157, s70, v151
	s_add_i32 s71, 0, 0x1c000
	ds_read_b128 v[144:147], v157
	ds_read_b128 v[158:161], v157 offset:1024
	ds_read_b128 v[162:165], v157 offset:2048
	ds_read_b128 v[166:169], v157 offset:3072
	v_add_u32_e32 v157, s71, v151
	ds_read_b128 v[170:173], v157
	ds_read_b128 v[174:177], v157 offset:1024
	ds_read_b128 v[178:181], v157 offset:2048
	ds_read_b128 v[182:185], v157 offset:3072
	s_add_u32 s50, s50, 0x100000
	s_addc_u32 s51, s51, 0
	s_mov_b32 m0, s53
	ds_read_b128 v[186:189], v155 offset:32768
	ds_read_b128 v[190:193], v155 offset:33792
	ds_read_b128 v[194:197], v155 offset:34816
	ds_read_b128 v[198:201], v155 offset:35840
	ds_read_b128 v[202:205], v155 offset:36864
	ds_read_b128 v[206:209], v155 offset:37888
	ds_read_b128 v[210:213], v155 offset:38912
	ds_read_b128 v[214:217], v155 offset:39936
	global_load_lds_dwordx4 v128, s[50:51]
	s_mov_b32 m0, s54
	s_nop 0
	global_load_lds_dwordx4 v132, s[50:51]
	s_waitcnt vmcnt(8)
	s_waitcnt lgkmcnt(0)
	s_barrier
	v_mfma_f32_16x16x32_bf16 v[124:127], v[144:147], v[186:189], v[124:127]
	v_mfma_f32_16x16x32_bf16 v[120:123], v[162:165], v[186:189], v[120:123]
	v_mfma_f32_16x16x32_bf16 v[108:111], v[144:147], v[194:197], v[108:111]
	v_mfma_f32_16x16x32_bf16 v[104:107], v[162:165], v[194:197], v[104:107]
	v_mfma_f32_16x16x32_bf16 v[92:95], v[144:147], v[202:205], v[92:95]
	v_mfma_f32_16x16x32_bf16 v[88:91], v[162:165], v[202:205], v[88:91]
	v_mfma_f32_16x16x32_bf16 v[76:79], v[144:147], v[210:213], v[76:79]
	v_mfma_f32_16x16x32_bf16 v[72:75], v[162:165], v[210:213], v[72:75]
	v_mfma_f32_16x16x32_bf16 v[124:127], v[158:161], v[190:193], v[124:127]
	v_mfma_f32_16x16x32_bf16 v[120:123], v[166:169], v[190:193], v[120:123]
	v_mfma_f32_16x16x32_bf16 v[108:111], v[158:161], v[198:201], v[108:111]
	v_mfma_f32_16x16x32_bf16 v[104:107], v[166:169], v[198:201], v[104:107]
	v_mfma_f32_16x16x32_bf16 v[92:95], v[158:161], v[206:209], v[92:95]
	v_mfma_f32_16x16x32_bf16 v[88:91], v[166:169], v[206:209], v[88:91]
	v_mfma_f32_16x16x32_bf16 v[76:79], v[158:161], v[214:217], v[76:79]
	v_mfma_f32_16x16x32_bf16 v[72:75], v[166:169], v[214:217], v[72:75]
	v_mfma_f32_16x16x32_bf16 v[116:119], v[170:173], v[186:189], v[116:119]
	v_mfma_f32_16x16x32_bf16 v[112:115], v[178:181], v[186:189], v[112:115]
	v_mfma_f32_16x16x32_bf16 v[100:103], v[170:173], v[194:197], v[100:103]
	v_mfma_f32_16x16x32_bf16 v[96:99], v[178:181], v[194:197], v[96:99]
	v_mfma_f32_16x16x32_bf16 v[84:87], v[170:173], v[202:205], v[84:87]
	v_mfma_f32_16x16x32_bf16 v[80:83], v[178:181], v[202:205], v[80:83]
	v_mfma_f32_16x16x32_bf16 v[68:71], v[170:173], v[210:213], v[68:71]
	v_mfma_f32_16x16x32_bf16 v[64:67], v[178:181], v[210:213], v[64:67]
	v_mfma_f32_16x16x32_bf16 v[116:119], v[174:177], v[190:193], v[116:119]
	v_mfma_f32_16x16x32_bf16 v[112:115], v[182:185], v[190:193], v[112:115]
	v_mfma_f32_16x16x32_bf16 v[100:103], v[174:177], v[198:201], v[100:103]
	v_mfma_f32_16x16x32_bf16 v[96:99], v[182:185], v[198:201], v[96:99]
	v_mfma_f32_16x16x32_bf16 v[84:87], v[174:177], v[206:209], v[84:87]
	v_mfma_f32_16x16x32_bf16 v[80:83], v[182:185], v[206:209], v[80:83]
	v_mfma_f32_16x16x32_bf16 v[68:71], v[174:177], v[214:217], v[68:71]
	v_mfma_f32_16x16x32_bf16 v[64:67], v[182:185], v[214:217], v[64:67]
	s_barrier
	s_add_i32 s50, s70, s33
	s_mov_b32 m0, s50
	ds_read_b128 v[186:189], v155 offset:49152
	ds_read_b128 v[190:193], v155 offset:50176
	ds_read_b128 v[194:197], v155 offset:51200
	ds_read_b128 v[198:201], v155 offset:52224
	ds_read_b128 v[202:205], v155 offset:53248
	ds_read_b128 v[206:209], v155 offset:54272
	ds_read_b128 v[210:213], v155 offset:55296
	ds_read_b128 v[214:217], v155 offset:56320
	global_load_lds_dwordx4 v130, s[98:99]
	s_add_i32 m0, s50, 0x2000
	s_add_u32 s48, s48, 0x100080
	s_addc_u32 s49, s49, 0
	s_add_i32 s50, s71, s33
	global_load_lds_dwordx4 v134, s[98:99]
	s_mov_b32 m0, s50
	s_nop 0
	global_load_lds_dwordx4 v130, s[48:49]
	s_add_i32 m0, s50, 0x2000
	s_nop 0
	global_load_lds_dwordx4 v134, s[48:49]
	s_mov_b32 m0, s56
	s_nop 0
	global_load_lds_dwordx4 v128, s[100:101]
	s_mov_b32 m0, s57
	s_nop 0
	global_load_lds_dwordx4 v132, s[100:101]
	s_waitcnt vmcnt(8)
	s_waitcnt lgkmcnt(0)
	s_barrier
	v_mfma_f32_16x16x32_bf16 v[60:63], v[144:147], v[186:189], v[60:63]
	v_mfma_f32_16x16x32_bf16 v[56:59], v[162:165], v[186:189], v[56:59]
	v_mfma_f32_16x16x32_bf16 v[44:47], v[144:147], v[194:197], v[44:47]
	v_mfma_f32_16x16x32_bf16 v[40:43], v[162:165], v[194:197], v[40:43]
	v_mfma_f32_16x16x32_bf16 v[28:31], v[144:147], v[202:205], v[28:31]
	v_mfma_f32_16x16x32_bf16 v[24:27], v[162:165], v[202:205], v[24:27]
	v_mfma_f32_16x16x32_bf16 v[12:15], v[144:147], v[210:213], v[12:15]
	v_mfma_f32_16x16x32_bf16 v[8:11], v[162:165], v[210:213], v[8:11]
	v_mfma_f32_16x16x32_bf16 v[60:63], v[158:161], v[190:193], v[60:63]
	v_mfma_f32_16x16x32_bf16 v[56:59], v[166:169], v[190:193], v[56:59]
	v_mfma_f32_16x16x32_bf16 v[44:47], v[158:161], v[198:201], v[44:47]
	v_mfma_f32_16x16x32_bf16 v[40:43], v[166:169], v[198:201], v[40:43]
	v_mfma_f32_16x16x32_bf16 v[28:31], v[158:161], v[206:209], v[28:31]
	v_mfma_f32_16x16x32_bf16 v[24:27], v[166:169], v[206:209], v[24:27]
	v_mfma_f32_16x16x32_bf16 v[12:15], v[158:161], v[214:217], v[12:15]
	v_mfma_f32_16x16x32_bf16 v[8:11], v[166:169], v[214:217], v[8:11]
	v_mfma_f32_16x16x32_bf16 v[52:55], v[170:173], v[186:189], v[52:55]
	v_mfma_f32_16x16x32_bf16 v[48:51], v[178:181], v[186:189], v[48:51]
	v_mfma_f32_16x16x32_bf16 v[36:39], v[170:173], v[194:197], v[36:39]
	v_mfma_f32_16x16x32_bf16 v[32:35], v[178:181], v[194:197], v[32:35]
	v_mfma_f32_16x16x32_bf16 v[20:23], v[170:173], v[202:205], v[20:23]
	v_mfma_f32_16x16x32_bf16 v[16:19], v[178:181], v[202:205], v[16:19]
	v_mfma_f32_16x16x32_bf16 v[4:7], v[170:173], v[210:213], v[4:7]
	v_mfma_f32_16x16x32_bf16 v[0:3], v[178:181], v[210:213], v[0:3]
	v_mfma_f32_16x16x32_bf16 v[52:55], v[174:177], v[190:193], v[52:55]
	v_mfma_f32_16x16x32_bf16 v[48:51], v[182:185], v[190:193], v[48:51]
	v_mfma_f32_16x16x32_bf16 v[36:39], v[174:177], v[198:201], v[36:39]
	v_mfma_f32_16x16x32_bf16 v[32:35], v[182:185], v[198:201], v[32:35]
	v_mfma_f32_16x16x32_bf16 v[20:23], v[174:177], v[206:209], v[20:23]
	v_mfma_f32_16x16x32_bf16 v[16:19], v[182:185], v[206:209], v[16:19]
	v_mfma_f32_16x16x32_bf16 v[4:7], v[174:177], v[214:217], v[4:7]
	v_mfma_f32_16x16x32_bf16 v[0:3], v[182:185], v[214:217], v[0:3]
	s_barrier
	s_add_i32 s69, s69, 2
	s_add_u32 s46, s46, 0x100
	s_addc_u32 s47, s47, 0
	s_add_u32 s67, s67, 0x100
	s_addc_u32 s68, s68, 0
	s_cmp_gt_u32 s69, 61
	s_cbranch_scc0 .LBB0_2770
	s_and_b64 vcc, exec, s[18:19]
	s_cbranch_vccz .LBB0_2773
	s_barrier

; #define PG8_STAGE(bufoff, gbase, voff) do { _Pragma("unroll") for (int _i = 0; _i < 2; ++_i) \
;         __builtin_amdgcn_global_load_lds((const unsigned*)((const char*)(gbase) + (voff)[_i]), (PG8_LAS unsigned*)(lds + (bufoff) + ldsw + _i * 8192), 16, 0, 0); } while (0)
; #define PG8_LDA(dst, b, h) do { _Pragma("unroll") for (int m = 0; m < 4; ++m) _Pragma("unroll") for (int k = 0; k < 2; ++k) dst[m][k] = *(const PG8_LAS bf16x8*)(lds + PG8_SA(b, h) + aoff + m * 2048 + k * 1024); } while (0)
; #define PG8_LDB(dst, b, h) do { _Pragma("unroll") for (int n = 0; n < 2; ++n) _Pragma("unroll") for (int k = 0; k < 2; ++k) dst[n][k] = *(const PG8_LAS bf16x8*)(lds + PG8_SB(b, h) + boff + n * 2048 + k * 1024); } while (0)
; #define PG8_MMA(ai, bj, At, Bt) do { __builtin_amdgcn_s_setprio(1); _Pragma("unroll") for (int m = 0; m < 4; ++m) _Pragma("unroll") for (int n = 0; n < 2; ++n) _Pragma("unroll") for (int k = 0; k < 2; ++k) \
;         acc[ai][bj][m][n] = __builtin_amdgcn_mfma_f32_16x16x32_bf16(Bt[n][k], At[m][k], acc[ai][bj][m][n], 0, 0, 0); __builtin_amdgcn_s_setprio(0); } while (0)
; #define PG8_WAIT_V(n) asm volatile("s_waitcnt vmcnt(" #n ")" ::: "memory")
; #define PG8_WAIT_L(n) asm volatile("s_waitcnt lgkmcnt(" #n ")" ::: "memory")
; #define PG8_BAR __builtin_amdgcn_s_barrier()
; #define PG8_SCHED __builtin_amdgcn_sched_barrier(0)
; template <class Epi, class Sched, bool ALIGN_EPI = false, bool SP2 = false>
; __device__ __forceinline__ void gemm_phase(PG8_LAS unsigned char* lds, const Gemm g, const Sched& S, const Epi& E) {
;     ...
;             PG8_LDB(B0, 0, 0); PG8_LDB(B1, 0, 1); PG8_SCHED; PG8_LDA(At, 0, 0); PG8_STAGE(PG8_SA(1, 1), a1 + hstepA, voffA);
;             PG8_WAIT_V(8); PG8_WAIT_L(0); PG8_BAR; PG8_MMA(0, 0, At, B0); PG8_MMA(0, 1, At, B1); PG8_BAR; PG8_SCHED;
;             PG8_LDA(At, 0, 1); PG8_STAGE(PG8_SB(0, 0), b2, voffB); PG8_STAGE(PG8_SB(0, 1), b2 + hstep, voffB); PG8_STAGE(PG8_SA(0, 0), a2, voffA);
;             PG8_WAIT_V(8); PG8_WAIT_L(0); PG8_BAR; PG8_MMA(1, 0, At, B0); PG8_MMA(1, 1, At, B1); PG8_BAR; PG8_SCHED;
.LBB0_2882:
	ds_read_b128 v[128:131], v236
	ds_read_b128 v[132:135], v236 offset:1024
	ds_read_b128 v[136:139], v236 offset:2048
	ds_read_b128 v[140:143], v236 offset:3072
	ds_read_b128 v[144:147], v237
	ds_read_b128 v[148:151], v237 offset:1024
	ds_read_b128 v[152:155], v237 offset:2048
	ds_read_b128 v[156:159], v237 offset:3072
	s_add_u32 s10, s8, 0x100
	s_addc_u32 s11, s9, 0
	s_cmp_eq_u32 s88, 60
	s_cselect_b32 s61, s7, s11
	s_cselect_b32 s60, s51, s10
	s_cselect_b32 s59, s49, s87
	s_cselect_b32 s58, s85, s86
	v_lshl_add_u64 v[164:165], s[8:9], 0, v[178:179]
	s_add_i32 m0, s57, 0xc000
	ds_read_b128 v[160:163], v238
	ds_read_b128 v[186:189], v238 offset:1024
	ds_read_b128 v[190:193], v238 offset:2048
	ds_read_b128 v[194:197], v238 offset:3072
	ds_read_b128 v[198:201], v238 offset:4096
	ds_read_b128 v[202:205], v238 offset:5120
	ds_read_b128 v[206:209], v238 offset:6144
	ds_read_b128 v[210:213], v238 offset:7168
	global_load_lds_dwordx4 v[164:165], off
	v_lshl_add_u64 v[164:165], s[8:9], 0, v[180:181]
	s_add_i32 m0, s57, 0xe000
	s_nop 0
	global_load_lds_dwordx4 v[164:165], off
	s_waitcnt vmcnt(8)
	s_waitcnt lgkmcnt(0)
	s_barrier
	v_mfma_f32_16x16x32_bf16 v[124:127], v[128:131], v[160:163], v[124:127]
	v_mfma_f32_16x16x32_bf16 v[120:123], v[136:139], v[160:163], v[120:123]
	v_mfma_f32_16x16x32_bf16 v[108:111], v[128:131], v[190:193], v[108:111]
	v_mfma_f32_16x16x32_bf16 v[104:107], v[136:139], v[190:193], v[104:107]
	v_mfma_f32_16x16x32_bf16 v[92:95], v[128:131], v[198:201], v[92:95]
	v_mfma_f32_16x16x32_bf16 v[88:91], v[136:139], v[198:201], v[88:91]
	v_mfma_f32_16x16x32_bf16 v[76:79], v[128:131], v[206:209], v[76:79]
	v_mfma_f32_16x16x32_bf16 v[72:75], v[136:139], v[206:209], v[72:75]
	v_mfma_f32_16x16x32_bf16 v[124:127], v[132:135], v[186:189], v[124:127]
	v_mfma_f32_16x16x32_bf16 v[120:123], v[140:143], v[186:189], v[120:123]
	v_mfma_f32_16x16x32_bf16 v[108:111], v[132:135], v[194:197], v[108:111]
	v_mfma_f32_16x16x32_bf16 v[104:107], v[140:143], v[194:197], v[104:107]
	v_mfma_f32_16x16x32_bf16 v[92:95], v[132:135], v[202:205], v[92:95]
	v_mfma_f32_16x16x32_bf16 v[88:91], v[140:143], v[202:205], v[88:91]
	v_mfma_f32_16x16x32_bf16 v[76:79], v[132:135], v[210:213], v[76:79]
	v_mfma_f32_16x16x32_bf16 v[72:75], v[140:143], v[210:213], v[72:75]
	v_mfma_f32_16x16x32_bf16 v[116:119], v[144:147], v[160:163], v[116:119]
	v_mfma_f32_16x16x32_bf16 v[112:115], v[152:155], v[160:163], v[112:115]
	v_mfma_f32_16x16x32_bf16 v[100:103], v[144:147], v[190:193], v[100:103]
	v_mfma_f32_16x16x32_bf16 v[96:99], v[152:155], v[190:193], v[96:99]
	v_mfma_f32_16x16x32_bf16 v[84:87], v[144:147], v[198:201], v[84:87]
	v_mfma_f32_16x16x32_bf16 v[80:83], v[152:155], v[198:201], v[80:83]
	v_mfma_f32_16x16x32_bf16 v[68:71], v[144:147], v[206:209], v[68:71]
	v_mfma_f32_16x16x32_bf16 v[64:67], v[152:155], v[206:209], v[64:67]
	v_mfma_f32_16x16x32_bf16 v[116:119], v[148:151], v[186:189], v[116:119]
	v_mfma_f32_16x16x32_bf16 v[112:115], v[156:159], v[186:189], v[112:115]
	v_mfma_f32_16x16x32_bf16 v[100:103], v[148:151], v[194:197], v[100:103]
	v_mfma_f32_16x16x32_bf16 v[96:99], v[156:159], v[194:197], v[96:99]
	v_mfma_f32_16x16x32_bf16 v[84:87], v[148:151], v[202:205], v[84:87]
	v_mfma_f32_16x16x32_bf16 v[80:83], v[156:159], v[202:205], v[80:83]
	v_mfma_f32_16x16x32_bf16 v[68:71], v[148:151], v[210:213], v[68:71]
	v_mfma_f32_16x16x32_bf16 v[64:67], v[156:159], v[210:213], v[64:67]
	s_barrier
	s_add_u32 s98, s58, s16
	s_addc_u32 s99, s59, s17
	s_add_u32 s100, s60, s16
	s_addc_u32 s101, s61, s17
	s_add_i32 s8, s72, s63
	s_mov_b32 m0, s8
	ds_read_b128 v[160:163], v238 offset:16384
	ds_read_b128 v[186:189], v238 offset:17408
	ds_read_b128 v[190:193], v238 offset:18432
	ds_read_b128 v[194:197], v238 offset:19456
	ds_read_b128 v[198:201], v238 offset:20480
	ds_read_b128 v[202:205], v238 offset:21504
	ds_read_b128 v[206:209], v238 offset:22528
	ds_read_b128 v[210:213], v238 offset:23552
	global_load_lds_dwordx4 v168, s[58:59]
	s_add_i32 m0, s8, 0x2000
	s_add_u32 s8, s58, 0x100000
	s_addc_u32 s9, s59, 0
	s_add_i32 s89, s73, s63
	global_load_lds_dwordx4 v172, s[58:59]
	s_mov_b32 m0, s89
	s_nop 0
	global_load_lds_dwordx4 v168, s[8:9]
	s_add_i32 m0, s89, 0x2000
	s_nop 0
	global_load_lds_dwordx4 v172, s[8:9]
	s_mov_b32 m0, s57
	s_nop 0
	global_load_lds_dwordx4 v166, s[60:61]
	s_mov_b32 m0, s64
	s_nop 0
	global_load_lds_dwordx4 v170, s[60:61]
	s_waitcnt vmcnt(8)
	s_waitcnt lgkmcnt(0)
	s_barrier
	v_mfma_f32_16x16x32_bf16 v[60:63], v[128:131], v[160:163], v[60:63]
	v_mfma_f32_16x16x32_bf16 v[56:59], v[136:139], v[160:163], v[56:59]
	v_mfma_f32_16x16x32_bf16 v[44:47], v[128:131], v[190:193], v[44:47]
	v_mfma_f32_16x16x32_bf16 v[40:43], v[136:139], v[190:193], v[40:43]
	v_mfma_f32_16x16x32_bf16 v[28:31], v[128:131], v[198:201], v[28:31]
	v_mfma_f32_16x16x32_bf16 v[24:27], v[136:139], v[198:201], v[24:27]
	v_mfma_f32_16x16x32_bf16 v[12:15], v[128:131], v[206:209], v[12:15]
	v_mfma_f32_16x16x32_bf16 v[8:11], v[136:139], v[206:209], v[8:11]
	v_mfma_f32_16x16x32_bf16 v[60:63], v[132:135], v[186:189], v[60:63]
	v_mfma_f32_16x16x32_bf16 v[56:59], v[140:143], v[186:189], v[56:59]
	v_mfma_f32_16x16x32_bf16 v[44:47], v[132:135], v[194:197], v[44:47]
	v_mfma_f32_16x16x32_bf16 v[40:43], v[140:143], v[194:197], v[40:43]
	v_mfma_f32_16x16x32_bf16 v[28:31], v[132:135], v[202:205], v[28:31]
	v_mfma_f32_16x16x32_bf16 v[24:27], v[140:143], v[202:205], v[24:27]
	v_mfma_f32_16x16x32_bf16 v[12:15], v[132:135], v[210:213], v[12:15]
	v_mfma_f32_16x16x32_bf16 v[8:11], v[140:143], v[210:213], v[8:11]
	v_mfma_f32_16x16x32_bf16 v[52:55], v[144:147], v[160:163], v[52:55]
	v_mfma_f32_16x16x32_bf16 v[48:51], v[152:155], v[160:163], v[48:51]
	v_mfma_f32_16x16x32_bf16 v[36:39], v[144:147], v[190:193], v[36:39]
	v_mfma_f32_16x16x32_bf16 v[32:35], v[152:155], v[190:193], v[32:35]
	v_mfma_f32_16x16x32_bf16 v[20:23], v[144:147], v[198:201], v[20:23]
	v_mfma_f32_16x16x32_bf16 v[16:19], v[152:155], v[198:201], v[16:19]
	v_mfma_f32_16x16x32_bf16 v[4:7], v[144:147], v[206:209], v[4:7]
	v_mfma_f32_16x16x32_bf16 v[0:3], v[152:155], v[206:209], v[0:3]
	v_mfma_f32_16x16x32_bf16 v[52:55], v[148:151], v[186:189], v[52:55]
	v_mfma_f32_16x16x32_bf16 v[48:51], v[156:159], v[186:189], v[48:51]
	v_mfma_f32_16x16x32_bf16 v[36:39], v[148:151], v[194:197], v[36:39]
	v_mfma_f32_16x16x32_bf16 v[32:35], v[156:159], v[194:197], v[32:35]
	v_mfma_f32_16x16x32_bf16 v[20:23], v[148:151], v[202:205], v[20:23]
	v_mfma_f32_16x16x32_bf16 v[16:19], v[156:159], v[202:205], v[16:19]
	v_mfma_f32_16x16x32_bf16 v[4:7], v[148:151], v[210:213], v[4:7]
	v_mfma_f32_16x16x32_bf16 v[0:3], v[156:159], v[210:213], v[0:3]
	s_barrier
; #define PG8_STAGE(bufoff, gbase, voff) do { _Pragma("unroll") for (int _i = 0; _i < 2; ++_i) \
;         __builtin_amdgcn_global_load_lds((const unsigned*)((const char*)(gbase) + (voff)[_i]), (PG8_LAS unsigned*)(lds + (bufoff) + ldsw + _i * 8192), 16, 0, 0); } while (0)
; #define PG8_LDA(dst, b, h) do { _Pragma("unroll") for (int m = 0; m < 4; ++m) _Pragma("unroll") for (int k = 0; k < 2; ++k) dst[m][k] = *(const PG8_LAS bf16x8*)(lds + PG8_SA(b, h) + aoff + m * 2048 + k * 1024); } while (0)
; #define PG8_LDB(dst, b, h) do { _Pragma("unroll") for (int n = 0; n < 2; ++n) _Pragma("unroll") for (int k = 0; k < 2; ++k) dst[n][k] = *(const PG8_LAS bf16x8*)(lds + PG8_SB(b, h) + boff + n * 2048 + k * 1024); } while (0)
; #define PG8_MMA(ai, bj, At, Bt) do { __builtin_amdgcn_s_setprio(1); _Pragma("unroll") for (int m = 0; m < 4; ++m) _Pragma("unroll") for (int n = 0; n < 2; ++n) _Pragma("unroll") for (int k = 0; k < 2; ++k) \
;         acc[ai][bj][m][n] = __builtin_amdgcn_mfma_f32_16x16x32_bf16(Bt[n][k], At[m][k], acc[ai][bj][m][n], 0, 0, 0); __builtin_amdgcn_s_setprio(0); } while (0)
; #define PG8_WAIT_V(n) asm volatile("s_waitcnt vmcnt(" #n ")" ::: "memory")
; #define PG8_WAIT_L(n) asm volatile("s_waitcnt lgkmcnt(" #n ")" ::: "memory")
; #define PG8_BAR __builtin_amdgcn_s_barrier()
; #define PG8_SCHED __builtin_amdgcn_sched_barrier(0)
; template <class Epi, class Sched, bool ALIGN_EPI = false, bool SP2 = false>
; __device__ __forceinline__ void gemm_phase(PG8_LAS unsigned char* lds, const Gemm g, const Sched& S, const Epi& E) {
;     ...
;             PG8_LDB(B0, 1, 0); PG8_LDB(B1, 1, 1); PG8_SCHED; PG8_LDA(At, 1, 0); PG8_STAGE(PG8_SA(0, 1), a2 + hstepA, voffA);
;             PG8_WAIT_V(8); PG8_WAIT_L(0); PG8_BAR; PG8_MMA(0, 0, At, B0); PG8_MMA(0, 1, At, B1); PG8_BAR; PG8_SCHED;
;             PG8_LDA(At, 1, 1); PG8_STAGE(PG8_SB(1, 0), b3, voffB); PG8_STAGE(PG8_SB(1, 1), b3 + hstep, voffB); PG8_STAGE(PG8_SA(1, 0), a3, voffA);
;             PG8_WAIT_V(8); PG8_WAIT_L(0); PG8_BAR; PG8_MMA(1, 0, At, B0); PG8_MMA(1, 1, At, B1); PG8_BAR; PG8_SCHED;
	s_add_i32 s89, 0, 0x18000
	s_add_i32 s90, 0, 0x1c000
	v_add_u32_e32 v140, s89, v234
	v_add_u32_e32 v156, s90, v234
	ds_read_b128 v[128:131], v140
	ds_read_b128 v[132:135], v140 offset:1024
	ds_read_b128 v[136:139], v140 offset:2048
	ds_read_b128 v[140:143], v140 offset:3072
	ds_read_b128 v[144:147], v156
	ds_read_b128 v[148:151], v156 offset:1024
	ds_read_b128 v[152:155], v156 offset:2048
	ds_read_b128 v[156:159], v156 offset:3072
	s_add_u32 s8, s60, 0x100000
	s_addc_u32 s9, s61, 0
	s_mov_b32 m0, s65
	ds_read_b128 v[160:163], v238 offset:32768
	ds_read_b128 v[186:189], v238 offset:33792
	ds_read_b128 v[190:193], v238 offset:34816
	ds_read_b128 v[194:197], v238 offset:35840
	ds_read_b128 v[198:201], v238 offset:36864
	ds_read_b128 v[202:205], v238 offset:37888
	ds_read_b128 v[206:209], v238 offset:38912
	ds_read_b128 v[210:213], v238 offset:39936
	global_load_lds_dwordx4 v166, s[8:9]
	s_mov_b32 m0, s66
	s_nop 0
	global_load_lds_dwordx4 v170, s[8:9]
	s_waitcnt vmcnt(8)
	s_waitcnt lgkmcnt(0)
	s_barrier
	v_mfma_f32_16x16x32_bf16 v[124:127], v[128:131], v[160:163], v[124:127]
	v_mfma_f32_16x16x32_bf16 v[120:123], v[136:139], v[160:163], v[120:123]
	v_mfma_f32_16x16x32_bf16 v[108:111], v[128:131], v[190:193], v[108:111]
	v_mfma_f32_16x16x32_bf16 v[104:107], v[136:139], v[190:193], v[104:107]
	v_mfma_f32_16x16x32_bf16 v[92:95], v[128:131], v[198:201], v[92:95]
	v_mfma_f32_16x16x32_bf16 v[88:91], v[136:139], v[198:201], v[88:91]
	v_mfma_f32_16x16x32_bf16 v[76:79], v[128:131], v[206:209], v[76:79]
	v_mfma_f32_16x16x32_bf16 v[72:75], v[136:139], v[206:209], v[72:75]
	v_mfma_f32_16x16x32_bf16 v[124:127], v[132:135], v[186:189], v[124:127]
	v_mfma_f32_16x16x32_bf16 v[120:123], v[140:143], v[186:189], v[120:123]
	v_mfma_f32_16x16x32_bf16 v[108:111], v[132:135], v[194:197], v[108:111]
	v_mfma_f32_16x16x32_bf16 v[104:107], v[140:143], v[194:197], v[104:107]
	v_mfma_f32_16x16x32_bf16 v[92:95], v[132:135], v[202:205], v[92:95]
	v_mfma_f32_16x16x32_bf16 v[88:91], v[140:143], v[202:205], v[88:91]
	v_mfma_f32_16x16x32_bf16 v[76:79], v[132:135], v[210:213], v[76:79]
	v_mfma_f32_16x16x32_bf16 v[72:75], v[140:143], v[210:213], v[72:75]
	v_mfma_f32_16x16x32_bf16 v[116:119], v[144:147], v[160:163], v[116:119]
	v_mfma_f32_16x16x32_bf16 v[112:115], v[152:155], v[160:163], v[112:115]
	v_mfma_f32_16x16x32_bf16 v[100:103], v[144:147], v[190:193], v[100:103]
	v_mfma_f32_16x16x32_bf16 v[96:99], v[152:155], v[190:193], v[96:99]
	v_mfma_f32_16x16x32_bf16 v[84:87], v[144:147], v[198:201], v[84:87]
	v_mfma_f32_16x16x32_bf16 v[80:83], v[152:155], v[198:201], v[80:83]
	v_mfma_f32_16x16x32_bf16 v[68:71], v[144:147], v[206:209], v[68:71]
	v_mfma_f32_16x16x32_bf16 v[64:67], v[152:155], v[206:209], v[64:67]
	v_mfma_f32_16x16x32_bf16 v[116:119], v[148:151], v[186:189], v[116:119]
	v_mfma_f32_16x16x32_bf16 v[112:115], v[156:159], v[186:189], v[112:115]
	v_mfma_f32_16x16x32_bf16 v[100:103], v[148:151], v[194:197], v[100:103]
	v_mfma_f32_16x16x32_bf16 v[96:99], v[156:159], v[194:197], v[96:99]
	v_mfma_f32_16x16x32_bf16 v[84:87], v[148:151], v[202:205], v[84:87]
	v_mfma_f32_16x16x32_bf16 v[80:83], v[156:159], v[202:205], v[80:83]
	v_mfma_f32_16x16x32_bf16 v[68:71], v[148:151], v[210:213], v[68:71]
	v_mfma_f32_16x16x32_bf16 v[64:67], v[156:159], v[210:213], v[64:67]
	s_barrier
	s_add_i32 s8, s89, s63
	s_mov_b32 m0, s8
	ds_read_b128 v[160:163], v238 offset:49152
	ds_read_b128 v[186:189], v238 offset:50176
	ds_read_b128 v[190:193], v238 offset:51200
	ds_read_b128 v[194:197], v238 offset:52224
	ds_read_b128 v[198:201], v238 offset:53248
	ds_read_b128 v[202:205], v238 offset:54272
	ds_read_b128 v[206:209], v238 offset:55296
	ds_read_b128 v[210:213], v238 offset:56320
	global_load_lds_dwordx4 v168, s[98:99]
	s_add_i32 m0, s8, 0x2000
	s_add_u32 s8, s58, 0x100080
	s_addc_u32 s9, s59, 0
	s_add_i32 s58, s90, s63
	global_load_lds_dwordx4 v172, s[98:99]
	s_mov_b32 m0, s58
	s_nop 0
	global_load_lds_dwordx4 v168, s[8:9]
	s_add_i32 m0, s58, 0x2000
	s_nop 0
	global_load_lds_dwordx4 v172, s[8:9]
	s_mov_b32 m0, s70
	s_nop 0
	global_load_lds_dwordx4 v166, s[100:101]
	s_mov_b32 m0, s71
	s_nop 0
	global_load_lds_dwordx4 v170, s[100:101]
	s_waitcnt vmcnt(8)
	s_waitcnt lgkmcnt(0)
	s_barrier
	v_mfma_f32_16x16x32_bf16 v[60:63], v[128:131], v[160:163], v[60:63]
	v_mfma_f32_16x16x32_bf16 v[56:59], v[136:139], v[160:163], v[56:59]
	v_mfma_f32_16x16x32_bf16 v[44:47], v[128:131], v[190:193], v[44:47]
	v_mfma_f32_16x16x32_bf16 v[40:43], v[136:139], v[190:193], v[40:43]
	v_mfma_f32_16x16x32_bf16 v[28:31], v[128:131], v[198:201], v[28:31]
	v_mfma_f32_16x16x32_bf16 v[24:27], v[136:139], v[198:201], v[24:27]
	v_mfma_f32_16x16x32_bf16 v[12:15], v[128:131], v[206:209], v[12:15]
	v_mfma_f32_16x16x32_bf16 v[8:11], v[136:139], v[206:209], v[8:11]
	v_mfma_f32_16x16x32_bf16 v[60:63], v[132:135], v[186:189], v[60:63]
	v_mfma_f32_16x16x32_bf16 v[56:59], v[140:143], v[186:189], v[56:59]
	v_mfma_f32_16x16x32_bf16 v[44:47], v[132:135], v[194:197], v[44:47]
	v_mfma_f32_16x16x32_bf16 v[40:43], v[140:143], v[194:197], v[40:43]
	v_mfma_f32_16x16x32_bf16 v[28:31], v[132:135], v[202:205], v[28:31]
	v_mfma_f32_16x16x32_bf16 v[24:27], v[140:143], v[202:205], v[24:27]
	v_mfma_f32_16x16x32_bf16 v[12:15], v[132:135], v[210:213], v[12:15]
	v_mfma_f32_16x16x32_bf16 v[8:11], v[140:143], v[210:213], v[8:11]
	v_mfma_f32_16x16x32_bf16 v[52:55], v[144:147], v[160:163], v[52:55]
	v_mfma_f32_16x16x32_bf16 v[48:51], v[152:155], v[160:163], v[48:51]
	v_mfma_f32_16x16x32_bf16 v[36:39], v[144:147], v[190:193], v[36:39]
	v_mfma_f32_16x16x32_bf16 v[32:35], v[152:155], v[190:193], v[32:35]
	v_mfma_f32_16x16x32_bf16 v[20:23], v[144:147], v[198:201], v[20:23]
	v_mfma_f32_16x16x32_bf16 v[16:19], v[152:155], v[198:201], v[16:19]
	v_mfma_f32_16x16x32_bf16 v[4:7], v[144:147], v[206:209], v[4:7]
	v_mfma_f32_16x16x32_bf16 v[0:3], v[152:155], v[206:209], v[0:3]
	v_mfma_f32_16x16x32_bf16 v[52:55], v[148:151], v[186:189], v[52:55]
	v_mfma_f32_16x16x32_bf16 v[48:51], v[156:159], v[186:189], v[48:51]
	v_mfma_f32_16x16x32_bf16 v[36:39], v[148:151], v[194:197], v[36:39]
	v_mfma_f32_16x16x32_bf16 v[32:35], v[156:159], v[194:197], v[32:35]
	v_mfma_f32_16x16x32_bf16 v[20:23], v[148:151], v[202:205], v[20:23]
	v_mfma_f32_16x16x32_bf16 v[16:19], v[156:159], v[202:205], v[16:19]
	v_mfma_f32_16x16x32_bf16 v[4:7], v[148:151], v[210:213], v[4:7]
	v_mfma_f32_16x16x32_bf16 v[0:3], v[156:159], v[210:213], v[0:3]
	s_barrier
	s_add_i32 s88, s88, 2
	s_add_u32 s86, s86, 0x100
	s_addc_u32 s87, s87, 0
	s_cmp_gt_u32 s88, 61
	s_mov_b64 s[8:9], s[10:11]
	s_cbranch_scc0 .LBB0_2882
	s_and_b64 vcc, exec, s[18:19]
	s_cbranch_vccz .LBB0_2885
	s_barrier

; #define PG8_STAGE(bufoff, gbase, voff) do { _Pragma("unroll") for (int _i = 0; _i < 2; ++_i) \
;         __builtin_amdgcn_global_load_lds((const unsigned*)((const char*)(gbase) + (voff)[_i]), (PG8_LAS unsigned*)(lds + (bufoff) + ldsw + _i * 8192), 16, 0, 0); } while (0)
; #define PG8_LDA(dst, b, h) do { _Pragma("unroll") for (int m = 0; m < 4; ++m) _Pragma("unroll") for (int k = 0; k < 2; ++k) dst[m][k] = *(const PG8_LAS bf16x8*)(lds + PG8_SA(b, h) + aoff + m * 2048 + k * 1024); } while (0)
; #define PG8_LDB(dst, b, h) do { _Pragma("unroll") for (int n = 0; n < 2; ++n) _Pragma("unroll") for (int k = 0; k < 2; ++k) dst[n][k] = *(const PG8_LAS bf16x8*)(lds + PG8_SB(b, h) + boff + n * 2048 + k * 1024); } while (0)
; #define PG8_MMA(ai, bj, At, Bt) do { __builtin_amdgcn_s_setprio(1); _Pragma("unroll") for (int m = 0; m < 4; ++m) _Pragma("unroll") for (int n = 0; n < 2; ++n) _Pragma("unroll") for (int k = 0; k < 2; ++k) \
;         acc[ai][bj][m][n] = __builtin_amdgcn_mfma_f32_16x16x32_bf16(Bt[n][k], At[m][k], acc[ai][bj][m][n], 0, 0, 0); __builtin_amdgcn_s_setprio(0); } while (0)
; #define PG8_WAIT_V(n) asm volatile("s_waitcnt vmcnt(" #n ")" ::: "memory")
; #define PG8_WAIT_L(n) asm volatile("s_waitcnt lgkmcnt(" #n ")" ::: "memory")
; #define PG8_BAR __builtin_amdgcn_s_barrier()
; #define PG8_SCHED __builtin_amdgcn_sched_barrier(0)
; template <class Epi, class Sched, bool ALIGN_EPI = false, bool SP2 = false>
; __device__ __forceinline__ void gemm_phase(PG8_LAS unsigned char* lds, const Gemm g, const Sched& S, const Epi& E) {
;     ...
;             PG8_LDB(B0, 0, 0); PG8_LDB(B1, 0, 1); PG8_SCHED; PG8_LDA(At, 0, 0); PG8_STAGE(PG8_SA(1, 1), a1 + hstepA, voffA);
;             PG8_WAIT_V(8); PG8_WAIT_L(0); PG8_BAR; PG8_MMA(0, 0, At, B0); PG8_MMA(0, 1, At, B1); PG8_BAR; PG8_SCHED;
;             PG8_LDA(At, 0, 1); PG8_STAGE(PG8_SB(0, 0), b2, voffB); PG8_STAGE(PG8_SB(0, 1), b2 + hstep, voffB); PG8_STAGE(PG8_SA(0, 0), a2, voffA);
;             PG8_WAIT_V(8); PG8_WAIT_L(0); PG8_BAR; PG8_MMA(1, 0, At, B0); PG8_MMA(1, 1, At, B1); PG8_BAR; PG8_SCHED;
.LBB0_3087:
	ds_read_b128 v[144:147], v153
	ds_read_b128 v[158:161], v153 offset:1024
	ds_read_b128 v[162:165], v153 offset:2048
	ds_read_b128 v[166:169], v153 offset:3072
	ds_read_b128 v[170:173], v154
	ds_read_b128 v[174:177], v154 offset:1024
	ds_read_b128 v[178:181], v154 offset:2048
	ds_read_b128 v[182:185], v154 offset:3072
	s_add_u32 s36, s34, 0x4000
	s_addc_u32 s37, s35, 0
	s_cmpk_eq_i32 s65, 0xa8
	s_cselect_b32 s42, s6, s36
	s_cselect_b32 s43, s7, s37
	s_cselect_b32 s40, s30, s63
	s_cselect_b32 s41, s31, s64
	s_add_u32 s36, s42, 0x8000
	s_addc_u32 s37, s43, 0
	s_add_i32 m0, s44, 0xc000
	ds_read_b128 v[186:189], v155
	ds_read_b128 v[190:193], v155 offset:1024
	ds_read_b128 v[194:197], v155 offset:2048
	ds_read_b128 v[198:201], v155 offset:3072
	ds_read_b128 v[202:205], v155 offset:4096
	ds_read_b128 v[206:209], v155 offset:5120
	ds_read_b128 v[210:213], v155 offset:6144
	ds_read_b128 v[214:217], v155 offset:7168
	global_load_lds_dwordx4 v136, s[34:35]
	s_add_i32 m0, s44, 0xe000
	s_nop 0
	global_load_lds_dwordx4 v138, s[34:35]
	s_waitcnt vmcnt(8)
	s_waitcnt lgkmcnt(0)
	s_barrier
	v_mfma_f32_16x16x32_bf16 v[124:127], v[144:147], v[186:189], v[124:127]
	v_mfma_f32_16x16x32_bf16 v[120:123], v[162:165], v[186:189], v[120:123]
	v_mfma_f32_16x16x32_bf16 v[108:111], v[144:147], v[194:197], v[108:111]
	v_mfma_f32_16x16x32_bf16 v[104:107], v[162:165], v[194:197], v[104:107]
	v_mfma_f32_16x16x32_bf16 v[92:95], v[144:147], v[202:205], v[92:95]
	v_mfma_f32_16x16x32_bf16 v[88:91], v[162:165], v[202:205], v[88:91]
	v_mfma_f32_16x16x32_bf16 v[76:79], v[144:147], v[210:213], v[76:79]
	v_mfma_f32_16x16x32_bf16 v[72:75], v[162:165], v[210:213], v[72:75]
	v_mfma_f32_16x16x32_bf16 v[124:127], v[158:161], v[190:193], v[124:127]
	v_mfma_f32_16x16x32_bf16 v[120:123], v[166:169], v[190:193], v[120:123]
	v_mfma_f32_16x16x32_bf16 v[108:111], v[158:161], v[198:201], v[108:111]
	v_mfma_f32_16x16x32_bf16 v[104:107], v[166:169], v[198:201], v[104:107]
	v_mfma_f32_16x16x32_bf16 v[92:95], v[158:161], v[206:209], v[92:95]
	v_mfma_f32_16x16x32_bf16 v[88:91], v[166:169], v[206:209], v[88:91]
	v_mfma_f32_16x16x32_bf16 v[76:79], v[158:161], v[214:217], v[76:79]
	v_mfma_f32_16x16x32_bf16 v[72:75], v[166:169], v[214:217], v[72:75]
	v_mfma_f32_16x16x32_bf16 v[116:119], v[170:173], v[186:189], v[116:119]
	v_mfma_f32_16x16x32_bf16 v[112:115], v[178:181], v[186:189], v[112:115]
	v_mfma_f32_16x16x32_bf16 v[100:103], v[170:173], v[194:197], v[100:103]
	v_mfma_f32_16x16x32_bf16 v[96:99], v[178:181], v[194:197], v[96:99]
	v_mfma_f32_16x16x32_bf16 v[84:87], v[170:173], v[202:205], v[84:87]
	v_mfma_f32_16x16x32_bf16 v[80:83], v[178:181], v[202:205], v[80:83]
	v_mfma_f32_16x16x32_bf16 v[68:71], v[170:173], v[210:213], v[68:71]
	v_mfma_f32_16x16x32_bf16 v[64:67], v[178:181], v[210:213], v[64:67]
	v_mfma_f32_16x16x32_bf16 v[116:119], v[174:177], v[190:193], v[116:119]
	v_mfma_f32_16x16x32_bf16 v[112:115], v[182:185], v[190:193], v[112:115]
	v_mfma_f32_16x16x32_bf16 v[100:103], v[174:177], v[198:201], v[100:103]
	v_mfma_f32_16x16x32_bf16 v[96:99], v[182:185], v[198:201], v[96:99]
	v_mfma_f32_16x16x32_bf16 v[84:87], v[174:177], v[206:209], v[84:87]
	v_mfma_f32_16x16x32_bf16 v[80:83], v[182:185], v[206:209], v[80:83]
	v_mfma_f32_16x16x32_bf16 v[68:71], v[174:177], v[214:217], v[68:71]
	v_mfma_f32_16x16x32_bf16 v[64:67], v[182:185], v[214:217], v[64:67]
	s_barrier
	s_add_u32 s98, s40, s16
	s_addc_u32 s99, s41, s17
	s_add_i32 s66, s53, s33
	s_mov_b32 m0, s66
	ds_read_b128 v[186:189], v155 offset:16384
	ds_read_b128 v[190:193], v155 offset:17408
	ds_read_b128 v[194:197], v155 offset:18432
	ds_read_b128 v[198:201], v155 offset:19456
	ds_read_b128 v[202:205], v155 offset:20480
	ds_read_b128 v[206:209], v155 offset:21504
	ds_read_b128 v[210:213], v155 offset:22528
	ds_read_b128 v[214:217], v155 offset:23552
	global_load_lds_dwordx4 v130, s[40:41]
	s_add_i32 m0, s66, 0x2000
	s_add_u32 s66, s40, 0x2b0000
	s_addc_u32 s67, s41, 0
	s_add_i32 s68, s54, s33
	global_load_lds_dwordx4 v134, s[40:41]
	s_mov_b32 m0, s68
	s_nop 0
	global_load_lds_dwordx4 v130, s[66:67]
	s_add_i32 m0, s68, 0x2000
	s_nop 0
	global_load_lds_dwordx4 v134, s[66:67]
	s_mov_b32 m0, s44
	s_nop 0
	global_load_lds_dwordx4 v128, s[42:43]
	s_mov_b32 m0, s45
	s_nop 0
	global_load_lds_dwordx4 v132, s[42:43]
	s_waitcnt vmcnt(8)
	s_waitcnt lgkmcnt(0)
	s_barrier
	v_mfma_f32_16x16x32_bf16 v[60:63], v[144:147], v[186:189], v[60:63]
	v_mfma_f32_16x16x32_bf16 v[56:59], v[162:165], v[186:189], v[56:59]
	v_mfma_f32_16x16x32_bf16 v[44:47], v[144:147], v[194:197], v[44:47]
	v_mfma_f32_16x16x32_bf16 v[40:43], v[162:165], v[194:197], v[40:43]
	v_mfma_f32_16x16x32_bf16 v[28:31], v[144:147], v[202:205], v[28:31]
	v_mfma_f32_16x16x32_bf16 v[24:27], v[162:165], v[202:205], v[24:27]
	v_mfma_f32_16x16x32_bf16 v[12:15], v[144:147], v[210:213], v[12:15]
	v_mfma_f32_16x16x32_bf16 v[8:11], v[162:165], v[210:213], v[8:11]
	v_mfma_f32_16x16x32_bf16 v[60:63], v[158:161], v[190:193], v[60:63]
	v_mfma_f32_16x16x32_bf16 v[56:59], v[166:169], v[190:193], v[56:59]
	v_mfma_f32_16x16x32_bf16 v[44:47], v[158:161], v[198:201], v[44:47]
	v_mfma_f32_16x16x32_bf16 v[40:43], v[166:169], v[198:201], v[40:43]
	v_mfma_f32_16x16x32_bf16 v[28:31], v[158:161], v[206:209], v[28:31]
	v_mfma_f32_16x16x32_bf16 v[24:27], v[166:169], v[206:209], v[24:27]
	v_mfma_f32_16x16x32_bf16 v[12:15], v[158:161], v[214:217], v[12:15]
	v_mfma_f32_16x16x32_bf16 v[8:11], v[166:169], v[214:217], v[8:11]
	v_mfma_f32_16x16x32_bf16 v[52:55], v[170:173], v[186:189], v[52:55]
	v_mfma_f32_16x16x32_bf16 v[48:51], v[178:181], v[186:189], v[48:51]
	v_mfma_f32_16x16x32_bf16 v[36:39], v[170:173], v[194:197], v[36:39]
	v_mfma_f32_16x16x32_bf16 v[32:35], v[178:181], v[194:197], v[32:35]
	v_mfma_f32_16x16x32_bf16 v[20:23], v[170:173], v[202:205], v[20:23]
	v_mfma_f32_16x16x32_bf16 v[16:19], v[178:181], v[202:205], v[16:19]
	v_mfma_f32_16x16x32_bf16 v[4:7], v[170:173], v[210:213], v[4:7]
	v_mfma_f32_16x16x32_bf16 v[0:3], v[178:181], v[210:213], v[0:3]
	v_mfma_f32_16x16x32_bf16 v[52:55], v[174:177], v[190:193], v[52:55]
	v_mfma_f32_16x16x32_bf16 v[48:51], v[182:185], v[190:193], v[48:51]
	v_mfma_f32_16x16x32_bf16 v[36:39], v[174:177], v[198:201], v[36:39]
	v_mfma_f32_16x16x32_bf16 v[32:35], v[182:185], v[198:201], v[32:35]
	v_mfma_f32_16x16x32_bf16 v[20:23], v[174:177], v[206:209], v[20:23]
	v_mfma_f32_16x16x32_bf16 v[16:19], v[182:185], v[206:209], v[16:19]
	v_mfma_f32_16x16x32_bf16 v[4:7], v[174:177], v[214:217], v[4:7]
	v_mfma_f32_16x16x32_bf16 v[0:3], v[182:185], v[214:217], v[0:3]
	s_barrier
; #define PG8_STAGE(bufoff, gbase, voff) do { _Pragma("unroll") for (int _i = 0; _i < 2; ++_i) \
;         __builtin_amdgcn_global_load_lds((const unsigned*)((const char*)(gbase) + (voff)[_i]), (PG8_LAS unsigned*)(lds + (bufoff) + ldsw + _i * 8192), 16, 0, 0); } while (0)
; #define PG8_LDA(dst, b, h) do { _Pragma("unroll") for (int m = 0; m < 4; ++m) _Pragma("unroll") for (int k = 0; k < 2; ++k) dst[m][k] = *(const PG8_LAS bf16x8*)(lds + PG8_SA(b, h) + aoff + m * 2048 + k * 1024); } while (0)
; #define PG8_LDB(dst, b, h) do { _Pragma("unroll") for (int n = 0; n < 2; ++n) _Pragma("unroll") for (int k = 0; k < 2; ++k) dst[n][k] = *(const PG8_LAS bf16x8*)(lds + PG8_SB(b, h) + boff + n * 2048 + k * 1024); } while (0)
; #define PG8_MMA(ai, bj, At, Bt) do { __builtin_amdgcn_s_setprio(1); _Pragma("unroll") for (int m = 0; m < 4; ++m) _Pragma("unroll") for (int n = 0; n < 2; ++n) _Pragma("unroll") for (int k = 0; k < 2; ++k) \
;         acc[ai][bj][m][n] = __builtin_amdgcn_mfma_f32_16x16x32_bf16(Bt[n][k], At[m][k], acc[ai][bj][m][n], 0, 0, 0); __builtin_amdgcn_s_setprio(0); } while (0)
; #define PG8_WAIT_V(n) asm volatile("s_waitcnt vmcnt(" #n ")" ::: "memory")
; #define PG8_WAIT_L(n) asm volatile("s_waitcnt lgkmcnt(" #n ")" ::: "memory")
; #define PG8_BAR __builtin_amdgcn_s_barrier()
; #define PG8_SCHED __builtin_amdgcn_sched_barrier(0)
; template <class Epi, class Sched, bool ALIGN_EPI = false, bool SP2 = false>
; __device__ __forceinline__ void gemm_phase(PG8_LAS unsigned char* lds, const Gemm g, const Sched& S, const Epi& E) {
;     ...
;             PG8_LDB(B0, 1, 0); PG8_LDB(B1, 1, 1); PG8_SCHED; PG8_LDA(At, 1, 0); PG8_STAGE(PG8_SA(0, 1), a2 + hstepA, voffA);
;             PG8_WAIT_V(8); PG8_WAIT_L(0); PG8_BAR; PG8_MMA(0, 0, At, B0); PG8_MMA(0, 1, At, B1); PG8_BAR; PG8_SCHED;
;             PG8_LDA(At, 1, 1); PG8_STAGE(PG8_SB(1, 0), b3, voffB); PG8_STAGE(PG8_SB(1, 1), b3 + hstep, voffB); PG8_STAGE(PG8_SA(1, 0), a3, voffA);
;             PG8_WAIT_V(8); PG8_WAIT_L(0); PG8_BAR; PG8_MMA(1, 0, At, B0); PG8_MMA(1, 1, At, B1); PG8_BAR; PG8_SCHED;
	s_add_i32 s66, 0, 0x18000
	v_add_u32_e32 v157, s66, v151
	s_add_i32 s67, 0, 0x1c000
	ds_read_b128 v[144:147], v157
	ds_read_b128 v[158:161], v157 offset:1024
	ds_read_b128 v[162:165], v157 offset:2048
	ds_read_b128 v[166:169], v157 offset:3072
	v_add_u32_e32 v157, s67, v151
	ds_read_b128 v[170:173], v157
	ds_read_b128 v[174:177], v157 offset:1024
	ds_read_b128 v[178:181], v157 offset:2048
	ds_read_b128 v[182:185], v157 offset:3072
	s_add_u32 s42, s42, 0x4000
	s_addc_u32 s43, s43, 0
	s_mov_b32 m0, s46
	ds_read_b128 v[186:189], v155 offset:32768
	ds_read_b128 v[190:193], v155 offset:33792
	ds_read_b128 v[194:197], v155 offset:34816
	ds_read_b128 v[198:201], v155 offset:35840
	ds_read_b128 v[202:205], v155 offset:36864
	ds_read_b128 v[206:209], v155 offset:37888
	ds_read_b128 v[210:213], v155 offset:38912
	ds_read_b128 v[214:217], v155 offset:39936
	global_load_lds_dwordx4 v128, s[42:43]
	s_mov_b32 m0, s47
	s_nop 0
	global_load_lds_dwordx4 v132, s[42:43]
	s_waitcnt vmcnt(8)
	s_waitcnt lgkmcnt(0)
	s_barrier
	v_mfma_f32_16x16x32_bf16 v[124:127], v[144:147], v[186:189], v[124:127]
	v_mfma_f32_16x16x32_bf16 v[120:123], v[162:165], v[186:189], v[120:123]
	v_mfma_f32_16x16x32_bf16 v[108:111], v[144:147], v[194:197], v[108:111]
	v_mfma_f32_16x16x32_bf16 v[104:107], v[162:165], v[194:197], v[104:107]
	v_mfma_f32_16x16x32_bf16 v[92:95], v[144:147], v[202:205], v[92:95]
	v_mfma_f32_16x16x32_bf16 v[88:91], v[162:165], v[202:205], v[88:91]
	v_mfma_f32_16x16x32_bf16 v[76:79], v[144:147], v[210:213], v[76:79]
	v_mfma_f32_16x16x32_bf16 v[72:75], v[162:165], v[210:213], v[72:75]
	v_mfma_f32_16x16x32_bf16 v[124:127], v[158:161], v[190:193], v[124:127]
	v_mfma_f32_16x16x32_bf16 v[120:123], v[166:169], v[190:193], v[120:123]
	v_mfma_f32_16x16x32_bf16 v[108:111], v[158:161], v[198:201], v[108:111]
	v_mfma_f32_16x16x32_bf16 v[104:107], v[166:169], v[198:201], v[104:107]
	v_mfma_f32_16x16x32_bf16 v[92:95], v[158:161], v[206:209], v[92:95]
	v_mfma_f32_16x16x32_bf16 v[88:91], v[166:169], v[206:209], v[88:91]
	v_mfma_f32_16x16x32_bf16 v[76:79], v[158:161], v[214:217], v[76:79]
	v_mfma_f32_16x16x32_bf16 v[72:75], v[166:169], v[214:217], v[72:75]
	v_mfma_f32_16x16x32_bf16 v[116:119], v[170:173], v[186:189], v[116:119]
	v_mfma_f32_16x16x32_bf16 v[112:115], v[178:181], v[186:189], v[112:115]
	v_mfma_f32_16x16x32_bf16 v[100:103], v[170:173], v[194:197], v[100:103]
	v_mfma_f32_16x16x32_bf16 v[96:99], v[178:181], v[194:197], v[96:99]
	v_mfma_f32_16x16x32_bf16 v[84:87], v[170:173], v[202:205], v[84:87]
	v_mfma_f32_16x16x32_bf16 v[80:83], v[178:181], v[202:205], v[80:83]
	v_mfma_f32_16x16x32_bf16 v[68:71], v[170:173], v[210:213], v[68:71]
	v_mfma_f32_16x16x32_bf16 v[64:67], v[178:181], v[210:213], v[64:67]
	v_mfma_f32_16x16x32_bf16 v[116:119], v[174:177], v[190:193], v[116:119]
	v_mfma_f32_16x16x32_bf16 v[112:115], v[182:185], v[190:193], v[112:115]
	v_mfma_f32_16x16x32_bf16 v[100:103], v[174:177], v[198:201], v[100:103]
	v_mfma_f32_16x16x32_bf16 v[96:99], v[182:185], v[198:201], v[96:99]
	v_mfma_f32_16x16x32_bf16 v[84:87], v[174:177], v[206:209], v[84:87]
	v_mfma_f32_16x16x32_bf16 v[80:83], v[182:185], v[206:209], v[80:83]
	v_mfma_f32_16x16x32_bf16 v[68:71], v[174:177], v[214:217], v[68:71]
	v_mfma_f32_16x16x32_bf16 v[64:67], v[182:185], v[214:217], v[64:67]
	s_barrier
	s_add_i32 s42, s66, s33
	s_mov_b32 m0, s42
	ds_read_b128 v[186:189], v155 offset:49152
	ds_read_b128 v[190:193], v155 offset:50176
	ds_read_b128 v[194:197], v155 offset:51200
	ds_read_b128 v[198:201], v155 offset:52224
	ds_read_b128 v[202:205], v155 offset:53248
	ds_read_b128 v[206:209], v155 offset:54272
	ds_read_b128 v[210:213], v155 offset:55296
	ds_read_b128 v[214:217], v155 offset:56320
	global_load_lds_dwordx4 v130, s[98:99]
	s_add_i32 m0, s42, 0x2000
	s_add_u32 s40, s40, 0x2b0080
	s_addc_u32 s41, s41, 0
	s_add_i32 s42, s67, s33
	global_load_lds_dwordx4 v134, s[98:99]
	s_mov_b32 m0, s42
	s_nop 0
	global_load_lds_dwordx4 v130, s[40:41]
	s_add_i32 m0, s42, 0x2000
	s_nop 0
	global_load_lds_dwordx4 v134, s[40:41]
	s_mov_b32 m0, s49
	s_nop 0
	global_load_lds_dwordx4 v128, s[36:37]
	s_mov_b32 m0, s50
	s_nop 0
	global_load_lds_dwordx4 v132, s[36:37]
	s_waitcnt vmcnt(8)
	s_waitcnt lgkmcnt(0)
	s_barrier
	v_mfma_f32_16x16x32_bf16 v[60:63], v[144:147], v[186:189], v[60:63]
	v_mfma_f32_16x16x32_bf16 v[56:59], v[162:165], v[186:189], v[56:59]
	v_mfma_f32_16x16x32_bf16 v[44:47], v[144:147], v[194:197], v[44:47]
	v_mfma_f32_16x16x32_bf16 v[40:43], v[162:165], v[194:197], v[40:43]
	v_mfma_f32_16x16x32_bf16 v[28:31], v[144:147], v[202:205], v[28:31]
	v_mfma_f32_16x16x32_bf16 v[24:27], v[162:165], v[202:205], v[24:27]
	v_mfma_f32_16x16x32_bf16 v[12:15], v[144:147], v[210:213], v[12:15]
	v_mfma_f32_16x16x32_bf16 v[8:11], v[162:165], v[210:213], v[8:11]
	v_mfma_f32_16x16x32_bf16 v[60:63], v[158:161], v[190:193], v[60:63]
	v_mfma_f32_16x16x32_bf16 v[56:59], v[166:169], v[190:193], v[56:59]
	v_mfma_f32_16x16x32_bf16 v[44:47], v[158:161], v[198:201], v[44:47]
	v_mfma_f32_16x16x32_bf16 v[40:43], v[166:169], v[198:201], v[40:43]
	v_mfma_f32_16x16x32_bf16 v[28:31], v[158:161], v[206:209], v[28:31]
	v_mfma_f32_16x16x32_bf16 v[24:27], v[166:169], v[206:209], v[24:27]
	v_mfma_f32_16x16x32_bf16 v[12:15], v[158:161], v[214:217], v[12:15]
	v_mfma_f32_16x16x32_bf16 v[8:11], v[166:169], v[214:217], v[8:11]
	v_mfma_f32_16x16x32_bf16 v[52:55], v[170:173], v[186:189], v[52:55]
	v_mfma_f32_16x16x32_bf16 v[48:51], v[178:181], v[186:189], v[48:51]
	v_mfma_f32_16x16x32_bf16 v[36:39], v[170:173], v[194:197], v[36:39]
	v_mfma_f32_16x16x32_bf16 v[32:35], v[178:181], v[194:197], v[32:35]
	v_mfma_f32_16x16x32_bf16 v[20:23], v[170:173], v[202:205], v[20:23]
	v_mfma_f32_16x16x32_bf16 v[16:19], v[178:181], v[202:205], v[16:19]
	v_mfma_f32_16x16x32_bf16 v[4:7], v[170:173], v[210:213], v[4:7]
	v_mfma_f32_16x16x32_bf16 v[0:3], v[178:181], v[210:213], v[0:3]
	v_mfma_f32_16x16x32_bf16 v[52:55], v[174:177], v[190:193], v[52:55]
	v_mfma_f32_16x16x32_bf16 v[48:51], v[182:185], v[190:193], v[48:51]
	v_mfma_f32_16x16x32_bf16 v[36:39], v[174:177], v[198:201], v[36:39]
	v_mfma_f32_16x16x32_bf16 v[32:35], v[182:185], v[198:201], v[32:35]
	v_mfma_f32_16x16x32_bf16 v[20:23], v[174:177], v[206:209], v[20:23]
	v_mfma_f32_16x16x32_bf16 v[16:19], v[182:185], v[206:209], v[16:19]
	v_mfma_f32_16x16x32_bf16 v[4:7], v[174:177], v[214:217], v[4:7]
	v_mfma_f32_16x16x32_bf16 v[0:3], v[182:185], v[214:217], v[0:3]
	s_barrier
	s_add_i32 s65, s65, 2
	s_add_u32 s63, s63, 0x100
	s_addc_u32 s64, s64, 0
	s_add_u32 s34, s34, 0x10000
	s_addc_u32 s35, s35, 0
	s_cmpk_gt_u32 s65, 0xa9
	s_cbranch_scc0 .LBB0_3087
	s_and_b64 vcc, exec, s[18:19]
	s_cbranch_vccz .LBB0_3090
	s_barrier

; #define PG8_STAGE(bufoff, gbase, voff) do { _Pragma("unroll") for (int _i = 0; _i < 2; ++_i) \
;         __builtin_amdgcn_global_load_lds((const unsigned*)((const char*)(gbase) + (voff)[_i]), (PG8_LAS unsigned*)(lds + (bufoff) + ldsw + _i * 8192), 16, 0, 0); } while (0)
; #define PG8_LDA(dst, b, h) do { _Pragma("unroll") for (int m = 0; m < 4; ++m) _Pragma("unroll") for (int k = 0; k < 2; ++k) dst[m][k] = *(const PG8_LAS bf16x8*)(lds + PG8_SA(b, h) + aoff + m * 2048 + k * 1024); } while (0)
; #define PG8_LDB(dst, b, h) do { _Pragma("unroll") for (int n = 0; n < 2; ++n) _Pragma("unroll") for (int k = 0; k < 2; ++k) dst[n][k] = *(const PG8_LAS bf16x8*)(lds + PG8_SB(b, h) + boff + n * 2048 + k * 1024); } while (0)
; #define PG8_MMA(ai, bj, At, Bt) do { __builtin_amdgcn_s_setprio(1); _Pragma("unroll") for (int m = 0; m < 4; ++m) _Pragma("unroll") for (int n = 0; n < 2; ++n) _Pragma("unroll") for (int k = 0; k < 2; ++k) \
;         acc[ai][bj][m][n] = __builtin_amdgcn_mfma_f32_16x16x32_bf16(Bt[n][k], At[m][k], acc[ai][bj][m][n], 0, 0, 0); __builtin_amdgcn_s_setprio(0); } while (0)
; #define PG8_WAIT_V(n) asm volatile("s_waitcnt vmcnt(" #n ")" ::: "memory")
; #define PG8_WAIT_L(n) asm volatile("s_waitcnt lgkmcnt(" #n ")" ::: "memory")
; #define PG8_BAR __builtin_amdgcn_s_barrier()
; #define PG8_SCHED __builtin_amdgcn_sched_barrier(0)
; template <class Epi, class Sched, bool ALIGN_EPI = false, bool SP2 = false>
; __device__ __forceinline__ void gemm_phase(PG8_LAS unsigned char* lds, const Gemm g, const Sched& S, const Epi& E) {
;     ...
;             PG8_LDB(B0, 0, 0); PG8_LDB(B1, 0, 1); PG8_SCHED; PG8_LDA(At, 0, 0); PG8_STAGE(PG8_SA(1, 1), a1 + hstepA, voffA);
;             PG8_WAIT_V(8); PG8_WAIT_L(0); PG8_BAR; PG8_MMA(0, 0, At, B0); PG8_MMA(0, 1, At, B1); PG8_BAR; PG8_SCHED;
;             PG8_LDA(At, 0, 1); PG8_STAGE(PG8_SB(0, 0), b2, voffB); PG8_STAGE(PG8_SB(0, 1), b2 + hstep, voffB); PG8_STAGE(PG8_SA(0, 0), a2, voffA);
;             PG8_WAIT_V(8); PG8_WAIT_L(0); PG8_BAR; PG8_MMA(1, 0, At, B0); PG8_MMA(1, 1, At, B1); PG8_BAR; PG8_SCHED;
.LBB0_3203:
	ds_read_b128 v[144:147], v155
	ds_read_b128 v[148:151], v155 offset:1024
	ds_read_b128 v[160:163], v155 offset:2048
	ds_read_b128 v[164:167], v155 offset:3072
	ds_read_b128 v[168:171], v156
	ds_read_b128 v[172:175], v156 offset:1024
	ds_read_b128 v[176:179], v156 offset:2048
	ds_read_b128 v[180:183], v156 offset:3072
	s_add_u32 s58, s56, 0xfff00080
	s_addc_u32 s59, s57, -1
	s_cmp_eq_u32 s74, 60
	s_cselect_b32 s61, s47, s59
	s_cselect_b32 s60, s53, s58
	s_cselect_b32 s59, s45, s73
	s_cselect_b32 s58, s71, s72
	s_add_i32 m0, s29, 0xc000
	ds_read_b128 v[184:187], v157
	ds_read_b128 v[188:191], v157 offset:1024
	ds_read_b128 v[192:195], v157 offset:2048
	ds_read_b128 v[196:199], v157 offset:3072
	ds_read_b128 v[200:203], v157 offset:4096
	ds_read_b128 v[204:207], v157 offset:5120
	ds_read_b128 v[208:211], v157 offset:6144
	ds_read_b128 v[212:215], v157 offset:7168
	global_load_lds_dwordx4 v136, s[56:57]
	s_add_i32 m0, s29, 0xe000
	s_nop 0
	global_load_lds_dwordx4 v138, s[56:57]
	s_waitcnt vmcnt(8)
	s_waitcnt lgkmcnt(0)
	s_barrier
	v_mfma_f32_16x16x32_bf16 v[124:127], v[144:147], v[184:187], v[124:127]
	v_mfma_f32_16x16x32_bf16 v[72:75], v[160:163], v[184:187], v[72:75]
	v_mfma_f32_16x16x32_bf16 v[116:119], v[144:147], v[192:195], v[116:119]
	v_mfma_f32_16x16x32_bf16 v[68:71], v[160:163], v[192:195], v[68:71]
	v_mfma_f32_16x16x32_bf16 v[108:111], v[144:147], v[200:203], v[108:111]
	v_mfma_f32_16x16x32_bf16 v[96:99], v[160:163], v[200:203], v[96:99]
	v_mfma_f32_16x16x32_bf16 v[92:95], v[144:147], v[208:211], v[92:95]
	v_mfma_f32_16x16x32_bf16 v[88:91], v[160:163], v[208:211], v[88:91]
	v_mfma_f32_16x16x32_bf16 v[124:127], v[148:151], v[188:191], v[124:127]
	v_mfma_f32_16x16x32_bf16 v[72:75], v[164:167], v[188:191], v[72:75]
	v_mfma_f32_16x16x32_bf16 v[116:119], v[148:151], v[196:199], v[116:119]
	v_mfma_f32_16x16x32_bf16 v[68:71], v[164:167], v[196:199], v[68:71]
	v_mfma_f32_16x16x32_bf16 v[108:111], v[148:151], v[204:207], v[108:111]
	v_mfma_f32_16x16x32_bf16 v[96:99], v[164:167], v[204:207], v[96:99]
	v_mfma_f32_16x16x32_bf16 v[92:95], v[148:151], v[212:215], v[92:95]
	v_mfma_f32_16x16x32_bf16 v[88:91], v[164:167], v[212:215], v[88:91]
	v_mfma_f32_16x16x32_bf16 v[120:123], v[168:171], v[184:187], v[120:123]
	v_mfma_f32_16x16x32_bf16 v[84:87], v[176:179], v[184:187], v[84:87]
	v_mfma_f32_16x16x32_bf16 v[112:115], v[168:171], v[192:195], v[112:115]
	v_mfma_f32_16x16x32_bf16 v[80:83], v[176:179], v[192:195], v[80:83]
	v_mfma_f32_16x16x32_bf16 v[104:107], v[168:171], v[200:203], v[104:107]
	v_mfma_f32_16x16x32_bf16 v[100:103], v[176:179], v[200:203], v[100:103]
	v_mfma_f32_16x16x32_bf16 v[76:79], v[168:171], v[208:211], v[76:79]
	v_mfma_f32_16x16x32_bf16 v[64:67], v[176:179], v[208:211], v[64:67]
	v_mfma_f32_16x16x32_bf16 v[120:123], v[172:175], v[188:191], v[120:123]
	v_mfma_f32_16x16x32_bf16 v[84:87], v[180:183], v[188:191], v[84:87]
	v_mfma_f32_16x16x32_bf16 v[112:115], v[172:175], v[196:199], v[112:115]
	v_mfma_f32_16x16x32_bf16 v[80:83], v[180:183], v[196:199], v[80:83]
	v_mfma_f32_16x16x32_bf16 v[104:107], v[172:175], v[204:207], v[104:107]
	v_mfma_f32_16x16x32_bf16 v[100:103], v[180:183], v[204:207], v[100:103]
	v_mfma_f32_16x16x32_bf16 v[76:79], v[172:175], v[212:215], v[76:79]
	v_mfma_f32_16x16x32_bf16 v[64:67], v[180:183], v[212:215], v[64:67]
	s_barrier
	s_add_u32 s98, s58, s20
	s_addc_u32 s99, s59, s21
	s_add_u32 s100, s60, s20
	s_addc_u32 s101, s61, s21
	s_add_i32 s75, s68, s3
	s_mov_b32 m0, s75
	ds_read_b128 v[184:187], v157 offset:16384
	ds_read_b128 v[188:191], v157 offset:17408
	ds_read_b128 v[192:195], v157 offset:18432
	ds_read_b128 v[196:199], v157 offset:19456
	ds_read_b128 v[200:203], v157 offset:20480
	ds_read_b128 v[204:207], v157 offset:21504
	ds_read_b128 v[208:211], v157 offset:22528
	ds_read_b128 v[212:215], v157 offset:23552
	global_load_lds_dwordx4 v130, s[58:59]
	s_add_i32 m0, s75, 0x2000
	s_add_u32 s84, s58, 0x100000
	s_addc_u32 s85, s59, 0
	s_add_i32 s75, s69, s3
	global_load_lds_dwordx4 v134, s[58:59]
	s_mov_b32 m0, s75
	s_nop 0
	global_load_lds_dwordx4 v130, s[84:85]
	s_add_i32 m0, s75, 0x2000
	s_nop 0
	global_load_lds_dwordx4 v134, s[84:85]
	s_mov_b32 m0, s29
	s_nop 0
	global_load_lds_dwordx4 v128, s[60:61]
	s_mov_b32 m0, s33
	s_nop 0
	global_load_lds_dwordx4 v132, s[60:61]
	s_waitcnt vmcnt(8)
	s_waitcnt lgkmcnt(0)
	s_barrier
	v_mfma_f32_16x16x32_bf16 v[60:63], v[144:147], v[184:187], v[60:63]
	v_mfma_f32_16x16x32_bf16 v[56:59], v[160:163], v[184:187], v[56:59]
	v_mfma_f32_16x16x32_bf16 v[44:47], v[144:147], v[192:195], v[44:47]
	v_mfma_f32_16x16x32_bf16 v[40:43], v[160:163], v[192:195], v[40:43]
	v_mfma_f32_16x16x32_bf16 v[28:31], v[144:147], v[200:203], v[28:31]
	v_mfma_f32_16x16x32_bf16 v[24:27], v[160:163], v[200:203], v[24:27]
	v_mfma_f32_16x16x32_bf16 v[12:15], v[144:147], v[208:211], v[12:15]
	v_mfma_f32_16x16x32_bf16 v[8:11], v[160:163], v[208:211], v[8:11]
	v_mfma_f32_16x16x32_bf16 v[60:63], v[148:151], v[188:191], v[60:63]
	v_mfma_f32_16x16x32_bf16 v[56:59], v[164:167], v[188:191], v[56:59]
	v_mfma_f32_16x16x32_bf16 v[44:47], v[148:151], v[196:199], v[44:47]
	v_mfma_f32_16x16x32_bf16 v[40:43], v[164:167], v[196:199], v[40:43]
	v_mfma_f32_16x16x32_bf16 v[28:31], v[148:151], v[204:207], v[28:31]
	v_mfma_f32_16x16x32_bf16 v[24:27], v[164:167], v[204:207], v[24:27]
	v_mfma_f32_16x16x32_bf16 v[12:15], v[148:151], v[212:215], v[12:15]
	v_mfma_f32_16x16x32_bf16 v[8:11], v[164:167], v[212:215], v[8:11]
	v_mfma_f32_16x16x32_bf16 v[52:55], v[168:171], v[184:187], v[52:55]
	v_mfma_f32_16x16x32_bf16 v[48:51], v[176:179], v[184:187], v[48:51]
	v_mfma_f32_16x16x32_bf16 v[36:39], v[168:171], v[192:195], v[36:39]
	v_mfma_f32_16x16x32_bf16 v[32:35], v[176:179], v[192:195], v[32:35]
	v_mfma_f32_16x16x32_bf16 v[20:23], v[168:171], v[200:203], v[20:23]
	v_mfma_f32_16x16x32_bf16 v[16:19], v[176:179], v[200:203], v[16:19]
	v_mfma_f32_16x16x32_bf16 v[4:7], v[168:171], v[208:211], v[4:7]
	v_mfma_f32_16x16x32_bf16 v[0:3], v[176:179], v[208:211], v[0:3]
	v_mfma_f32_16x16x32_bf16 v[52:55], v[172:175], v[188:191], v[52:55]
	v_mfma_f32_16x16x32_bf16 v[48:51], v[180:183], v[188:191], v[48:51]
	v_mfma_f32_16x16x32_bf16 v[36:39], v[172:175], v[196:199], v[36:39]
	v_mfma_f32_16x16x32_bf16 v[32:35], v[180:183], v[196:199], v[32:35]
	v_mfma_f32_16x16x32_bf16 v[20:23], v[172:175], v[204:207], v[20:23]
	v_mfma_f32_16x16x32_bf16 v[16:19], v[180:183], v[204:207], v[16:19]
	v_mfma_f32_16x16x32_bf16 v[4:7], v[172:175], v[212:215], v[4:7]
	v_mfma_f32_16x16x32_bf16 v[0:3], v[180:183], v[212:215], v[0:3]
	s_barrier
; #define PG8_STAGE(bufoff, gbase, voff) do { _Pragma("unroll") for (int _i = 0; _i < 2; ++_i) \
;         __builtin_amdgcn_global_load_lds((const unsigned*)((const char*)(gbase) + (voff)[_i]), (PG8_LAS unsigned*)(lds + (bufoff) + ldsw + _i * 8192), 16, 0, 0); } while (0)
; #define PG8_LDA(dst, b, h) do { _Pragma("unroll") for (int m = 0; m < 4; ++m) _Pragma("unroll") for (int k = 0; k < 2; ++k) dst[m][k] = *(const PG8_LAS bf16x8*)(lds + PG8_SA(b, h) + aoff + m * 2048 + k * 1024); } while (0)
; #define PG8_LDB(dst, b, h) do { _Pragma("unroll") for (int n = 0; n < 2; ++n) _Pragma("unroll") for (int k = 0; k < 2; ++k) dst[n][k] = *(const PG8_LAS bf16x8*)(lds + PG8_SB(b, h) + boff + n * 2048 + k * 1024); } while (0)
; #define PG8_MMA(ai, bj, At, Bt) do { __builtin_amdgcn_s_setprio(1); _Pragma("unroll") for (int m = 0; m < 4; ++m) _Pragma("unroll") for (int n = 0; n < 2; ++n) _Pragma("unroll") for (int k = 0; k < 2; ++k) \
;         acc[ai][bj][m][n] = __builtin_amdgcn_mfma_f32_16x16x32_bf16(Bt[n][k], At[m][k], acc[ai][bj][m][n], 0, 0, 0); __builtin_amdgcn_s_setprio(0); } while (0)
; #define PG8_WAIT_V(n) asm volatile("s_waitcnt vmcnt(" #n ")" ::: "memory")
; #define PG8_WAIT_L(n) asm volatile("s_waitcnt lgkmcnt(" #n ")" ::: "memory")
; #define PG8_BAR __builtin_amdgcn_s_barrier()
; #define PG8_SCHED __builtin_amdgcn_sched_barrier(0)
; template <class Epi, class Sched, bool ALIGN_EPI = false, bool SP2 = false>
; __device__ __forceinline__ void gemm_phase(PG8_LAS unsigned char* lds, const Gemm g, const Sched& S, const Epi& E) {
;     ...
;             PG8_LDB(B0, 1, 0); PG8_LDB(B1, 1, 1); PG8_SCHED; PG8_LDA(At, 1, 0); PG8_STAGE(PG8_SA(0, 1), a2 + hstepA, voffA);
;             PG8_WAIT_V(8); PG8_WAIT_L(0); PG8_BAR; PG8_MMA(0, 0, At, B0); PG8_MMA(0, 1, At, B1); PG8_BAR; PG8_SCHED;
;             PG8_LDA(At, 1, 1); PG8_STAGE(PG8_SB(1, 0), b3, voffB); PG8_STAGE(PG8_SB(1, 1), b3 + hstep, voffB); PG8_STAGE(PG8_SA(1, 0), a3, voffA);
;             PG8_WAIT_V(8); PG8_WAIT_L(0); PG8_BAR; PG8_MMA(1, 0, At, B0); PG8_MMA(1, 1, At, B1); PG8_BAR; PG8_SCHED;
	s_add_i32 s75, 0, 0x18000
	s_add_i32 s84, 0, 0x1c000
	v_add_u32_e32 v164, s75, v153
	v_add_u32_e32 v180, s84, v153
	ds_read_b128 v[144:147], v164
	ds_read_b128 v[148:151], v164 offset:1024
	ds_read_b128 v[160:163], v164 offset:2048
	ds_read_b128 v[164:167], v164 offset:3072
	ds_read_b128 v[168:171], v180
	ds_read_b128 v[172:175], v180 offset:1024
	ds_read_b128 v[176:179], v180 offset:2048
	ds_read_b128 v[180:183], v180 offset:3072
	s_add_u32 s60, s60, 0x100000
	s_addc_u32 s61, s61, 0
	s_mov_b32 m0, s55
	ds_read_b128 v[184:187], v157 offset:32768
	ds_read_b128 v[188:191], v157 offset:33792
	ds_read_b128 v[192:195], v157 offset:34816
	ds_read_b128 v[196:199], v157 offset:35840
	ds_read_b128 v[200:203], v157 offset:36864
	ds_read_b128 v[204:207], v157 offset:37888
	ds_read_b128 v[208:211], v157 offset:38912
	ds_read_b128 v[212:215], v157 offset:39936
	global_load_lds_dwordx4 v128, s[60:61]
	s_mov_b32 m0, s62
	s_nop 0
	global_load_lds_dwordx4 v132, s[60:61]
	s_waitcnt vmcnt(8)
	s_waitcnt lgkmcnt(0)
	s_barrier
	v_mfma_f32_16x16x32_bf16 v[124:127], v[144:147], v[184:187], v[124:127]
	v_mfma_f32_16x16x32_bf16 v[72:75], v[160:163], v[184:187], v[72:75]
	v_mfma_f32_16x16x32_bf16 v[116:119], v[144:147], v[192:195], v[116:119]
	v_mfma_f32_16x16x32_bf16 v[68:71], v[160:163], v[192:195], v[68:71]
	v_mfma_f32_16x16x32_bf16 v[108:111], v[144:147], v[200:203], v[108:111]
	v_mfma_f32_16x16x32_bf16 v[96:99], v[160:163], v[200:203], v[96:99]
	v_mfma_f32_16x16x32_bf16 v[92:95], v[144:147], v[208:211], v[92:95]
	v_mfma_f32_16x16x32_bf16 v[88:91], v[160:163], v[208:211], v[88:91]
	v_mfma_f32_16x16x32_bf16 v[124:127], v[148:151], v[188:191], v[124:127]
	v_mfma_f32_16x16x32_bf16 v[72:75], v[164:167], v[188:191], v[72:75]
	v_mfma_f32_16x16x32_bf16 v[116:119], v[148:151], v[196:199], v[116:119]
	v_mfma_f32_16x16x32_bf16 v[68:71], v[164:167], v[196:199], v[68:71]
	v_mfma_f32_16x16x32_bf16 v[108:111], v[148:151], v[204:207], v[108:111]
	v_mfma_f32_16x16x32_bf16 v[96:99], v[164:167], v[204:207], v[96:99]
	v_mfma_f32_16x16x32_bf16 v[92:95], v[148:151], v[212:215], v[92:95]
	v_mfma_f32_16x16x32_bf16 v[88:91], v[164:167], v[212:215], v[88:91]
	v_mfma_f32_16x16x32_bf16 v[120:123], v[168:171], v[184:187], v[120:123]
	v_mfma_f32_16x16x32_bf16 v[84:87], v[176:179], v[184:187], v[84:87]
	v_mfma_f32_16x16x32_bf16 v[112:115], v[168:171], v[192:195], v[112:115]
	v_mfma_f32_16x16x32_bf16 v[80:83], v[176:179], v[192:195], v[80:83]
	v_mfma_f32_16x16x32_bf16 v[104:107], v[168:171], v[200:203], v[104:107]
	v_mfma_f32_16x16x32_bf16 v[100:103], v[176:179], v[200:203], v[100:103]
	v_mfma_f32_16x16x32_bf16 v[76:79], v[168:171], v[208:211], v[76:79]
	v_mfma_f32_16x16x32_bf16 v[64:67], v[176:179], v[208:211], v[64:67]
	v_mfma_f32_16x16x32_bf16 v[120:123], v[172:175], v[188:191], v[120:123]
	v_mfma_f32_16x16x32_bf16 v[84:87], v[180:183], v[188:191], v[84:87]
	v_mfma_f32_16x16x32_bf16 v[112:115], v[172:175], v[196:199], v[112:115]
	v_mfma_f32_16x16x32_bf16 v[80:83], v[180:183], v[196:199], v[80:83]
	v_mfma_f32_16x16x32_bf16 v[104:107], v[172:175], v[204:207], v[104:107]
	v_mfma_f32_16x16x32_bf16 v[100:103], v[180:183], v[204:207], v[100:103]
	v_mfma_f32_16x16x32_bf16 v[76:79], v[172:175], v[212:215], v[76:79]
	v_mfma_f32_16x16x32_bf16 v[64:67], v[180:183], v[212:215], v[64:67]
	s_barrier
	s_add_i32 s60, s75, s3
	s_mov_b32 m0, s60
	ds_read_b128 v[184:187], v157 offset:49152
	ds_read_b128 v[188:191], v157 offset:50176
	ds_read_b128 v[192:195], v157 offset:51200
	ds_read_b128 v[196:199], v157 offset:52224
	ds_read_b128 v[200:203], v157 offset:53248
	ds_read_b128 v[204:207], v157 offset:54272
	ds_read_b128 v[208:211], v157 offset:55296
	ds_read_b128 v[212:215], v157 offset:56320
	global_load_lds_dwordx4 v130, s[98:99]
	s_add_i32 m0, s60, 0x2000
	s_add_u32 s58, s58, 0x100080
	s_addc_u32 s59, s59, 0
	s_add_i32 s60, s84, s3
	global_load_lds_dwordx4 v134, s[98:99]
	s_mov_b32 m0, s60
	s_nop 0
	global_load_lds_dwordx4 v130, s[58:59]
	s_add_i32 m0, s60, 0x2000
	s_nop 0
	global_load_lds_dwordx4 v134, s[58:59]
	s_mov_b32 m0, s64
	s_nop 0
	global_load_lds_dwordx4 v128, s[100:101]
	s_mov_b32 m0, s65
	s_nop 0
	global_load_lds_dwordx4 v132, s[100:101]
	s_waitcnt vmcnt(8)
	s_waitcnt lgkmcnt(0)
	s_barrier
	v_mfma_f32_16x16x32_bf16 v[60:63], v[144:147], v[184:187], v[60:63]
	v_mfma_f32_16x16x32_bf16 v[56:59], v[160:163], v[184:187], v[56:59]
	v_mfma_f32_16x16x32_bf16 v[44:47], v[144:147], v[192:195], v[44:47]
	v_mfma_f32_16x16x32_bf16 v[40:43], v[160:163], v[192:195], v[40:43]
	v_mfma_f32_16x16x32_bf16 v[28:31], v[144:147], v[200:203], v[28:31]
	v_mfma_f32_16x16x32_bf16 v[24:27], v[160:163], v[200:203], v[24:27]
	v_mfma_f32_16x16x32_bf16 v[12:15], v[144:147], v[208:211], v[12:15]
	v_mfma_f32_16x16x32_bf16 v[8:11], v[160:163], v[208:211], v[8:11]
	v_mfma_f32_16x16x32_bf16 v[60:63], v[148:151], v[188:191], v[60:63]
	v_mfma_f32_16x16x32_bf16 v[56:59], v[164:167], v[188:191], v[56:59]
	v_mfma_f32_16x16x32_bf16 v[44:47], v[148:151], v[196:199], v[44:47]
	v_mfma_f32_16x16x32_bf16 v[40:43], v[164:167], v[196:199], v[40:43]
	v_mfma_f32_16x16x32_bf16 v[28:31], v[148:151], v[204:207], v[28:31]
	v_mfma_f32_16x16x32_bf16 v[24:27], v[164:167], v[204:207], v[24:27]
	v_mfma_f32_16x16x32_bf16 v[12:15], v[148:151], v[212:215], v[12:15]
	v_mfma_f32_16x16x32_bf16 v[8:11], v[164:167], v[212:215], v[8:11]
	v_mfma_f32_16x16x32_bf16 v[52:55], v[168:171], v[184:187], v[52:55]
	v_mfma_f32_16x16x32_bf16 v[48:51], v[176:179], v[184:187], v[48:51]
	v_mfma_f32_16x16x32_bf16 v[36:39], v[168:171], v[192:195], v[36:39]
	v_mfma_f32_16x16x32_bf16 v[32:35], v[176:179], v[192:195], v[32:35]
	v_mfma_f32_16x16x32_bf16 v[20:23], v[168:171], v[200:203], v[20:23]
	v_mfma_f32_16x16x32_bf16 v[16:19], v[176:179], v[200:203], v[16:19]
	v_mfma_f32_16x16x32_bf16 v[4:7], v[168:171], v[208:211], v[4:7]
	v_mfma_f32_16x16x32_bf16 v[0:3], v[176:179], v[208:211], v[0:3]
	v_mfma_f32_16x16x32_bf16 v[52:55], v[172:175], v[188:191], v[52:55]
	v_mfma_f32_16x16x32_bf16 v[48:51], v[180:183], v[188:191], v[48:51]
	v_mfma_f32_16x16x32_bf16 v[36:39], v[172:175], v[196:199], v[36:39]
	v_mfma_f32_16x16x32_bf16 v[32:35], v[180:183], v[196:199], v[32:35]
	v_mfma_f32_16x16x32_bf16 v[20:23], v[172:175], v[204:207], v[20:23]
	v_mfma_f32_16x16x32_bf16 v[16:19], v[180:183], v[204:207], v[16:19]
	v_mfma_f32_16x16x32_bf16 v[4:7], v[172:175], v[212:215], v[4:7]
	v_mfma_f32_16x16x32_bf16 v[0:3], v[180:183], v[212:215], v[0:3]
	s_barrier
	s_add_i32 s74, s74, 2
	s_add_u32 s56, s56, 0x100
	s_addc_u32 s57, s57, 0
	s_add_u32 s72, s72, 0x100
	s_addc_u32 s73, s73, 0
	s_cmp_gt_u32 s74, 61
	s_cbranch_scc0 .LBB0_3203
	s_and_b64 vcc, exec, s[22:23]
	s_cbranch_vccz .LBB0_3206
	s_barrier
